# SSM u_b operand written by the in-projection epilogue into a dense per-group buffer (1 KiB contiguous u tiles)
# speedup vs baseline: 1.0055x; 1.0004x over previous
.LBB0_250:
	s_cmp_ge_u32 s8, 8
	s_cbranch_scc1 .Lg1_ub_tile
	v_lshl_or_b32 v146, s8, 8, v151
	s_mov_b64 s[74:75], s[18:19]
	s_mov_b32 s76, s67
	s_mov_b64 s[78:79], 0x100
	s_branch .Lg1_ub_done
.Lg1_ub_tile:
	s_sub_u32 s77, s8, 8
	s_lshl_b32 s77, s77, 22
	v_lshrrev_b32_e32 v147, 4, v151
	v_lshlrev_b32_e32 v147, 18, v147
	v_bfe_u32 v146, v151, 3, 1
	v_lshl_or_b32 v146, v146, 3, v147
	v_add_u32_e32 v146, s77, v146
	s_add_u32 s74, s62, 0x16800000
	s_addc_u32 s75, s63, 0
	s_mov_b32 s76, 32
	s_mov_b64 s[78:79], 0x400000
.Lg1_ub_done:
	v_lshl_add_u32 v148, s28, 8, v1
	v_mov_b64_e32 v[160:161], s[74:75]
	v_ashrrev_i32_e32 v147, 31, v146
	v_mad_i64_i32 v[160:161], s[28:29], v148, s76, v[160:161]
	s_and_b32 s8, s8, -4
	v_cvt_pk_bf16_f32 v156, v126, v127
	v_cvt_pk_bf16_f32 v157, v128, v129
	v_cvt_pk_bf16_f32 v158, v122, v123
	v_cvt_pk_bf16_f32 v159, v124, v125
	v_lshl_add_u64 v[160:161], v[146:147], 1, v[160:161]
	s_cmp_eq_u32 s8, 4
	v_ashrrev_i32_e32 v149, 31, v148
	global_store_dwordx4 v[160:161], v[156:159], off
	s_cselect_b64 s[28:29], -1, 0
	s_cmp_lg_u32 s8, 4
	v_cvt_pk_bf16_f32 v156, v118, v119
	v_cvt_pk_bf16_f32 v157, v120, v121
	v_cvt_pk_bf16_f32 v158, v114, v115
	v_cvt_pk_bf16_f32 v159, v116, v117
	v_lshl_add_u64 v[160:161], v[160:161], 0, s[78:79]
	global_store_dwordx4 v[160:161], v[156:159], off
	s_cbranch_scc1 .LBB0_254
	v_mul_f32_e32 v117, v117, v117
	v_fmac_f32_e32 v117, v116, v116
	v_mul_f32_e32 v116, v119, v119
	v_mul_f32_e32 v125, v125, v125
	v_fmac_f32_e32 v116, v118, v118
	v_mul_f32_e32 v118, v121, v121
	v_fmac_f32_e32 v125, v124, v124
	v_mul_f32_e32 v124, v127, v127
	v_fmac_f32_e32 v118, v120, v120
	v_mul_f32_e32 v115, v115, v115
	v_fmac_f32_e32 v124, v126, v126
	v_mul_f32_e32 v126, v129, v129
	v_add_f32_e32 v116, v116, v118
	v_fmac_f32_e32 v115, v114, v114
	v_fmac_f32_e32 v126, v128, v128
	v_mul_f32_e32 v123, v123, v123
	v_add_f32_e32 v114, v116, v115
	v_and_b32_e32 v116, 64, v155
	v_add_f32_e32 v124, v124, v126
	v_fmac_f32_e32 v123, v122, v122
	v_xor_b32_e32 v115, 16, v155
	v_add_u32_e32 v116, 64, v116
	v_add_f32_e32 v122, v124, v123
	v_cmp_lt_i32_e32 vcc, v115, v116
	v_add_f32_e32 v122, v125, v122
	v_add_f32_e32 v114, v117, v114
	v_cndmask_b32_e32 v115, v155, v115, vcc
	v_add_f32_e32 v114, v122, v114
	v_lshlrev_b32_e32 v115, 2, v115
	ds_bpermute_b32 v115, v115, v114
	s_waitcnt lgkmcnt(0)
	v_add_f32_e32 v114, v114, v115
	v_xor_b32_e32 v115, 32, v155
	v_cmp_lt_i32_e32 vcc, v115, v116
	s_nop 1
	v_cndmask_b32_e32 v115, v155, v115, vcc
	v_lshlrev_b32_e32 v115, 2, v115
	ds_bpermute_b32 v115, v115, v114
	s_and_saveexec_b64 s[8:9], s[4:5]
	s_cbranch_execz .LBB0_253
	v_lshl_add_u64 v[116:117], v[148:149], 2, s[20:21]
	s_waitcnt lgkmcnt(0)
	v_add_f32_e32 v114, v114, v115
	global_atomic_add_f32 v[116:117], v114, off

.LBB0_254:
	v_or_b32_e32 v114, 16, v148
	v_mov_b64_e32 v[120:121], s[74:75]
	v_mad_i64_i32 v[120:121], s[8:9], v114, s76, v[120:121]
	v_cvt_pk_bf16_f32 v116, v110, v111
	v_cvt_pk_bf16_f32 v117, v112, v113
	v_cvt_pk_bf16_f32 v118, v106, v107
	v_cvt_pk_bf16_f32 v119, v108, v109
	v_lshl_add_u64 v[120:121], v[146:147], 1, v[120:121]
	s_waitcnt lgkmcnt(0)
	v_cndmask_b32_e64 v115, 0, 1, s[28:29]
	global_store_dwordx4 v[120:121], v[116:119], off
	v_cmp_ne_u32_e64 s[8:9], 1, v115
	s_andn2_b64 vcc, exec, s[28:29]
	v_cvt_pk_bf16_f32 v116, v102, v103
	v_cvt_pk_bf16_f32 v117, v104, v105
	v_cvt_pk_bf16_f32 v118, v98, v99
	v_cvt_pk_bf16_f32 v119, v100, v101
	v_lshl_add_u64 v[120:121], v[120:121], 0, s[78:79]
	global_store_dwordx4 v[120:121], v[116:119], off
	s_cbranch_vccnz .LBB0_258
	v_mul_f32_e32 v101, v101, v101
	v_fmac_f32_e32 v101, v100, v100
	v_mul_f32_e32 v100, v103, v103
	v_mul_f32_e32 v109, v109, v109
	v_fmac_f32_e32 v100, v102, v102
	v_mul_f32_e32 v102, v105, v105
	v_fmac_f32_e32 v109, v108, v108
	v_mul_f32_e32 v108, v111, v111
	v_fmac_f32_e32 v102, v104, v104
	v_mul_f32_e32 v99, v99, v99
	v_fmac_f32_e32 v108, v110, v110
	v_mul_f32_e32 v110, v113, v113
	v_add_f32_e32 v100, v100, v102
	v_fmac_f32_e32 v99, v98, v98
	v_fmac_f32_e32 v110, v112, v112
	v_mul_f32_e32 v107, v107, v107
	v_add_f32_e32 v98, v100, v99
	v_and_b32_e32 v100, 64, v155
	v_add_f32_e32 v108, v108, v110
	v_fmac_f32_e32 v107, v106, v106
	v_xor_b32_e32 v99, 16, v155
	v_add_u32_e32 v100, 64, v100
	v_add_f32_e32 v106, v108, v107
	v_cmp_lt_i32_e32 vcc, v99, v100
	v_add_f32_e32 v106, v109, v106
	v_add_f32_e32 v98, v101, v98
	v_cndmask_b32_e32 v99, v155, v99, vcc
	v_add_f32_e32 v98, v106, v98
	v_lshlrev_b32_e32 v99, 2, v99
	ds_bpermute_b32 v99, v99, v98
	s_waitcnt lgkmcnt(0)
	v_add_f32_e32 v98, v98, v99
	v_xor_b32_e32 v99, 32, v155
	v_cmp_lt_i32_e32 vcc, v99, v100
	s_nop 1
	v_cndmask_b32_e32 v99, v155, v99, vcc
	v_lshlrev_b32_e32 v99, 2, v99
	ds_bpermute_b32 v99, v99, v98
	s_and_saveexec_b64 s[28:29], s[4:5]
	s_cbranch_execz .LBB0_257
	v_ashrrev_i32_e32 v115, 31, v114
	v_lshl_add_u64 v[100:101], v[114:115], 2, s[20:21]
	s_waitcnt lgkmcnt(0)
	v_add_f32_e32 v98, v98, v99
	global_atomic_add_f32 v[100:101], v98, off

.LBB0_258:
	v_or_b32_e32 v98, 32, v148
	v_mov_b64_e32 v[104:105], s[74:75]
	v_mad_i64_i32 v[104:105], s[28:29], v98, s76, v[104:105]
	v_cvt_pk_bf16_f32 v100, v94, v95
	v_cvt_pk_bf16_f32 v101, v96, v97
	v_cvt_pk_bf16_f32 v102, v90, v91
	v_cvt_pk_bf16_f32 v103, v92, v93
	v_lshl_add_u64 v[104:105], v[146:147], 1, v[104:105]
	global_store_dwordx4 v[104:105], v[100:103], off
	s_and_b64 vcc, exec, s[8:9]
	s_nop 0
	v_cvt_pk_bf16_f32 v100, v86, v87
	v_cvt_pk_bf16_f32 v101, v88, v89
	v_cvt_pk_bf16_f32 v102, v82, v83
	v_cvt_pk_bf16_f32 v103, v84, v85
	v_lshl_add_u64 v[104:105], v[104:105], 0, s[78:79]
	global_store_dwordx4 v[104:105], v[100:103], off
	s_cbranch_vccnz .LBB0_262
	v_mul_f32_e32 v85, v85, v85
	v_fmac_f32_e32 v85, v84, v84
	v_mul_f32_e32 v84, v87, v87
	v_mul_f32_e32 v93, v93, v93
	v_fmac_f32_e32 v84, v86, v86
	v_mul_f32_e32 v86, v89, v89
	v_fmac_f32_e32 v93, v92, v92
	v_mul_f32_e32 v92, v95, v95
	v_fmac_f32_e32 v86, v88, v88
	v_mul_f32_e32 v83, v83, v83
	v_fmac_f32_e32 v92, v94, v94
	v_mul_f32_e32 v94, v97, v97
	v_add_f32_e32 v84, v84, v86
	v_fmac_f32_e32 v83, v82, v82
	v_fmac_f32_e32 v94, v96, v96
	v_mul_f32_e32 v91, v91, v91
	v_add_f32_e32 v82, v84, v83
	v_and_b32_e32 v84, 64, v155
	v_add_f32_e32 v92, v92, v94
	v_fmac_f32_e32 v91, v90, v90
	v_xor_b32_e32 v83, 16, v155
	v_add_u32_e32 v84, 64, v84
	v_add_f32_e32 v90, v92, v91
	v_cmp_lt_i32_e32 vcc, v83, v84
	v_add_f32_e32 v90, v93, v90
	v_add_f32_e32 v82, v85, v82
	v_cndmask_b32_e32 v83, v155, v83, vcc
	v_add_f32_e32 v82, v90, v82
	v_lshlrev_b32_e32 v83, 2, v83
	ds_bpermute_b32 v83, v83, v82
	s_waitcnt lgkmcnt(0)
	v_add_f32_e32 v82, v82, v83
	v_xor_b32_e32 v83, 32, v155
	v_cmp_lt_i32_e32 vcc, v83, v84
	s_nop 1
	v_cndmask_b32_e32 v83, v155, v83, vcc
	v_lshlrev_b32_e32 v83, 2, v83
	ds_bpermute_b32 v83, v83, v82
	s_and_saveexec_b64 s[28:29], s[4:5]
	s_cbranch_execz .LBB0_261
	v_ashrrev_i32_e32 v99, 31, v98
	v_lshl_add_u64 v[84:85], v[98:99], 2, s[20:21]
	s_waitcnt lgkmcnt(0)
	v_add_f32_e32 v82, v82, v83
	global_atomic_add_f32 v[84:85], v82, off

.LBB0_262:
	v_or_b32_e32 v82, 48, v148
	v_mov_b64_e32 v[88:89], s[74:75]
	v_mad_i64_i32 v[88:89], s[28:29], v82, s76, v[88:89]
	v_cvt_pk_bf16_f32 v84, v78, v79
	v_cvt_pk_bf16_f32 v85, v80, v81
	v_cvt_pk_bf16_f32 v86, v74, v75
	v_cvt_pk_bf16_f32 v87, v76, v77
	v_lshl_add_u64 v[88:89], v[146:147], 1, v[88:89]
	global_store_dwordx4 v[88:89], v[84:87], off
	s_and_b64 vcc, exec, s[8:9]
	s_nop 0
	v_cvt_pk_bf16_f32 v84, v70, v71
	v_cvt_pk_bf16_f32 v85, v72, v73
	v_cvt_pk_bf16_f32 v86, v66, v67
	v_cvt_pk_bf16_f32 v87, v68, v69
	v_lshl_add_u64 v[88:89], v[88:89], 0, s[78:79]
	global_store_dwordx4 v[88:89], v[84:87], off
	s_cbranch_vccnz .LBB0_266
	v_mul_f32_e32 v69, v69, v69
	v_fmac_f32_e32 v69, v68, v68
	v_mul_f32_e32 v68, v71, v71
	v_mul_f32_e32 v77, v77, v77
	v_fmac_f32_e32 v68, v70, v70
	v_mul_f32_e32 v70, v73, v73
	v_fmac_f32_e32 v77, v76, v76
	v_mul_f32_e32 v76, v79, v79
	v_fmac_f32_e32 v70, v72, v72
	v_mul_f32_e32 v67, v67, v67
	v_fmac_f32_e32 v76, v78, v78
	v_mul_f32_e32 v78, v81, v81
	v_add_f32_e32 v68, v68, v70
	v_fmac_f32_e32 v67, v66, v66
	v_fmac_f32_e32 v78, v80, v80
	v_mul_f32_e32 v75, v75, v75
	v_add_f32_e32 v66, v68, v67
	v_and_b32_e32 v68, 64, v155
	v_add_f32_e32 v76, v76, v78
	v_fmac_f32_e32 v75, v74, v74
	v_xor_b32_e32 v67, 16, v155
	v_add_u32_e32 v68, 64, v68
	v_add_f32_e32 v74, v76, v75
	v_cmp_lt_i32_e32 vcc, v67, v68
	v_add_f32_e32 v74, v77, v74
	v_add_f32_e32 v66, v69, v66
	v_cndmask_b32_e32 v67, v155, v67, vcc
	v_add_f32_e32 v66, v74, v66
	v_lshlrev_b32_e32 v67, 2, v67
	ds_bpermute_b32 v67, v67, v66
	s_waitcnt lgkmcnt(0)
	v_add_f32_e32 v66, v66, v67
	v_xor_b32_e32 v67, 32, v155
	v_cmp_lt_i32_e32 vcc, v67, v68
	s_nop 1
	v_cndmask_b32_e32 v67, v155, v67, vcc
	v_lshlrev_b32_e32 v67, 2, v67
	ds_bpermute_b32 v67, v67, v66
	s_and_saveexec_b64 s[28:29], s[4:5]
	s_cbranch_execz .LBB0_265
	v_ashrrev_i32_e32 v83, 31, v82
	v_lshl_add_u64 v[68:69], v[82:83], 2, s[20:21]
	s_waitcnt lgkmcnt(0)
	v_add_f32_e32 v66, v66, v67
	global_atomic_add_f32 v[68:69], v66, off

.LBB0_266:
	v_add_u32_e32 v66, 0x80, v148
	v_mov_b64_e32 v[72:73], s[74:75]
	v_mad_i64_i32 v[72:73], s[28:29], v66, s76, v[72:73]
	v_cvt_pk_bf16_f32 v68, v62, v63
	v_cvt_pk_bf16_f32 v69, v64, v65
	v_cvt_pk_bf16_f32 v70, v58, v59
	v_cvt_pk_bf16_f32 v71, v60, v61
	v_lshl_add_u64 v[72:73], v[146:147], 1, v[72:73]
	global_store_dwordx4 v[72:73], v[68:71], off
	s_and_b64 vcc, exec, s[8:9]
	s_nop 0
	v_cvt_pk_bf16_f32 v68, v54, v55
	v_cvt_pk_bf16_f32 v69, v56, v57
	v_cvt_pk_bf16_f32 v70, v50, v51
	v_cvt_pk_bf16_f32 v71, v52, v53
	v_lshl_add_u64 v[72:73], v[72:73], 0, s[78:79]
	global_store_dwordx4 v[72:73], v[68:71], off
	s_cbranch_vccnz .LBB0_270
	v_mul_f32_e32 v53, v53, v53
	v_fmac_f32_e32 v53, v52, v52
	v_mul_f32_e32 v52, v55, v55
	v_mul_f32_e32 v61, v61, v61
	v_fmac_f32_e32 v52, v54, v54
	v_mul_f32_e32 v54, v57, v57
	v_fmac_f32_e32 v61, v60, v60
	v_mul_f32_e32 v60, v63, v63
	v_fmac_f32_e32 v54, v56, v56
	v_mul_f32_e32 v51, v51, v51
	v_fmac_f32_e32 v60, v62, v62
	v_mul_f32_e32 v62, v65, v65
	v_add_f32_e32 v52, v52, v54
	v_fmac_f32_e32 v51, v50, v50
	v_fmac_f32_e32 v62, v64, v64
	v_mul_f32_e32 v59, v59, v59
	v_add_f32_e32 v50, v52, v51
	v_and_b32_e32 v52, 64, v155
	v_add_f32_e32 v60, v60, v62
	v_fmac_f32_e32 v59, v58, v58
	v_xor_b32_e32 v51, 16, v155
	v_add_u32_e32 v52, 64, v52
	v_add_f32_e32 v58, v60, v59
	v_cmp_lt_i32_e32 vcc, v51, v52
	v_add_f32_e32 v58, v61, v58
	v_add_f32_e32 v50, v53, v50
	v_cndmask_b32_e32 v51, v155, v51, vcc
	v_add_f32_e32 v50, v58, v50
	v_lshlrev_b32_e32 v51, 2, v51
	ds_bpermute_b32 v51, v51, v50
	s_waitcnt lgkmcnt(0)
	v_add_f32_e32 v50, v50, v51
	v_xor_b32_e32 v51, 32, v155
	v_cmp_lt_i32_e32 vcc, v51, v52
	s_nop 1
	v_cndmask_b32_e32 v51, v155, v51, vcc
	v_lshlrev_b32_e32 v51, 2, v51
	ds_bpermute_b32 v51, v51, v50
	s_and_saveexec_b64 s[28:29], s[4:5]
	s_cbranch_execz .LBB0_269
	v_ashrrev_i32_e32 v67, 31, v66
	v_lshl_add_u64 v[52:53], v[66:67], 2, s[20:21]
	s_waitcnt lgkmcnt(0)
	v_add_f32_e32 v50, v50, v51
	global_atomic_add_f32 v[52:53], v50, off

.LBB0_270:
	v_add_u32_e32 v50, 0x90, v148
	v_mov_b64_e32 v[56:57], s[74:75]
	v_mad_i64_i32 v[56:57], s[28:29], v50, s76, v[56:57]
	v_cvt_pk_bf16_f32 v52, v46, v47
	v_cvt_pk_bf16_f32 v53, v48, v49
	v_cvt_pk_bf16_f32 v54, v42, v43
	v_cvt_pk_bf16_f32 v55, v44, v45
	v_lshl_add_u64 v[56:57], v[146:147], 1, v[56:57]
	global_store_dwordx4 v[56:57], v[52:55], off
	s_and_b64 vcc, exec, s[8:9]
	s_nop 0
	v_cvt_pk_bf16_f32 v52, v38, v39
	v_cvt_pk_bf16_f32 v53, v40, v41
	v_cvt_pk_bf16_f32 v54, v34, v35
	v_cvt_pk_bf16_f32 v55, v36, v37
	v_lshl_add_u64 v[56:57], v[56:57], 0, s[78:79]
	global_store_dwordx4 v[56:57], v[52:55], off
	s_cbranch_vccnz .LBB0_274
	v_mul_f32_e32 v37, v37, v37
	v_fmac_f32_e32 v37, v36, v36
	v_mul_f32_e32 v36, v39, v39
	v_mul_f32_e32 v45, v45, v45
	v_fmac_f32_e32 v36, v38, v38
	v_mul_f32_e32 v38, v41, v41
	v_fmac_f32_e32 v45, v44, v44
	v_mul_f32_e32 v44, v47, v47
	v_fmac_f32_e32 v38, v40, v40
	v_mul_f32_e32 v35, v35, v35
	v_fmac_f32_e32 v44, v46, v46
	v_mul_f32_e32 v46, v49, v49
	v_add_f32_e32 v36, v36, v38
	v_fmac_f32_e32 v35, v34, v34
	v_fmac_f32_e32 v46, v48, v48
	v_mul_f32_e32 v43, v43, v43
	v_add_f32_e32 v34, v36, v35
	v_and_b32_e32 v36, 64, v155
	v_add_f32_e32 v44, v44, v46
	v_fmac_f32_e32 v43, v42, v42
	v_xor_b32_e32 v35, 16, v155
	v_add_u32_e32 v36, 64, v36
	v_add_f32_e32 v42, v44, v43
	v_cmp_lt_i32_e32 vcc, v35, v36
	v_add_f32_e32 v42, v45, v42
	v_add_f32_e32 v34, v37, v34
	v_cndmask_b32_e32 v35, v155, v35, vcc
	v_add_f32_e32 v34, v42, v34
	v_lshlrev_b32_e32 v35, 2, v35
	ds_bpermute_b32 v35, v35, v34
	s_waitcnt lgkmcnt(0)
	v_add_f32_e32 v34, v34, v35
	v_xor_b32_e32 v35, 32, v155
	v_cmp_lt_i32_e32 vcc, v35, v36
	s_nop 1
	v_cndmask_b32_e32 v35, v155, v35, vcc
	v_lshlrev_b32_e32 v35, 2, v35
	ds_bpermute_b32 v35, v35, v34
	s_and_saveexec_b64 s[28:29], s[4:5]
	s_cbranch_execz .LBB0_273
	v_ashrrev_i32_e32 v51, 31, v50
	v_lshl_add_u64 v[36:37], v[50:51], 2, s[20:21]
	s_waitcnt lgkmcnt(0)
	v_add_f32_e32 v34, v34, v35
	global_atomic_add_f32 v[36:37], v34, off

.LBB0_274:
	v_add_u32_e32 v34, 0xa0, v148
	v_mov_b64_e32 v[40:41], s[74:75]
	v_mad_i64_i32 v[40:41], s[28:29], v34, s76, v[40:41]
	v_cvt_pk_bf16_f32 v36, v30, v31
	v_cvt_pk_bf16_f32 v37, v32, v33
	v_cvt_pk_bf16_f32 v38, v26, v27
	v_cvt_pk_bf16_f32 v39, v28, v29
	v_lshl_add_u64 v[40:41], v[146:147], 1, v[40:41]
	global_store_dwordx4 v[40:41], v[36:39], off
	s_and_b64 vcc, exec, s[8:9]
	s_nop 0
	v_cvt_pk_bf16_f32 v36, v22, v23
	v_cvt_pk_bf16_f32 v37, v24, v25
	v_cvt_pk_bf16_f32 v38, v18, v19
	v_cvt_pk_bf16_f32 v39, v20, v21
	v_lshl_add_u64 v[40:41], v[40:41], 0, s[78:79]
	global_store_dwordx4 v[40:41], v[36:39], off
	s_cbranch_vccnz .LBB0_278
	v_mul_f32_e32 v21, v21, v21
	v_fmac_f32_e32 v21, v20, v20
	v_mul_f32_e32 v20, v23, v23
	v_mul_f32_e32 v29, v29, v29
	v_fmac_f32_e32 v20, v22, v22
	v_mul_f32_e32 v22, v25, v25
	v_fmac_f32_e32 v29, v28, v28
	v_mul_f32_e32 v28, v31, v31
	v_fmac_f32_e32 v22, v24, v24
	v_mul_f32_e32 v19, v19, v19
	v_fmac_f32_e32 v28, v30, v30
	v_mul_f32_e32 v30, v33, v33
	v_add_f32_e32 v20, v20, v22
	v_fmac_f32_e32 v19, v18, v18
	v_fmac_f32_e32 v30, v32, v32
	v_mul_f32_e32 v27, v27, v27
	v_add_f32_e32 v18, v20, v19
	v_and_b32_e32 v20, 64, v155
	v_add_f32_e32 v28, v28, v30
	v_fmac_f32_e32 v27, v26, v26
	v_xor_b32_e32 v19, 16, v155
	v_add_u32_e32 v20, 64, v20
	v_add_f32_e32 v26, v28, v27
	v_cmp_lt_i32_e32 vcc, v19, v20
	v_add_f32_e32 v26, v29, v26
	v_add_f32_e32 v18, v21, v18
	v_cndmask_b32_e32 v19, v155, v19, vcc
	v_add_f32_e32 v18, v26, v18
	v_lshlrev_b32_e32 v19, 2, v19
	ds_bpermute_b32 v19, v19, v18
	s_waitcnt lgkmcnt(0)
	v_add_f32_e32 v18, v18, v19
	v_xor_b32_e32 v19, 32, v155
	v_cmp_lt_i32_e32 vcc, v19, v20
	s_nop 1
	v_cndmask_b32_e32 v19, v155, v19, vcc
	v_lshlrev_b32_e32 v19, 2, v19
	ds_bpermute_b32 v19, v19, v18
	s_and_saveexec_b64 s[28:29], s[4:5]
	s_cbranch_execz .LBB0_277
	v_ashrrev_i32_e32 v35, 31, v34
	v_lshl_add_u64 v[20:21], v[34:35], 2, s[20:21]
	s_waitcnt lgkmcnt(0)
	v_add_f32_e32 v18, v18, v19
	global_atomic_add_f32 v[20:21], v18, off

.LBB0_278:
	v_add_u32_e32 v18, 0xb0, v148
	v_mov_b64_e32 v[24:25], s[74:75]
	v_mad_i64_i32 v[24:25], s[28:29], v18, s76, v[24:25]
	v_cvt_pk_bf16_f32 v20, v14, v15
	v_cvt_pk_bf16_f32 v21, v16, v17
	v_cvt_pk_bf16_f32 v22, v10, v11
	v_cvt_pk_bf16_f32 v23, v12, v13
	v_lshl_add_u64 v[24:25], v[146:147], 1, v[24:25]
	global_store_dwordx4 v[24:25], v[20:23], off
	s_and_b64 vcc, exec, s[8:9]
	s_nop 0
	v_cvt_pk_bf16_f32 v20, v6, v7
	v_cvt_pk_bf16_f32 v21, v8, v9
	v_cvt_pk_bf16_f32 v22, v2, v3
	v_cvt_pk_bf16_f32 v23, v4, v5
	v_lshl_add_u64 v[24:25], v[24:25], 0, s[78:79]
	global_store_dwordx4 v[24:25], v[20:23], off
	s_cbranch_vccnz .LBB0_282
	v_mul_f32_e32 v5, v5, v5
	v_fmac_f32_e32 v5, v4, v4
	v_mul_f32_e32 v4, v7, v7
	v_mul_f32_e32 v13, v13, v13
	v_fmac_f32_e32 v4, v6, v6
	v_mul_f32_e32 v6, v9, v9
	v_fmac_f32_e32 v13, v12, v12
	v_mul_f32_e32 v12, v15, v15
	v_fmac_f32_e32 v6, v8, v8
	v_mul_f32_e32 v3, v3, v3
	v_fmac_f32_e32 v12, v14, v14
	v_mul_f32_e32 v14, v17, v17
	v_add_f32_e32 v4, v4, v6
	v_fmac_f32_e32 v3, v2, v2
	v_fmac_f32_e32 v14, v16, v16
	v_mul_f32_e32 v11, v11, v11
	v_add_f32_e32 v2, v4, v3
	v_and_b32_e32 v4, 64, v155
	v_add_f32_e32 v12, v12, v14
	v_fmac_f32_e32 v11, v10, v10
	v_xor_b32_e32 v3, 16, v155
	v_add_u32_e32 v4, 64, v4
	v_add_f32_e32 v10, v12, v11
	v_cmp_lt_i32_e32 vcc, v3, v4
	v_add_f32_e32 v10, v13, v10
	v_add_f32_e32 v2, v5, v2
	v_cndmask_b32_e32 v3, v155, v3, vcc
	v_add_f32_e32 v2, v10, v2
	v_lshlrev_b32_e32 v3, 2, v3
	ds_bpermute_b32 v3, v3, v2
	s_waitcnt lgkmcnt(0)
	v_add_f32_e32 v2, v2, v3
	v_xor_b32_e32 v3, 32, v155
	v_cmp_lt_i32_e32 vcc, v3, v4
	s_nop 1
	v_cndmask_b32_e32 v3, v155, v3, vcc
	v_lshlrev_b32_e32 v3, 2, v3
	ds_bpermute_b32 v3, v3, v2
	s_and_saveexec_b64 s[8:9], s[4:5]
	s_cbranch_execz .LBB0_281
	v_ashrrev_i32_e32 v19, 31, v18
	v_lshl_add_u64 v[4:5], v[18:19], 2, s[20:21]
	s_waitcnt lgkmcnt(0)
	v_add_f32_e32 v2, v2, v3
	global_atomic_add_f32 v[4:5], v2, off

.LBB0_340:
	s_cmp_lt_i32 s96, 4
	s_cselect_b64 s[0:1], -1, 0
	s_and_b64 s[8:9], s[0:1], s[4:5]
	s_andn2_b64 vcc, exec, s[8:9]
	s_cbranch_vccnz .LBB0_393
	v_cmp_gt_u32_e32 vcc, 2, v190
	s_and_saveexec_b64 s[0:1], vcc
	v_lshlrev_b32_e32 v2, 2, v190
	v_add_u32_e32 v2, 0x21000, v2
	v_mov_b32_e32 v3, 0
	ds_write_b32 v2, v3
	s_mov_b64 exec, s[0:1]
	v_and_b32_e32 v172, 31, v191
	v_lshrrev_b32_e32 v173, 5, v191
	v_and_b32_e32 v174, 1, v191
	v_and_b32_e32 v175, 15, v191
	v_lshrrev_b32_e32 v176, 4, v191
	s_mul_i32 s20, s89, 0x3200
	v_lshl_add_u32 v151, v191, 2, s20
	v_mul_u32_u24_e32 v182, 0x110, v175
	v_lshl_add_u32 v182, v176, 4, v182
	v_add_u32_e32 v152, s20, v182
	v_lshlrev_b32_e32 v182, 5, v172
	v_lshl_add_u32 v150, v173, 4, v182
	v_lshlrev_b32_e32 v182, 5, v172
	v_lshl_add_u32 v182, v173, 4, v182
	s_add_u32 s22, s20, 0x2200
	v_add_u32_e32 v162, s22, v182
	v_lshlrev_b32_e32 v182, 5, v175
	v_lshl_add_u32 v182, v176, 3, v182
	v_add_u32_e32 v163, s22, v182
	v_mul_u32_u24_e32 v182, 0x1800, v175
	v_lshl_add_u32 v154, v176, 3, v182
	v_add_u32_e32 v158, 0x18000, v154
	v_lshlrev_b32_e32 v182, 12, v175
	v_lshlrev_b32_e32 v182, 6, v175
	v_lshl_add_u32 v153, v176, 4, v182
	v_add_u32_e32 v157, 0x400, v153
	v_lshlrev_b32_e32 v182, 11, v175
	v_lshl_add_u32 v156, v176, 3, v182
	v_add_u32_e32 v159, 0x8000, v156
	s_and_b32 s21, s89, 3
	s_lshl_b32 s21, s21, 13
	s_add_u32 s21, s21, 0x19000
	v_lshlrev_b32_e32 v182, 5, v175
	v_lshl_add_u32 v182, v176, 3, v182
	v_add_u32_e32 v155, s21, v182
	v_lshrrev_b32_e32 v182, 4, v172
	v_lshlrev_b32_e32 v182, 10, v182
	v_lshl_add_u32 v182, v175, 4, v182
	v_lshl_add_u32 v177, v173, 8, v182
	v_lshrrev_b32_e32 v182, 1, v176
	v_lshlrev_b32_e32 v182, 8, v182
	v_and_b32_e32 v183, 1, v176
	v_lshl_add_u32 v182, v183, 3, v182
	v_lshl_add_u32 v178, v175, 4, v182
	v_lshrrev_b32_e32 v182, 1, v172
	v_lshl_add_u32 v182, v173, 5, v182
	v_lshlrev_b32_e32 v179, 3, v182
	v_lshlrev_b32_e32 v183, 14, v174
	v_lshl_add_u32 v180, v182, 2, v183
	v_lshlrev_b32_e32 v181, 4, v176
	s_waitcnt vmcnt(0) lgkmcnt(0)
	s_barrier
	s_cmp_lt_u32 s89, 4
	s_cbranch_scc0 .Lssm_ctx
	s_lshr_b32 s21, s89, 1
	s_and_b32 s22, s2, 7
	s_lshl_b32 s22, s22, 6
	s_lshr_b32 s26, s2, 3
	s_lshl_b32 s26, s26, 1
	s_add_u32 s22, s22, s26
	s_add_u32 s22, s22, s21
	s_lshr_b32 s23, s22, 6
	s_and_b32 s24, s22, 63
	s_lshl_b32 s25, s23, 10
	s_add_u32 s25, s25, 0x2000
	s_and_b32 s26, s89, 1
	s_cmp_eq_u32 s26, 0
	s_cbranch_scc0 .Lssm_lat_bwd
	s_add_u32 s28, s24, 0
	s_lshl_b32 s29, s28, 13
	s_add_u32 s29, s29, 0x200000
	s_add_u32 s10, s62, s29
	s_addc_u32 s11, s63, 0
	global_load_dwordx4 v[84:87], v177, s[10:11]
	global_load_dwordx4 v[88:91], v177, s[10:11] offset:2048
	s_add_u32 s12, s10, 0x1000
	s_addc_u32 s13, s11, 0
	global_load_dwordx4 v[92:95], v177, s[12:13]
	global_load_dwordx4 v[96:99], v177, s[12:13] offset:2048
	s_lshl_b32 s29, s28, 12
	s_add_u32 s29, s29, 0x300000
	s_add_u32 s16, s62, s29
	s_addc_u32 s17, s63, 0
	global_load_dwordx2 v[2:3], v178, s[16:17]
	global_load_dwordx2 v[4:5], v178, s[16:17] offset:1024
	global_load_dwordx2 v[6:7], v178, s[16:17] offset:512
	global_load_dwordx2 v[8:9], v178, s[16:17] offset:1536
	global_load_dwordx2 v[10:11], v178, s[16:17] offset:2048
	global_load_dwordx2 v[12:13], v178, s[16:17] offset:3072
	global_load_dwordx2 v[14:15], v178, s[16:17] offset:2560
	global_load_dwordx2 v[16:17], v178, s[16:17] offset:3584
	s_lshl_b32 s29, s28, 9
	s_add_u32 s29, s29, 0x100000
	s_add_u32 s18, s62, s29
	s_addc_u32 s19, s63, 0
	global_load_dwordx2 v[116:117], v179, s[18:19]
	global_load_dwordx2 v[118:119], v179, s[18:19] offset:128
	s_lshl_b32 s30, s23, 1
	s_lshl_b32 s30, s30, 15
	s_lshl_b32 s31, s24, 8
	s_add_u32 s30, s30, s31
	v_readlane_b32 s34, v254, 10
	v_readlane_b32 s35, v254, 11
	s_nop 3
	s_add_u32 s34, s34, s30
	s_addc_u32 s35, s35, 0
	global_load_dword v120, v180, s[34:35]
	global_load_dword v121, v180, s[34:35] offset:64
	v_readlane_b32 s34, v254, 28
	v_readlane_b32 s35, v254, 29
	s_nop 3
	s_lshl_b32 s31, s24, 6
	s_add_u32 s34, s34, s31
	s_addc_u32 s35, s35, 0
	global_load_dwordx4 v[164:167], v181, s[34:35]
	s_lshl_b32 s31, s25, 5
	s_lshl_b32 s29, s24, 19
	s_add_u32 s31, s31, s29
	s_add_u32 s31, s31, 0x16800000
	s_add_u32 s4, s62, s31
	s_addc_u32 s5, s63, 0
	s_lshl_b32 s31, s22, 1
	s_lshl_b32 s31, s31, 15
	s_add_u32 s31, s31, 0x4800000
	s_add_u32 s6, s62, s31
	s_addc_u32 s7, s63, 0
	s_add_u32 s34, s4, 0
	s_addc_u32 s35, s5, 0
	global_load_dwordx4 v[80:83], v150, s[34:35]
	s_mov_b64 s[10:11], s[34:35]
	s_add_u32 s10, s10, 1024
	s_addc_u32 s11, s11, 0
	global_load_dwordx4 v[144:147], v150, s[10:11]
	s_mov_b64 s[34:35], s[10:11]
	s_add_u32 s10, s10, 1024
	s_addc_u32 s11, s11, 0
	s_add_u32 s12, s6, 0
	s_addc_u32 s13, s7, 0
	s_mov_b32 s14, 0
	s_mov_b32 s40, 0xffff0000
	s_waitcnt vmcnt(0)
	v_and_b32_e32 v182, 0xffff, v2
	v_lshrrev_b32_e32 v183, 16, v2
	v_and_b32_e32 v184, 0xffff, v3
	v_lshrrev_b32_e32 v185, 16, v3
	v_lshl_or_b32 v100, v4, 16, v182
	v_and_or_b32 v101, v4, s40, v183
	v_lshl_or_b32 v102, v5, 16, v184
	v_and_or_b32 v103, v5, s40, v185
	v_and_b32_e32 v182, 0xffff, v6
	v_lshrrev_b32_e32 v183, 16, v6
	v_and_b32_e32 v184, 0xffff, v7
	v_lshrrev_b32_e32 v185, 16, v7
	v_lshl_or_b32 v104, v8, 16, v182
	v_and_or_b32 v105, v8, s40, v183
	v_lshl_or_b32 v106, v9, 16, v184
	v_and_or_b32 v107, v9, s40, v185
	v_and_b32_e32 v182, 0xffff, v10
	v_lshrrev_b32_e32 v183, 16, v10
	v_and_b32_e32 v184, 0xffff, v11
	v_lshrrev_b32_e32 v185, 16, v11
	v_lshl_or_b32 v108, v12, 16, v182
	v_and_or_b32 v109, v12, s40, v183
	v_lshl_or_b32 v110, v13, 16, v184
	v_and_or_b32 v111, v13, s40, v185
	v_and_b32_e32 v182, 0xffff, v14
	v_lshrrev_b32_e32 v183, 16, v14
	v_and_b32_e32 v184, 0xffff, v15
	v_lshrrev_b32_e32 v185, 16, v15
	v_lshl_or_b32 v112, v16, 16, v182
	v_and_or_b32 v113, v16, s40, v183
	v_lshl_or_b32 v114, v17, 16, v184
	v_and_or_b32 v115, v17, s40, v185
	v_cmp_eq_u32_e32 vcc, 1, v174
	v_xor_b32_e32 v182, 0x80000000, v117
	v_xor_b32_e32 v183, 0x80000000, v119
	s_nop 1
	v_cndmask_b32_e32 v122, v182, v117, vcc
	v_cndmask_b32_e32 v123, v183, v119, vcc
.Lssm_tileA_d0m0:
	s_waitcnt vmcnt(5)
	v_mfma_f32_32x32x16_bf16 v[16:31], v[80:83], v[84:87], 0
	v_mfma_f32_32x32x16_bf16 v[32:47], v[80:83], v[88:91], 0
	v_mfma_f32_32x32x16_bf16 v[48:63], v[80:83], v[92:95], 0
	v_mfma_f32_32x32x16_bf16 v[64:79], v[80:83], v[96:99], 0
	s_nop 11
	global_load_dwordx4 v[80:83], v150, s[10:11]
	s_add_u32 s34, s34, 1024
	s_addc_u32 s35, s35, 0
	s_add_u32 s10, s10, 1024
	s_addc_u32 s11, s11, 0
	v_permlane32_swap_b32_e32 v16, v48
	v_permlane32_swap_b32_e32 v17, v49
	v_permlane32_swap_b32_e32 v18, v50
	v_permlane32_swap_b32_e32 v19, v51
	v_permlane32_swap_b32_e32 v20, v52
	v_permlane32_swap_b32_e32 v21, v53
	v_permlane32_swap_b32_e32 v22, v54
	v_permlane32_swap_b32_e32 v23, v55
	v_permlane32_swap_b32_e32 v24, v56
	v_permlane32_swap_b32_e32 v25, v57
	v_permlane32_swap_b32_e32 v26, v58
	v_permlane32_swap_b32_e32 v27, v59
	v_permlane32_swap_b32_e32 v28, v60
	v_permlane32_swap_b32_e32 v29, v61
	v_permlane32_swap_b32_e32 v30, v62
	v_permlane32_swap_b32_e32 v31, v63
	v_permlane32_swap_b32_e32 v32, v64
	v_permlane32_swap_b32_e32 v33, v65
	v_permlane32_swap_b32_e32 v34, v66
	v_permlane32_swap_b32_e32 v35, v67
	v_permlane32_swap_b32_e32 v36, v68
	v_permlane32_swap_b32_e32 v37, v69
	v_permlane32_swap_b32_e32 v38, v70
	v_permlane32_swap_b32_e32 v39, v71
	v_permlane32_swap_b32_e32 v40, v72
	v_permlane32_swap_b32_e32 v41, v73
	v_permlane32_swap_b32_e32 v42, v74
	v_permlane32_swap_b32_e32 v43, v75
	v_permlane32_swap_b32_e32 v44, v76
	v_permlane32_swap_b32_e32 v45, v77
	v_permlane32_swap_b32_e32 v46, v78
	v_permlane32_swap_b32_e32 v47, v79
	v_fmac_f32_e32 v16, v116, v120
	v_fmac_f32_e32 v32, v118, v121
	v_fmac_f32_dpp v16, v120, v122 quad_perm:[1,0,3,2] row_mask:0xf bank_mask:0xf
	v_fmac_f32_dpp v32, v121, v123 quad_perm:[1,0,3,2] row_mask:0xf bank_mask:0xf
	v_cvt_pk_bf16_f32 v148, v16, v32
	ds_write_b32 v151, v148
	v_fmac_f32_e32 v17, v116, v16
	v_fmac_f32_e32 v33, v118, v32
	v_fmac_f32_dpp v17, v16, v122 quad_perm:[1,0,3,2] row_mask:0xf bank_mask:0xf
	v_fmac_f32_dpp v33, v32, v123 quad_perm:[1,0,3,2] row_mask:0xf bank_mask:0xf
	v_cvt_pk_bf16_f32 v149, v17, v33
	ds_write_b32 v151, v149 offset:272
	v_fmac_f32_e32 v18, v116, v17
	v_fmac_f32_e32 v34, v118, v33
	v_fmac_f32_dpp v18, v17, v122 quad_perm:[1,0,3,2] row_mask:0xf bank_mask:0xf
	v_fmac_f32_dpp v34, v33, v123 quad_perm:[1,0,3,2] row_mask:0xf bank_mask:0xf
	v_cvt_pk_bf16_f32 v148, v18, v34
	ds_write_b32 v151, v148 offset:544
	v_fmac_f32_e32 v19, v116, v18
	v_fmac_f32_e32 v35, v118, v34
	v_fmac_f32_dpp v19, v18, v122 quad_perm:[1,0,3,2] row_mask:0xf bank_mask:0xf
	v_fmac_f32_dpp v35, v34, v123 quad_perm:[1,0,3,2] row_mask:0xf bank_mask:0xf
	v_cvt_pk_bf16_f32 v149, v19, v35
	ds_write_b32 v151, v149 offset:816
	v_fmac_f32_e32 v48, v116, v19
	v_fmac_f32_e32 v64, v118, v35
	v_fmac_f32_dpp v48, v19, v122 quad_perm:[1,0,3,2] row_mask:0xf bank_mask:0xf
	v_fmac_f32_dpp v64, v35, v123 quad_perm:[1,0,3,2] row_mask:0xf bank_mask:0xf
	v_cvt_pk_bf16_f32 v148, v48, v64
	ds_write_b32 v151, v148 offset:1088
	v_fmac_f32_e32 v49, v116, v48
	v_fmac_f32_e32 v65, v118, v64
	v_fmac_f32_dpp v49, v48, v122 quad_perm:[1,0,3,2] row_mask:0xf bank_mask:0xf
	v_fmac_f32_dpp v65, v64, v123 quad_perm:[1,0,3,2] row_mask:0xf bank_mask:0xf
	v_cvt_pk_bf16_f32 v149, v49, v65
	ds_write_b32 v151, v149 offset:1360
	v_fmac_f32_e32 v50, v116, v49
	v_fmac_f32_e32 v66, v118, v65
	v_fmac_f32_dpp v50, v49, v122 quad_perm:[1,0,3,2] row_mask:0xf bank_mask:0xf
	v_fmac_f32_dpp v66, v65, v123 quad_perm:[1,0,3,2] row_mask:0xf bank_mask:0xf
	v_cvt_pk_bf16_f32 v148, v50, v66
	ds_write_b32 v151, v148 offset:1632
	v_fmac_f32_e32 v51, v116, v50
	v_fmac_f32_e32 v67, v118, v66
	v_fmac_f32_dpp v51, v50, v122 quad_perm:[1,0,3,2] row_mask:0xf bank_mask:0xf
	v_fmac_f32_dpp v67, v66, v123 quad_perm:[1,0,3,2] row_mask:0xf bank_mask:0xf
	v_cvt_pk_bf16_f32 v149, v51, v67
	ds_write_b32 v151, v149 offset:1904
	v_fmac_f32_e32 v20, v116, v51
	v_fmac_f32_e32 v36, v118, v67
	v_fmac_f32_dpp v20, v51, v122 quad_perm:[1,0,3,2] row_mask:0xf bank_mask:0xf
	v_fmac_f32_dpp v36, v67, v123 quad_perm:[1,0,3,2] row_mask:0xf bank_mask:0xf
	v_cvt_pk_bf16_f32 v148, v20, v36
	ds_write_b32 v151, v148 offset:2176
	v_fmac_f32_e32 v21, v116, v20
	v_fmac_f32_e32 v37, v118, v36
	v_fmac_f32_dpp v21, v20, v122 quad_perm:[1,0,3,2] row_mask:0xf bank_mask:0xf
	v_fmac_f32_dpp v37, v36, v123 quad_perm:[1,0,3,2] row_mask:0xf bank_mask:0xf
	v_cvt_pk_bf16_f32 v149, v21, v37
	ds_write_b32 v151, v149 offset:2448
	v_fmac_f32_e32 v22, v116, v21
	v_fmac_f32_e32 v38, v118, v37
	v_fmac_f32_dpp v22, v21, v122 quad_perm:[1,0,3,2] row_mask:0xf bank_mask:0xf
	v_fmac_f32_dpp v38, v37, v123 quad_perm:[1,0,3,2] row_mask:0xf bank_mask:0xf
	v_cvt_pk_bf16_f32 v148, v22, v38
	ds_write_b32 v151, v148 offset:2720
	v_fmac_f32_e32 v23, v116, v22
	v_fmac_f32_e32 v39, v118, v38
	v_fmac_f32_dpp v23, v22, v122 quad_perm:[1,0,3,2] row_mask:0xf bank_mask:0xf
	v_fmac_f32_dpp v39, v38, v123 quad_perm:[1,0,3,2] row_mask:0xf bank_mask:0xf
	v_cvt_pk_bf16_f32 v149, v23, v39
	ds_write_b32 v151, v149 offset:2992
	v_fmac_f32_e32 v52, v116, v23
	v_fmac_f32_e32 v68, v118, v39
	v_fmac_f32_dpp v52, v23, v122 quad_perm:[1,0,3,2] row_mask:0xf bank_mask:0xf
	v_fmac_f32_dpp v68, v39, v123 quad_perm:[1,0,3,2] row_mask:0xf bank_mask:0xf
	v_cvt_pk_bf16_f32 v148, v52, v68
	ds_write_b32 v151, v148 offset:3264
	v_fmac_f32_e32 v53, v116, v52
	v_fmac_f32_e32 v69, v118, v68
	v_fmac_f32_dpp v53, v52, v122 quad_perm:[1,0,3,2] row_mask:0xf bank_mask:0xf
	v_fmac_f32_dpp v69, v68, v123 quad_perm:[1,0,3,2] row_mask:0xf bank_mask:0xf
	v_cvt_pk_bf16_f32 v149, v53, v69
	ds_write_b32 v151, v149 offset:3536
	v_fmac_f32_e32 v54, v116, v53
	v_fmac_f32_e32 v70, v118, v69
	v_fmac_f32_dpp v54, v53, v122 quad_perm:[1,0,3,2] row_mask:0xf bank_mask:0xf
	v_fmac_f32_dpp v70, v69, v123 quad_perm:[1,0,3,2] row_mask:0xf bank_mask:0xf
	v_cvt_pk_bf16_f32 v148, v54, v70
	ds_write_b32 v151, v148 offset:3808
	v_fmac_f32_e32 v55, v116, v54
	v_fmac_f32_e32 v71, v118, v70
	v_fmac_f32_dpp v55, v54, v122 quad_perm:[1,0,3,2] row_mask:0xf bank_mask:0xf
	v_fmac_f32_dpp v71, v70, v123 quad_perm:[1,0,3,2] row_mask:0xf bank_mask:0xf
	v_cvt_pk_bf16_f32 v149, v55, v71
	ds_write_b32 v151, v149 offset:4080
	v_fmac_f32_e32 v24, v116, v55
	v_fmac_f32_e32 v40, v118, v71
	v_fmac_f32_dpp v24, v55, v122 quad_perm:[1,0,3,2] row_mask:0xf bank_mask:0xf
	v_fmac_f32_dpp v40, v71, v123 quad_perm:[1,0,3,2] row_mask:0xf bank_mask:0xf
	v_cvt_pk_bf16_f32 v148, v24, v40
	ds_write_b32 v151, v148 offset:4352
	v_fmac_f32_e32 v25, v116, v24
	v_fmac_f32_e32 v41, v118, v40
	v_fmac_f32_dpp v25, v24, v122 quad_perm:[1,0,3,2] row_mask:0xf bank_mask:0xf
	v_fmac_f32_dpp v41, v40, v123 quad_perm:[1,0,3,2] row_mask:0xf bank_mask:0xf
	v_cvt_pk_bf16_f32 v149, v25, v41
	ds_write_b32 v151, v149 offset:4624
	v_fmac_f32_e32 v26, v116, v25
	v_fmac_f32_e32 v42, v118, v41
	v_fmac_f32_dpp v26, v25, v122 quad_perm:[1,0,3,2] row_mask:0xf bank_mask:0xf
	v_fmac_f32_dpp v42, v41, v123 quad_perm:[1,0,3,2] row_mask:0xf bank_mask:0xf
	v_cvt_pk_bf16_f32 v148, v26, v42
	ds_write_b32 v151, v148 offset:4896
	v_fmac_f32_e32 v27, v116, v26
	v_fmac_f32_e32 v43, v118, v42
	v_fmac_f32_dpp v27, v26, v122 quad_perm:[1,0,3,2] row_mask:0xf bank_mask:0xf
	v_fmac_f32_dpp v43, v42, v123 quad_perm:[1,0,3,2] row_mask:0xf bank_mask:0xf
	v_cvt_pk_bf16_f32 v149, v27, v43
	ds_write_b32 v151, v149 offset:5168
	v_fmac_f32_e32 v56, v116, v27
	v_fmac_f32_e32 v72, v118, v43
	v_fmac_f32_dpp v56, v27, v122 quad_perm:[1,0,3,2] row_mask:0xf bank_mask:0xf
	v_fmac_f32_dpp v72, v43, v123 quad_perm:[1,0,3,2] row_mask:0xf bank_mask:0xf
	v_cvt_pk_bf16_f32 v148, v56, v72
	ds_write_b32 v151, v148 offset:5440
	v_fmac_f32_e32 v57, v116, v56
	v_fmac_f32_e32 v73, v118, v72
	v_fmac_f32_dpp v57, v56, v122 quad_perm:[1,0,3,2] row_mask:0xf bank_mask:0xf
	v_fmac_f32_dpp v73, v72, v123 quad_perm:[1,0,3,2] row_mask:0xf bank_mask:0xf
	v_cvt_pk_bf16_f32 v149, v57, v73
	ds_write_b32 v151, v149 offset:5712
	v_fmac_f32_e32 v58, v116, v57
	v_fmac_f32_e32 v74, v118, v73
	v_fmac_f32_dpp v58, v57, v122 quad_perm:[1,0,3,2] row_mask:0xf bank_mask:0xf
	v_fmac_f32_dpp v74, v73, v123 quad_perm:[1,0,3,2] row_mask:0xf bank_mask:0xf
	v_cvt_pk_bf16_f32 v148, v58, v74
	ds_write_b32 v151, v148 offset:5984
	v_fmac_f32_e32 v59, v116, v58
	v_fmac_f32_e32 v75, v118, v74
	v_fmac_f32_dpp v59, v58, v122 quad_perm:[1,0,3,2] row_mask:0xf bank_mask:0xf
	v_fmac_f32_dpp v75, v74, v123 quad_perm:[1,0,3,2] row_mask:0xf bank_mask:0xf
	v_cvt_pk_bf16_f32 v149, v59, v75
	ds_write_b32 v151, v149 offset:6256
	v_fmac_f32_e32 v28, v116, v59
	v_fmac_f32_e32 v44, v118, v75
	v_fmac_f32_dpp v28, v59, v122 quad_perm:[1,0,3,2] row_mask:0xf bank_mask:0xf
	v_fmac_f32_dpp v44, v75, v123 quad_perm:[1,0,3,2] row_mask:0xf bank_mask:0xf
	v_cvt_pk_bf16_f32 v148, v28, v44
	ds_write_b32 v151, v148 offset:6528
	v_fmac_f32_e32 v29, v116, v28
	v_fmac_f32_e32 v45, v118, v44
	v_fmac_f32_dpp v29, v28, v122 quad_perm:[1,0,3,2] row_mask:0xf bank_mask:0xf
	v_fmac_f32_dpp v45, v44, v123 quad_perm:[1,0,3,2] row_mask:0xf bank_mask:0xf
	v_cvt_pk_bf16_f32 v149, v29, v45
	ds_write_b32 v151, v149 offset:6800
	v_fmac_f32_e32 v30, v116, v29
	v_fmac_f32_e32 v46, v118, v45
	v_fmac_f32_dpp v30, v29, v122 quad_perm:[1,0,3,2] row_mask:0xf bank_mask:0xf
	v_fmac_f32_dpp v46, v45, v123 quad_perm:[1,0,3,2] row_mask:0xf bank_mask:0xf
	v_cvt_pk_bf16_f32 v148, v30, v46
	ds_write_b32 v151, v148 offset:7072
	v_fmac_f32_e32 v31, v116, v30
	v_fmac_f32_e32 v47, v118, v46
	v_fmac_f32_dpp v31, v30, v122 quad_perm:[1,0,3,2] row_mask:0xf bank_mask:0xf
	v_fmac_f32_dpp v47, v46, v123 quad_perm:[1,0,3,2] row_mask:0xf bank_mask:0xf
	v_cvt_pk_bf16_f32 v149, v31, v47
	ds_write_b32 v151, v149 offset:7344
	v_fmac_f32_e32 v60, v116, v31
	v_fmac_f32_e32 v76, v118, v47
	v_fmac_f32_dpp v60, v31, v122 quad_perm:[1,0,3,2] row_mask:0xf bank_mask:0xf
	v_fmac_f32_dpp v76, v47, v123 quad_perm:[1,0,3,2] row_mask:0xf bank_mask:0xf
	v_cvt_pk_bf16_f32 v148, v60, v76
	ds_write_b32 v151, v148 offset:7616
	v_fmac_f32_e32 v61, v116, v60
	v_fmac_f32_e32 v77, v118, v76
	v_fmac_f32_dpp v61, v60, v122 quad_perm:[1,0,3,2] row_mask:0xf bank_mask:0xf
	v_fmac_f32_dpp v77, v76, v123 quad_perm:[1,0,3,2] row_mask:0xf bank_mask:0xf
	v_cvt_pk_bf16_f32 v149, v61, v77
	ds_write_b32 v151, v149 offset:7888
	v_fmac_f32_e32 v62, v116, v61
	v_fmac_f32_e32 v78, v118, v77
	v_fmac_f32_dpp v62, v61, v122 quad_perm:[1,0,3,2] row_mask:0xf bank_mask:0xf
	v_fmac_f32_dpp v78, v77, v123 quad_perm:[1,0,3,2] row_mask:0xf bank_mask:0xf
	v_cvt_pk_bf16_f32 v148, v62, v78
	ds_write_b32 v151, v148 offset:8160
	v_fmac_f32_e32 v63, v116, v62
	v_fmac_f32_e32 v79, v118, v78
	v_fmac_f32_dpp v63, v62, v122 quad_perm:[1,0,3,2] row_mask:0xf bank_mask:0xf
	v_fmac_f32_dpp v79, v78, v123 quad_perm:[1,0,3,2] row_mask:0xf bank_mask:0xf
	v_cvt_pk_bf16_f32 v149, v63, v79
	ds_write_b32 v151, v149 offset:8432
	v_mov_b32_e32 v120, v63
	v_mov_b32_e32 v121, v79
	ds_read_b128 v[124:127], v152
	ds_read_b128 v[128:131], v152 offset:64
	ds_read_b128 v[132:135], v152 offset:128
	ds_read_b128 v[136:139], v152 offset:192
	s_waitcnt lgkmcnt(3)
	v_mfma_f32_16x16x32_bf16 v[140:143], v[100:103], v[124:127], 0
	s_waitcnt lgkmcnt(2)
	v_mfma_f32_16x16x32_bf16 v[140:143], v[104:107], v[128:131], v[140:143]
	s_waitcnt lgkmcnt(1)
	v_mfma_f32_16x16x32_bf16 v[140:143], v[108:111], v[132:135], v[140:143]
	s_waitcnt lgkmcnt(0)
	v_mfma_f32_16x16x32_bf16 v[140:143], v[112:115], v[136:139], v[140:143]
	s_nop 9
	global_store_dwordx4 v153, v[140:143], s[12:13]
	s_nop 1
	ds_read_b128 v[124:127], v152 offset:4352
	ds_read_b128 v[128:131], v152 offset:4416
	ds_read_b128 v[132:135], v152 offset:4480
	ds_read_b128 v[136:139], v152 offset:4544
	s_waitcnt lgkmcnt(3)
	v_mfma_f32_16x16x32_bf16 v[140:143], v[100:103], v[124:127], 0
	s_waitcnt lgkmcnt(2)
	v_mfma_f32_16x16x32_bf16 v[140:143], v[104:107], v[128:131], v[140:143]
	s_waitcnt lgkmcnt(1)
	v_mfma_f32_16x16x32_bf16 v[140:143], v[108:111], v[132:135], v[140:143]
	s_waitcnt lgkmcnt(0)
	v_mfma_f32_16x16x32_bf16 v[140:143], v[112:115], v[136:139], v[140:143]
	s_nop 9
	global_store_dwordx4 v157, v[140:143], s[12:13]
	s_nop 1
	s_add_u32 s12, s12, 2048
	s_addc_u32 s13, s13, 0
	s_waitcnt vmcnt(5)
	v_mfma_f32_32x32x16_bf16 v[16:31], v[144:147], v[84:87], 0
	v_mfma_f32_32x32x16_bf16 v[32:47], v[144:147], v[88:91], 0
	v_mfma_f32_32x32x16_bf16 v[48:63], v[144:147], v[92:95], 0
	v_mfma_f32_32x32x16_bf16 v[64:79], v[144:147], v[96:99], 0
	s_nop 11
	global_load_dwordx4 v[144:147], v150, s[10:11]
	s_add_u32 s34, s34, 1024
	s_addc_u32 s35, s35, 0
	s_add_u32 s10, s10, 1024
	s_addc_u32 s11, s11, 0
	v_permlane32_swap_b32_e32 v16, v48
	v_permlane32_swap_b32_e32 v17, v49
	v_permlane32_swap_b32_e32 v18, v50
	v_permlane32_swap_b32_e32 v19, v51
	v_permlane32_swap_b32_e32 v20, v52
	v_permlane32_swap_b32_e32 v21, v53
	v_permlane32_swap_b32_e32 v22, v54
	v_permlane32_swap_b32_e32 v23, v55
	v_permlane32_swap_b32_e32 v24, v56
	v_permlane32_swap_b32_e32 v25, v57
	v_permlane32_swap_b32_e32 v26, v58
	v_permlane32_swap_b32_e32 v27, v59
	v_permlane32_swap_b32_e32 v28, v60
	v_permlane32_swap_b32_e32 v29, v61
	v_permlane32_swap_b32_e32 v30, v62
	v_permlane32_swap_b32_e32 v31, v63
	v_permlane32_swap_b32_e32 v32, v64
	v_permlane32_swap_b32_e32 v33, v65
	v_permlane32_swap_b32_e32 v34, v66
	v_permlane32_swap_b32_e32 v35, v67
	v_permlane32_swap_b32_e32 v36, v68
	v_permlane32_swap_b32_e32 v37, v69
	v_permlane32_swap_b32_e32 v38, v70
	v_permlane32_swap_b32_e32 v39, v71
	v_permlane32_swap_b32_e32 v40, v72
	v_permlane32_swap_b32_e32 v41, v73
	v_permlane32_swap_b32_e32 v42, v74
	v_permlane32_swap_b32_e32 v43, v75
	v_permlane32_swap_b32_e32 v44, v76
	v_permlane32_swap_b32_e32 v45, v77
	v_permlane32_swap_b32_e32 v46, v78
	v_permlane32_swap_b32_e32 v47, v79
	v_fmac_f32_e32 v16, v116, v120
	v_fmac_f32_e32 v32, v118, v121
	v_fmac_f32_dpp v16, v120, v122 quad_perm:[1,0,3,2] row_mask:0xf bank_mask:0xf
	v_fmac_f32_dpp v32, v121, v123 quad_perm:[1,0,3,2] row_mask:0xf bank_mask:0xf
	v_cvt_pk_bf16_f32 v148, v16, v32
	ds_write_b32 v151, v148
	v_fmac_f32_e32 v17, v116, v16
	v_fmac_f32_e32 v33, v118, v32
	v_fmac_f32_dpp v17, v16, v122 quad_perm:[1,0,3,2] row_mask:0xf bank_mask:0xf
	v_fmac_f32_dpp v33, v32, v123 quad_perm:[1,0,3,2] row_mask:0xf bank_mask:0xf
	v_cvt_pk_bf16_f32 v149, v17, v33
	ds_write_b32 v151, v149 offset:272
	v_fmac_f32_e32 v18, v116, v17
	v_fmac_f32_e32 v34, v118, v33
	v_fmac_f32_dpp v18, v17, v122 quad_perm:[1,0,3,2] row_mask:0xf bank_mask:0xf
	v_fmac_f32_dpp v34, v33, v123 quad_perm:[1,0,3,2] row_mask:0xf bank_mask:0xf
	v_cvt_pk_bf16_f32 v148, v18, v34
	ds_write_b32 v151, v148 offset:544
	v_fmac_f32_e32 v19, v116, v18
	v_fmac_f32_e32 v35, v118, v34
	v_fmac_f32_dpp v19, v18, v122 quad_perm:[1,0,3,2] row_mask:0xf bank_mask:0xf
	v_fmac_f32_dpp v35, v34, v123 quad_perm:[1,0,3,2] row_mask:0xf bank_mask:0xf
	v_cvt_pk_bf16_f32 v149, v19, v35
	ds_write_b32 v151, v149 offset:816
	v_fmac_f32_e32 v48, v116, v19
	v_fmac_f32_e32 v64, v118, v35
	v_fmac_f32_dpp v48, v19, v122 quad_perm:[1,0,3,2] row_mask:0xf bank_mask:0xf
	v_fmac_f32_dpp v64, v35, v123 quad_perm:[1,0,3,2] row_mask:0xf bank_mask:0xf
	v_cvt_pk_bf16_f32 v148, v48, v64
	ds_write_b32 v151, v148 offset:1088
	v_fmac_f32_e32 v49, v116, v48
	v_fmac_f32_e32 v65, v118, v64
	v_fmac_f32_dpp v49, v48, v122 quad_perm:[1,0,3,2] row_mask:0xf bank_mask:0xf
	v_fmac_f32_dpp v65, v64, v123 quad_perm:[1,0,3,2] row_mask:0xf bank_mask:0xf
	v_cvt_pk_bf16_f32 v149, v49, v65
	ds_write_b32 v151, v149 offset:1360
	v_fmac_f32_e32 v50, v116, v49
	v_fmac_f32_e32 v66, v118, v65
	v_fmac_f32_dpp v50, v49, v122 quad_perm:[1,0,3,2] row_mask:0xf bank_mask:0xf
	v_fmac_f32_dpp v66, v65, v123 quad_perm:[1,0,3,2] row_mask:0xf bank_mask:0xf
	v_cvt_pk_bf16_f32 v148, v50, v66
	ds_write_b32 v151, v148 offset:1632
	v_fmac_f32_e32 v51, v116, v50
	v_fmac_f32_e32 v67, v118, v66
	v_fmac_f32_dpp v51, v50, v122 quad_perm:[1,0,3,2] row_mask:0xf bank_mask:0xf
	v_fmac_f32_dpp v67, v66, v123 quad_perm:[1,0,3,2] row_mask:0xf bank_mask:0xf
	v_cvt_pk_bf16_f32 v149, v51, v67
	ds_write_b32 v151, v149 offset:1904
	v_fmac_f32_e32 v20, v116, v51
	v_fmac_f32_e32 v36, v118, v67
	v_fmac_f32_dpp v20, v51, v122 quad_perm:[1,0,3,2] row_mask:0xf bank_mask:0xf
	v_fmac_f32_dpp v36, v67, v123 quad_perm:[1,0,3,2] row_mask:0xf bank_mask:0xf
	v_cvt_pk_bf16_f32 v148, v20, v36
	ds_write_b32 v151, v148 offset:2176
	v_fmac_f32_e32 v21, v116, v20
	v_fmac_f32_e32 v37, v118, v36
	v_fmac_f32_dpp v21, v20, v122 quad_perm:[1,0,3,2] row_mask:0xf bank_mask:0xf
	v_fmac_f32_dpp v37, v36, v123 quad_perm:[1,0,3,2] row_mask:0xf bank_mask:0xf
	v_cvt_pk_bf16_f32 v149, v21, v37
	ds_write_b32 v151, v149 offset:2448
	v_fmac_f32_e32 v22, v116, v21
	v_fmac_f32_e32 v38, v118, v37
	v_fmac_f32_dpp v22, v21, v122 quad_perm:[1,0,3,2] row_mask:0xf bank_mask:0xf
	v_fmac_f32_dpp v38, v37, v123 quad_perm:[1,0,3,2] row_mask:0xf bank_mask:0xf
	v_cvt_pk_bf16_f32 v148, v22, v38
	ds_write_b32 v151, v148 offset:2720
	v_fmac_f32_e32 v23, v116, v22
	v_fmac_f32_e32 v39, v118, v38
	v_fmac_f32_dpp v23, v22, v122 quad_perm:[1,0,3,2] row_mask:0xf bank_mask:0xf
	v_fmac_f32_dpp v39, v38, v123 quad_perm:[1,0,3,2] row_mask:0xf bank_mask:0xf
	v_cvt_pk_bf16_f32 v149, v23, v39
	ds_write_b32 v151, v149 offset:2992
	v_fmac_f32_e32 v52, v116, v23
	v_fmac_f32_e32 v68, v118, v39
	v_fmac_f32_dpp v52, v23, v122 quad_perm:[1,0,3,2] row_mask:0xf bank_mask:0xf
	v_fmac_f32_dpp v68, v39, v123 quad_perm:[1,0,3,2] row_mask:0xf bank_mask:0xf
	v_cvt_pk_bf16_f32 v148, v52, v68
	ds_write_b32 v151, v148 offset:3264
	v_fmac_f32_e32 v53, v116, v52
	v_fmac_f32_e32 v69, v118, v68
	v_fmac_f32_dpp v53, v52, v122 quad_perm:[1,0,3,2] row_mask:0xf bank_mask:0xf
	v_fmac_f32_dpp v69, v68, v123 quad_perm:[1,0,3,2] row_mask:0xf bank_mask:0xf
	v_cvt_pk_bf16_f32 v149, v53, v69
	ds_write_b32 v151, v149 offset:3536
	v_fmac_f32_e32 v54, v116, v53
	v_fmac_f32_e32 v70, v118, v69
	v_fmac_f32_dpp v54, v53, v122 quad_perm:[1,0,3,2] row_mask:0xf bank_mask:0xf
	v_fmac_f32_dpp v70, v69, v123 quad_perm:[1,0,3,2] row_mask:0xf bank_mask:0xf
	v_cvt_pk_bf16_f32 v148, v54, v70
	ds_write_b32 v151, v148 offset:3808
	v_fmac_f32_e32 v55, v116, v54
	v_fmac_f32_e32 v71, v118, v70
	v_fmac_f32_dpp v55, v54, v122 quad_perm:[1,0,3,2] row_mask:0xf bank_mask:0xf
	v_fmac_f32_dpp v71, v70, v123 quad_perm:[1,0,3,2] row_mask:0xf bank_mask:0xf
	v_cvt_pk_bf16_f32 v149, v55, v71
	ds_write_b32 v151, v149 offset:4080
	v_fmac_f32_e32 v24, v116, v55
	v_fmac_f32_e32 v40, v118, v71
	v_fmac_f32_dpp v24, v55, v122 quad_perm:[1,0,3,2] row_mask:0xf bank_mask:0xf
	v_fmac_f32_dpp v40, v71, v123 quad_perm:[1,0,3,2] row_mask:0xf bank_mask:0xf
	v_cvt_pk_bf16_f32 v148, v24, v40
	ds_write_b32 v151, v148 offset:4352
	v_fmac_f32_e32 v25, v116, v24
	v_fmac_f32_e32 v41, v118, v40
	v_fmac_f32_dpp v25, v24, v122 quad_perm:[1,0,3,2] row_mask:0xf bank_mask:0xf
	v_fmac_f32_dpp v41, v40, v123 quad_perm:[1,0,3,2] row_mask:0xf bank_mask:0xf
	v_cvt_pk_bf16_f32 v149, v25, v41
	ds_write_b32 v151, v149 offset:4624
	v_fmac_f32_e32 v26, v116, v25
	v_fmac_f32_e32 v42, v118, v41
	v_fmac_f32_dpp v26, v25, v122 quad_perm:[1,0,3,2] row_mask:0xf bank_mask:0xf
	v_fmac_f32_dpp v42, v41, v123 quad_perm:[1,0,3,2] row_mask:0xf bank_mask:0xf
	v_cvt_pk_bf16_f32 v148, v26, v42
	ds_write_b32 v151, v148 offset:4896
	v_fmac_f32_e32 v27, v116, v26
	v_fmac_f32_e32 v43, v118, v42
	v_fmac_f32_dpp v27, v26, v122 quad_perm:[1,0,3,2] row_mask:0xf bank_mask:0xf
	v_fmac_f32_dpp v43, v42, v123 quad_perm:[1,0,3,2] row_mask:0xf bank_mask:0xf
	v_cvt_pk_bf16_f32 v149, v27, v43
	ds_write_b32 v151, v149 offset:5168
	v_fmac_f32_e32 v56, v116, v27
	v_fmac_f32_e32 v72, v118, v43
	v_fmac_f32_dpp v56, v27, v122 quad_perm:[1,0,3,2] row_mask:0xf bank_mask:0xf
	v_fmac_f32_dpp v72, v43, v123 quad_perm:[1,0,3,2] row_mask:0xf bank_mask:0xf
	v_cvt_pk_bf16_f32 v148, v56, v72
	ds_write_b32 v151, v148 offset:5440
	v_fmac_f32_e32 v57, v116, v56
	v_fmac_f32_e32 v73, v118, v72
	v_fmac_f32_dpp v57, v56, v122 quad_perm:[1,0,3,2] row_mask:0xf bank_mask:0xf
	v_fmac_f32_dpp v73, v72, v123 quad_perm:[1,0,3,2] row_mask:0xf bank_mask:0xf
	v_cvt_pk_bf16_f32 v149, v57, v73
	ds_write_b32 v151, v149 offset:5712
	v_fmac_f32_e32 v58, v116, v57
	v_fmac_f32_e32 v74, v118, v73
	v_fmac_f32_dpp v58, v57, v122 quad_perm:[1,0,3,2] row_mask:0xf bank_mask:0xf
	v_fmac_f32_dpp v74, v73, v123 quad_perm:[1,0,3,2] row_mask:0xf bank_mask:0xf
	v_cvt_pk_bf16_f32 v148, v58, v74
	ds_write_b32 v151, v148 offset:5984
	v_fmac_f32_e32 v59, v116, v58
	v_fmac_f32_e32 v75, v118, v74
	v_fmac_f32_dpp v59, v58, v122 quad_perm:[1,0,3,2] row_mask:0xf bank_mask:0xf
	v_fmac_f32_dpp v75, v74, v123 quad_perm:[1,0,3,2] row_mask:0xf bank_mask:0xf
	v_cvt_pk_bf16_f32 v149, v59, v75
	ds_write_b32 v151, v149 offset:6256
	v_fmac_f32_e32 v28, v116, v59
	v_fmac_f32_e32 v44, v118, v75
	v_fmac_f32_dpp v28, v59, v122 quad_perm:[1,0,3,2] row_mask:0xf bank_mask:0xf
	v_fmac_f32_dpp v44, v75, v123 quad_perm:[1,0,3,2] row_mask:0xf bank_mask:0xf
	v_cvt_pk_bf16_f32 v148, v28, v44
	ds_write_b32 v151, v148 offset:6528
	v_fmac_f32_e32 v29, v116, v28
	v_fmac_f32_e32 v45, v118, v44
	v_fmac_f32_dpp v29, v28, v122 quad_perm:[1,0,3,2] row_mask:0xf bank_mask:0xf
	v_fmac_f32_dpp v45, v44, v123 quad_perm:[1,0,3,2] row_mask:0xf bank_mask:0xf
	v_cvt_pk_bf16_f32 v149, v29, v45
	ds_write_b32 v151, v149 offset:6800
	v_fmac_f32_e32 v30, v116, v29
	v_fmac_f32_e32 v46, v118, v45
	v_fmac_f32_dpp v30, v29, v122 quad_perm:[1,0,3,2] row_mask:0xf bank_mask:0xf
	v_fmac_f32_dpp v46, v45, v123 quad_perm:[1,0,3,2] row_mask:0xf bank_mask:0xf
	v_cvt_pk_bf16_f32 v148, v30, v46
	ds_write_b32 v151, v148 offset:7072
	v_fmac_f32_e32 v31, v116, v30
	v_fmac_f32_e32 v47, v118, v46
	v_fmac_f32_dpp v31, v30, v122 quad_perm:[1,0,3,2] row_mask:0xf bank_mask:0xf
	v_fmac_f32_dpp v47, v46, v123 quad_perm:[1,0,3,2] row_mask:0xf bank_mask:0xf
	v_cvt_pk_bf16_f32 v149, v31, v47
	ds_write_b32 v151, v149 offset:7344
	v_fmac_f32_e32 v60, v116, v31
	v_fmac_f32_e32 v76, v118, v47
	v_fmac_f32_dpp v60, v31, v122 quad_perm:[1,0,3,2] row_mask:0xf bank_mask:0xf
	v_fmac_f32_dpp v76, v47, v123 quad_perm:[1,0,3,2] row_mask:0xf bank_mask:0xf
	v_cvt_pk_bf16_f32 v148, v60, v76
	ds_write_b32 v151, v148 offset:7616
	v_fmac_f32_e32 v61, v116, v60
	v_fmac_f32_e32 v77, v118, v76
	v_fmac_f32_dpp v61, v60, v122 quad_perm:[1,0,3,2] row_mask:0xf bank_mask:0xf
	v_fmac_f32_dpp v77, v76, v123 quad_perm:[1,0,3,2] row_mask:0xf bank_mask:0xf
	v_cvt_pk_bf16_f32 v149, v61, v77
	ds_write_b32 v151, v149 offset:7888
	v_fmac_f32_e32 v62, v116, v61
	v_fmac_f32_e32 v78, v118, v77
	v_fmac_f32_dpp v62, v61, v122 quad_perm:[1,0,3,2] row_mask:0xf bank_mask:0xf
	v_fmac_f32_dpp v78, v77, v123 quad_perm:[1,0,3,2] row_mask:0xf bank_mask:0xf
	v_cvt_pk_bf16_f32 v148, v62, v78
	ds_write_b32 v151, v148 offset:8160
	v_fmac_f32_e32 v63, v116, v62
	v_fmac_f32_e32 v79, v118, v78
	v_fmac_f32_dpp v63, v62, v122 quad_perm:[1,0,3,2] row_mask:0xf bank_mask:0xf
	v_fmac_f32_dpp v79, v78, v123 quad_perm:[1,0,3,2] row_mask:0xf bank_mask:0xf
	v_cvt_pk_bf16_f32 v149, v63, v79
	ds_write_b32 v151, v149 offset:8432
	v_mov_b32_e32 v120, v63
	v_mov_b32_e32 v121, v79
	ds_read_b128 v[124:127], v152
	ds_read_b128 v[128:131], v152 offset:64
	ds_read_b128 v[132:135], v152 offset:128
	ds_read_b128 v[136:139], v152 offset:192
	s_waitcnt lgkmcnt(3)
	v_mfma_f32_16x16x32_bf16 v[140:143], v[100:103], v[124:127], 0
	s_waitcnt lgkmcnt(2)
	v_mfma_f32_16x16x32_bf16 v[140:143], v[104:107], v[128:131], v[140:143]
	s_waitcnt lgkmcnt(1)
	v_mfma_f32_16x16x32_bf16 v[140:143], v[108:111], v[132:135], v[140:143]
	s_waitcnt lgkmcnt(0)
	v_mfma_f32_16x16x32_bf16 v[140:143], v[112:115], v[136:139], v[140:143]
	s_nop 9
	global_store_dwordx4 v153, v[140:143], s[12:13]
	s_nop 1
	ds_read_b128 v[124:127], v152 offset:4352
	ds_read_b128 v[128:131], v152 offset:4416
	ds_read_b128 v[132:135], v152 offset:4480
	ds_read_b128 v[136:139], v152 offset:4544
	s_waitcnt lgkmcnt(3)
	v_mfma_f32_16x16x32_bf16 v[140:143], v[100:103], v[124:127], 0
	s_waitcnt lgkmcnt(2)
	v_mfma_f32_16x16x32_bf16 v[140:143], v[104:107], v[128:131], v[140:143]
	s_waitcnt lgkmcnt(1)
	v_mfma_f32_16x16x32_bf16 v[140:143], v[108:111], v[132:135], v[140:143]
	s_waitcnt lgkmcnt(0)
	v_mfma_f32_16x16x32_bf16 v[140:143], v[112:115], v[136:139], v[140:143]
	s_nop 9
	global_store_dwordx4 v157, v[140:143], s[12:13]
	s_nop 1
	s_add_u32 s12, s12, 2048
	s_addc_u32 s13, s13, 0
	s_add_u32 s14, s14, 2
	s_cmp_lt_u32 s14, 16
	s_cbranch_scc1 .Lssm_tileA_d0m0
	s_waitcnt vmcnt(0) lgkmcnt(0)
	s_lshr_b32 s21, s89, 1
	s_lshl_b32 s21, s21, 2
	s_add_u32 s37, s21, 0x21000
	v_mov_b32_e32 v182, s37
	v_mov_b32_e32 v183, 1
	v_cmp_eq_u32_e32 vcc, 0, v191
	s_and_saveexec_b64 s[0:1], vcc
	ds_add_u32 v182, v183
	s_mov_b64 exec, s[0:1]
	s_waitcnt lgkmcnt(0)
	s_mov_b32 s38, 0

.Lssm_spin_done_d0m0:
	s_mov_b64 s[42:43], s[6:7]
	s_add_u32 s42, s42, 32768
	s_addc_u32 s43, s43, 0
	s_lshl_b32 s31, s25, 11
	s_lshl_b32 s29, s24, 5
	s_add_u32 s31, s31, s29
	s_add_u32 s31, s31, 344981504
	s_add_u32 s12, s62, s31
	s_addc_u32 s13, s63, 0
	s_mov_b64 s[64:65], s[34:35]
	s_sub_u32 s64, s64, 1024
	s_subb_u32 s65, s65, 0
	global_load_dwordx4 v[6:9], v153, s[42:43]
	global_load_dwordx4 v[10:13], v157, s[42:43]
	s_add_u32 s42, s42, 2048
	s_addc_u32 s43, s43, 0
	s_waitcnt vmcnt(0)
.Lssm_tileB_d0m0:
	s_waitcnt vmcnt(7)
	v_mfma_f32_32x32x16_bf16 v[16:31], v[80:83], v[84:87], 0
	v_mfma_f32_32x32x16_bf16 v[32:47], v[80:83], v[88:91], 0
	v_mfma_f32_32x32x16_bf16 v[48:63], v[80:83], v[92:95], 0
	v_mfma_f32_32x32x16_bf16 v[64:79], v[80:83], v[96:99], 0
	ds_write_b128 v162, v[80:83]
	global_load_dwordx4 v[172:175], v153, s[42:43]
	global_load_dwordx4 v[176:179], v157, s[42:43]
	s_add_u32 s42, s42, 2048
	s_addc_u32 s43, s43, 0
	s_nop 11
	global_load_dwordx4 v[80:83], v150, s[10:11]
	s_add_u32 s34, s34, 1024
	s_addc_u32 s35, s35, 0
	s_add_u32 s10, s10, 1024
	s_addc_u32 s11, s11, 0
	v_permlane32_swap_b32_e32 v16, v48
	v_permlane32_swap_b32_e32 v17, v49
	v_permlane32_swap_b32_e32 v18, v50
	v_permlane32_swap_b32_e32 v19, v51
	v_permlane32_swap_b32_e32 v20, v52
	v_permlane32_swap_b32_e32 v21, v53
	v_permlane32_swap_b32_e32 v22, v54
	v_permlane32_swap_b32_e32 v23, v55
	v_permlane32_swap_b32_e32 v24, v56
	v_permlane32_swap_b32_e32 v25, v57
	v_permlane32_swap_b32_e32 v26, v58
	v_permlane32_swap_b32_e32 v27, v59
	v_permlane32_swap_b32_e32 v28, v60
	v_permlane32_swap_b32_e32 v29, v61
	v_permlane32_swap_b32_e32 v30, v62
	v_permlane32_swap_b32_e32 v31, v63
	v_permlane32_swap_b32_e32 v32, v64
	v_permlane32_swap_b32_e32 v33, v65
	v_permlane32_swap_b32_e32 v34, v66
	v_permlane32_swap_b32_e32 v35, v67
	v_permlane32_swap_b32_e32 v36, v68
	v_permlane32_swap_b32_e32 v37, v69
	v_permlane32_swap_b32_e32 v38, v70
	v_permlane32_swap_b32_e32 v39, v71
	v_permlane32_swap_b32_e32 v40, v72
	v_permlane32_swap_b32_e32 v41, v73
	v_permlane32_swap_b32_e32 v42, v74
	v_permlane32_swap_b32_e32 v43, v75
	v_permlane32_swap_b32_e32 v44, v76
	v_permlane32_swap_b32_e32 v45, v77
	v_permlane32_swap_b32_e32 v46, v78
	v_permlane32_swap_b32_e32 v47, v79
	v_fmac_f32_e32 v16, v116, v120
	v_fmac_f32_e32 v32, v118, v121
	v_fmac_f32_dpp v16, v120, v122 quad_perm:[1,0,3,2] row_mask:0xf bank_mask:0xf
	v_fmac_f32_dpp v32, v121, v123 quad_perm:[1,0,3,2] row_mask:0xf bank_mask:0xf
	v_cvt_pk_bf16_f32 v148, v16, v32
	ds_write_b32 v151, v148
	v_fmac_f32_e32 v17, v116, v16
	v_fmac_f32_e32 v33, v118, v32
	v_fmac_f32_dpp v17, v16, v122 quad_perm:[1,0,3,2] row_mask:0xf bank_mask:0xf
	v_fmac_f32_dpp v33, v32, v123 quad_perm:[1,0,3,2] row_mask:0xf bank_mask:0xf
	v_cvt_pk_bf16_f32 v149, v17, v33
	ds_write_b32 v151, v149 offset:272
	v_fmac_f32_e32 v18, v116, v17
	v_fmac_f32_e32 v34, v118, v33
	v_fmac_f32_dpp v18, v17, v122 quad_perm:[1,0,3,2] row_mask:0xf bank_mask:0xf
	v_fmac_f32_dpp v34, v33, v123 quad_perm:[1,0,3,2] row_mask:0xf bank_mask:0xf
	v_cvt_pk_bf16_f32 v148, v18, v34
	ds_write_b32 v151, v148 offset:544
	v_fmac_f32_e32 v19, v116, v18
	v_fmac_f32_e32 v35, v118, v34
	v_fmac_f32_dpp v19, v18, v122 quad_perm:[1,0,3,2] row_mask:0xf bank_mask:0xf
	v_fmac_f32_dpp v35, v34, v123 quad_perm:[1,0,3,2] row_mask:0xf bank_mask:0xf
	v_cvt_pk_bf16_f32 v149, v19, v35
	ds_write_b32 v151, v149 offset:816
	v_fmac_f32_e32 v48, v116, v19
	v_fmac_f32_e32 v64, v118, v35
	v_fmac_f32_dpp v48, v19, v122 quad_perm:[1,0,3,2] row_mask:0xf bank_mask:0xf
	v_fmac_f32_dpp v64, v35, v123 quad_perm:[1,0,3,2] row_mask:0xf bank_mask:0xf
	v_cvt_pk_bf16_f32 v148, v48, v64
	ds_write_b32 v151, v148 offset:1088
	v_fmac_f32_e32 v49, v116, v48
	v_fmac_f32_e32 v65, v118, v64
	v_fmac_f32_dpp v49, v48, v122 quad_perm:[1,0,3,2] row_mask:0xf bank_mask:0xf
	v_fmac_f32_dpp v65, v64, v123 quad_perm:[1,0,3,2] row_mask:0xf bank_mask:0xf
	v_cvt_pk_bf16_f32 v149, v49, v65
	ds_write_b32 v151, v149 offset:1360
	v_fmac_f32_e32 v50, v116, v49
	v_fmac_f32_e32 v66, v118, v65
	v_fmac_f32_dpp v50, v49, v122 quad_perm:[1,0,3,2] row_mask:0xf bank_mask:0xf
	v_fmac_f32_dpp v66, v65, v123 quad_perm:[1,0,3,2] row_mask:0xf bank_mask:0xf
	v_cvt_pk_bf16_f32 v148, v50, v66
	ds_write_b32 v151, v148 offset:1632
	v_fmac_f32_e32 v51, v116, v50
	v_fmac_f32_e32 v67, v118, v66
	v_fmac_f32_dpp v51, v50, v122 quad_perm:[1,0,3,2] row_mask:0xf bank_mask:0xf
	v_fmac_f32_dpp v67, v66, v123 quad_perm:[1,0,3,2] row_mask:0xf bank_mask:0xf
	v_cvt_pk_bf16_f32 v149, v51, v67
	ds_write_b32 v151, v149 offset:1904
	v_fmac_f32_e32 v20, v116, v51
	v_fmac_f32_e32 v36, v118, v67
	v_fmac_f32_dpp v20, v51, v122 quad_perm:[1,0,3,2] row_mask:0xf bank_mask:0xf
	v_fmac_f32_dpp v36, v67, v123 quad_perm:[1,0,3,2] row_mask:0xf bank_mask:0xf
	v_cvt_pk_bf16_f32 v148, v20, v36
	ds_write_b32 v151, v148 offset:2176
	v_fmac_f32_e32 v21, v116, v20
	v_fmac_f32_e32 v37, v118, v36
	v_fmac_f32_dpp v21, v20, v122 quad_perm:[1,0,3,2] row_mask:0xf bank_mask:0xf
	v_fmac_f32_dpp v37, v36, v123 quad_perm:[1,0,3,2] row_mask:0xf bank_mask:0xf
	v_cvt_pk_bf16_f32 v149, v21, v37
	ds_write_b32 v151, v149 offset:2448
	v_fmac_f32_e32 v22, v116, v21
	v_fmac_f32_e32 v38, v118, v37
	v_fmac_f32_dpp v22, v21, v122 quad_perm:[1,0,3,2] row_mask:0xf bank_mask:0xf
	v_fmac_f32_dpp v38, v37, v123 quad_perm:[1,0,3,2] row_mask:0xf bank_mask:0xf
	v_cvt_pk_bf16_f32 v148, v22, v38
	ds_write_b32 v151, v148 offset:2720
	v_fmac_f32_e32 v23, v116, v22
	v_fmac_f32_e32 v39, v118, v38
	v_fmac_f32_dpp v23, v22, v122 quad_perm:[1,0,3,2] row_mask:0xf bank_mask:0xf
	v_fmac_f32_dpp v39, v38, v123 quad_perm:[1,0,3,2] row_mask:0xf bank_mask:0xf
	v_cvt_pk_bf16_f32 v149, v23, v39
	ds_write_b32 v151, v149 offset:2992
	v_fmac_f32_e32 v52, v116, v23
	v_fmac_f32_e32 v68, v118, v39
	v_fmac_f32_dpp v52, v23, v122 quad_perm:[1,0,3,2] row_mask:0xf bank_mask:0xf
	v_fmac_f32_dpp v68, v39, v123 quad_perm:[1,0,3,2] row_mask:0xf bank_mask:0xf
	v_cvt_pk_bf16_f32 v148, v52, v68
	ds_write_b32 v151, v148 offset:3264
	v_fmac_f32_e32 v53, v116, v52
	v_fmac_f32_e32 v69, v118, v68
	v_fmac_f32_dpp v53, v52, v122 quad_perm:[1,0,3,2] row_mask:0xf bank_mask:0xf
	v_fmac_f32_dpp v69, v68, v123 quad_perm:[1,0,3,2] row_mask:0xf bank_mask:0xf
	v_cvt_pk_bf16_f32 v149, v53, v69
	ds_write_b32 v151, v149 offset:3536
	v_fmac_f32_e32 v54, v116, v53
	v_fmac_f32_e32 v70, v118, v69
	v_fmac_f32_dpp v54, v53, v122 quad_perm:[1,0,3,2] row_mask:0xf bank_mask:0xf
	v_fmac_f32_dpp v70, v69, v123 quad_perm:[1,0,3,2] row_mask:0xf bank_mask:0xf
	v_cvt_pk_bf16_f32 v148, v54, v70
	ds_write_b32 v151, v148 offset:3808
	v_fmac_f32_e32 v55, v116, v54
	v_fmac_f32_e32 v71, v118, v70
	v_fmac_f32_dpp v55, v54, v122 quad_perm:[1,0,3,2] row_mask:0xf bank_mask:0xf
	v_fmac_f32_dpp v71, v70, v123 quad_perm:[1,0,3,2] row_mask:0xf bank_mask:0xf
	v_cvt_pk_bf16_f32 v149, v55, v71
	ds_write_b32 v151, v149 offset:4080
	v_fmac_f32_e32 v24, v116, v55
	v_fmac_f32_e32 v40, v118, v71
	v_fmac_f32_dpp v24, v55, v122 quad_perm:[1,0,3,2] row_mask:0xf bank_mask:0xf
	v_fmac_f32_dpp v40, v71, v123 quad_perm:[1,0,3,2] row_mask:0xf bank_mask:0xf
	v_cvt_pk_bf16_f32 v148, v24, v40
	ds_write_b32 v151, v148 offset:4352
	v_fmac_f32_e32 v25, v116, v24
	v_fmac_f32_e32 v41, v118, v40
	v_fmac_f32_dpp v25, v24, v122 quad_perm:[1,0,3,2] row_mask:0xf bank_mask:0xf
	v_fmac_f32_dpp v41, v40, v123 quad_perm:[1,0,3,2] row_mask:0xf bank_mask:0xf
	v_cvt_pk_bf16_f32 v149, v25, v41
	ds_write_b32 v151, v149 offset:4624
	v_fmac_f32_e32 v26, v116, v25
	v_fmac_f32_e32 v42, v118, v41
	v_fmac_f32_dpp v26, v25, v122 quad_perm:[1,0,3,2] row_mask:0xf bank_mask:0xf
	v_fmac_f32_dpp v42, v41, v123 quad_perm:[1,0,3,2] row_mask:0xf bank_mask:0xf
	v_cvt_pk_bf16_f32 v148, v26, v42
	ds_write_b32 v151, v148 offset:4896
	v_fmac_f32_e32 v27, v116, v26
	v_fmac_f32_e32 v43, v118, v42
	v_fmac_f32_dpp v27, v26, v122 quad_perm:[1,0,3,2] row_mask:0xf bank_mask:0xf
	v_fmac_f32_dpp v43, v42, v123 quad_perm:[1,0,3,2] row_mask:0xf bank_mask:0xf
	v_cvt_pk_bf16_f32 v149, v27, v43
	ds_write_b32 v151, v149 offset:5168
	v_fmac_f32_e32 v56, v116, v27
	v_fmac_f32_e32 v72, v118, v43
	v_fmac_f32_dpp v56, v27, v122 quad_perm:[1,0,3,2] row_mask:0xf bank_mask:0xf
	v_fmac_f32_dpp v72, v43, v123 quad_perm:[1,0,3,2] row_mask:0xf bank_mask:0xf
	v_cvt_pk_bf16_f32 v148, v56, v72
	ds_write_b32 v151, v148 offset:5440
	v_fmac_f32_e32 v57, v116, v56
	v_fmac_f32_e32 v73, v118, v72
	v_fmac_f32_dpp v57, v56, v122 quad_perm:[1,0,3,2] row_mask:0xf bank_mask:0xf
	v_fmac_f32_dpp v73, v72, v123 quad_perm:[1,0,3,2] row_mask:0xf bank_mask:0xf
	v_cvt_pk_bf16_f32 v149, v57, v73
	ds_write_b32 v151, v149 offset:5712
	v_fmac_f32_e32 v58, v116, v57
	v_fmac_f32_e32 v74, v118, v73
	v_fmac_f32_dpp v58, v57, v122 quad_perm:[1,0,3,2] row_mask:0xf bank_mask:0xf
	v_fmac_f32_dpp v74, v73, v123 quad_perm:[1,0,3,2] row_mask:0xf bank_mask:0xf
	v_cvt_pk_bf16_f32 v148, v58, v74
	ds_write_b32 v151, v148 offset:5984
	v_fmac_f32_e32 v59, v116, v58
	v_fmac_f32_e32 v75, v118, v74
	v_fmac_f32_dpp v59, v58, v122 quad_perm:[1,0,3,2] row_mask:0xf bank_mask:0xf
	v_fmac_f32_dpp v75, v74, v123 quad_perm:[1,0,3,2] row_mask:0xf bank_mask:0xf
	v_cvt_pk_bf16_f32 v149, v59, v75
	ds_write_b32 v151, v149 offset:6256
	v_fmac_f32_e32 v28, v116, v59
	v_fmac_f32_e32 v44, v118, v75
	v_fmac_f32_dpp v28, v59, v122 quad_perm:[1,0,3,2] row_mask:0xf bank_mask:0xf
	v_fmac_f32_dpp v44, v75, v123 quad_perm:[1,0,3,2] row_mask:0xf bank_mask:0xf
	v_cvt_pk_bf16_f32 v148, v28, v44
	ds_write_b32 v151, v148 offset:6528
	v_fmac_f32_e32 v29, v116, v28
	v_fmac_f32_e32 v45, v118, v44
	v_fmac_f32_dpp v29, v28, v122 quad_perm:[1,0,3,2] row_mask:0xf bank_mask:0xf
	v_fmac_f32_dpp v45, v44, v123 quad_perm:[1,0,3,2] row_mask:0xf bank_mask:0xf
	v_cvt_pk_bf16_f32 v149, v29, v45
	ds_write_b32 v151, v149 offset:6800
	v_fmac_f32_e32 v30, v116, v29
	v_fmac_f32_e32 v46, v118, v45
	v_fmac_f32_dpp v30, v29, v122 quad_perm:[1,0,3,2] row_mask:0xf bank_mask:0xf
	v_fmac_f32_dpp v46, v45, v123 quad_perm:[1,0,3,2] row_mask:0xf bank_mask:0xf
	v_cvt_pk_bf16_f32 v148, v30, v46
	ds_write_b32 v151, v148 offset:7072
	v_fmac_f32_e32 v31, v116, v30
	v_fmac_f32_e32 v47, v118, v46
	v_fmac_f32_dpp v31, v30, v122 quad_perm:[1,0,3,2] row_mask:0xf bank_mask:0xf
	v_fmac_f32_dpp v47, v46, v123 quad_perm:[1,0,3,2] row_mask:0xf bank_mask:0xf
	v_cvt_pk_bf16_f32 v149, v31, v47
	ds_write_b32 v151, v149 offset:7344
	v_fmac_f32_e32 v60, v116, v31
	v_fmac_f32_e32 v76, v118, v47
	v_fmac_f32_dpp v60, v31, v122 quad_perm:[1,0,3,2] row_mask:0xf bank_mask:0xf
	v_fmac_f32_dpp v76, v47, v123 quad_perm:[1,0,3,2] row_mask:0xf bank_mask:0xf
	v_cvt_pk_bf16_f32 v148, v60, v76
	ds_write_b32 v151, v148 offset:7616
	v_fmac_f32_e32 v61, v116, v60
	v_fmac_f32_e32 v77, v118, v76
	v_fmac_f32_dpp v61, v60, v122 quad_perm:[1,0,3,2] row_mask:0xf bank_mask:0xf
	v_fmac_f32_dpp v77, v76, v123 quad_perm:[1,0,3,2] row_mask:0xf bank_mask:0xf
	v_cvt_pk_bf16_f32 v149, v61, v77
	ds_write_b32 v151, v149 offset:7888
	v_fmac_f32_e32 v62, v116, v61
	v_fmac_f32_e32 v78, v118, v77
	v_fmac_f32_dpp v62, v61, v122 quad_perm:[1,0,3,2] row_mask:0xf bank_mask:0xf
	v_fmac_f32_dpp v78, v77, v123 quad_perm:[1,0,3,2] row_mask:0xf bank_mask:0xf
	v_cvt_pk_bf16_f32 v148, v62, v78
	ds_write_b32 v151, v148 offset:8160
	v_fmac_f32_e32 v63, v116, v62
	v_fmac_f32_e32 v79, v118, v78
	v_fmac_f32_dpp v63, v62, v122 quad_perm:[1,0,3,2] row_mask:0xf bank_mask:0xf
	v_fmac_f32_dpp v79, v78, v123 quad_perm:[1,0,3,2] row_mask:0xf bank_mask:0xf
	v_cvt_pk_bf16_f32 v149, v63, v79
	ds_write_b32 v151, v149 offset:8432
	v_mov_b32_e32 v120, v63
	v_mov_b32_e32 v121, v79
	ds_read_b128 v[124:127], v152
	ds_read_b128 v[128:131], v152 offset:64
	ds_read_b128 v[132:135], v152 offset:128
	ds_read_b128 v[136:139], v152 offset:192
	ds_read_b64 v[160:161], v163
	s_waitcnt lgkmcnt(4)
	v_mfma_f32_16x16x32_bf16 v[140:143], v[100:103], v[124:127], 0
	s_waitcnt lgkmcnt(3)
	v_mfma_f32_16x16x32_bf16 v[140:143], v[104:107], v[128:131], v[140:143]
	s_waitcnt lgkmcnt(2)
	v_mfma_f32_16x16x32_bf16 v[140:143], v[108:111], v[132:135], v[140:143]
	s_waitcnt lgkmcnt(1)
	v_mfma_f32_16x16x32_bf16 v[140:143], v[112:115], v[136:139], v[140:143]
	s_nop 9
	s_waitcnt vmcnt(7) lgkmcnt(0)
	v_add_f32_e32 v182, v6, v140
	v_add_f32_e32 v183, v7, v141
	v_add_f32_e32 v184, v8, v142
	v_add_f32_e32 v185, v9, v143
	v_lshlrev_b32_e32 v186, 16, v160
	v_and_b32_e32 v187, 0xffff0000, v160
	v_lshlrev_b32_e32 v188, 16, v161
	v_and_b32_e32 v189, 0xffff0000, v161
	v_fmac_f32_e32 v182, v164, v186
	v_fmac_f32_e32 v183, v165, v187
	v_fmac_f32_e32 v184, v166, v188
	v_fmac_f32_e32 v185, v167, v189
	v_mul_f32_e32 v186, 0x3d372713, v182
	v_mul_f32_e32 v187, 0x3d372713, v183
	v_mul_f32_e32 v188, 0x3d372713, v184
	v_mul_f32_e32 v189, 0x3d372713, v185
	v_mul_f32_e32 v186, v182, v186
	v_mul_f32_e32 v187, v183, v187
	v_mul_f32_e32 v188, v184, v188
	v_mul_f32_e32 v189, v185, v189
	v_fma_f32 v186, v182, v186, v182
	v_fma_f32 v187, v183, v187, v183
	v_fma_f32 v188, v184, v188, v184
	v_fma_f32 v189, v185, v189, v185
	v_mul_f32_e32 v186, 0xbfcc422a, v186
	v_mul_f32_e32 v187, 0xbfcc422a, v187
	v_mul_f32_e32 v188, 0xbfcc422a, v188
	v_mul_f32_e32 v189, 0xbfcc422a, v189
	v_mul_f32_e32 v186, 0x3fb8aa3b, v186
	v_mul_f32_e32 v187, 0x3fb8aa3b, v187
	v_mul_f32_e32 v188, 0x3fb8aa3b, v188
	v_mul_f32_e32 v189, 0x3fb8aa3b, v189
	v_exp_f32_e32 v186, v186
	v_exp_f32_e32 v187, v187
	v_exp_f32_e32 v188, v188
	v_exp_f32_e32 v189, v189
	v_add_f32_e32 v186, 1.0, v186
	v_add_f32_e32 v187, 1.0, v187
	v_add_f32_e32 v188, 1.0, v188
	v_add_f32_e32 v189, 1.0, v189
	v_rcp_f32_e32 v186, v186
	v_rcp_f32_e32 v187, v187
	v_rcp_f32_e32 v188, v188
	v_rcp_f32_e32 v189, v189
	v_mul_f32_e32 v182, v182, v186
	v_mul_f32_e32 v183, v183, v187
	v_mul_f32_e32 v184, v184, v188
	v_mul_f32_e32 v185, v185, v189
	v_cvt_pk_bf16_f32 v148, v182, v183
	v_cvt_pk_bf16_f32 v149, v184, v185
	global_store_dwordx2 v156, v[148:149], s[12:13]
	ds_read_b128 v[124:127], v152 offset:4352
	ds_read_b128 v[128:131], v152 offset:4416
	ds_read_b128 v[132:135], v152 offset:4480
	ds_read_b128 v[136:139], v152 offset:4544
	ds_read_b64 v[160:161], v163 offset:512
	s_waitcnt lgkmcnt(4)
	v_mfma_f32_16x16x32_bf16 v[140:143], v[100:103], v[124:127], 0
	s_waitcnt lgkmcnt(3)
	v_mfma_f32_16x16x32_bf16 v[140:143], v[104:107], v[128:131], v[140:143]
	s_waitcnt lgkmcnt(2)
	v_mfma_f32_16x16x32_bf16 v[140:143], v[108:111], v[132:135], v[140:143]
	s_waitcnt lgkmcnt(1)
	v_mfma_f32_16x16x32_bf16 v[140:143], v[112:115], v[136:139], v[140:143]
	s_nop 9
	s_waitcnt vmcnt(7) lgkmcnt(0)
	v_add_f32_e32 v182, v10, v140
	v_add_f32_e32 v183, v11, v141
	v_add_f32_e32 v184, v12, v142
	v_add_f32_e32 v185, v13, v143
	v_lshlrev_b32_e32 v186, 16, v160
	v_and_b32_e32 v187, 0xffff0000, v160
	v_lshlrev_b32_e32 v188, 16, v161
	v_and_b32_e32 v189, 0xffff0000, v161
	v_fmac_f32_e32 v182, v164, v186
	v_fmac_f32_e32 v183, v165, v187
	v_fmac_f32_e32 v184, v166, v188
	v_fmac_f32_e32 v185, v167, v189
	v_mul_f32_e32 v186, 0x3d372713, v182
	v_mul_f32_e32 v187, 0x3d372713, v183
	v_mul_f32_e32 v188, 0x3d372713, v184
	v_mul_f32_e32 v189, 0x3d372713, v185
	v_mul_f32_e32 v186, v182, v186
	v_mul_f32_e32 v187, v183, v187
	v_mul_f32_e32 v188, v184, v188
	v_mul_f32_e32 v189, v185, v189
	v_fma_f32 v186, v182, v186, v182
	v_fma_f32 v187, v183, v187, v183
	v_fma_f32 v188, v184, v188, v184
	v_fma_f32 v189, v185, v189, v185
	v_mul_f32_e32 v186, 0xbfcc422a, v186
	v_mul_f32_e32 v187, 0xbfcc422a, v187
	v_mul_f32_e32 v188, 0xbfcc422a, v188
	v_mul_f32_e32 v189, 0xbfcc422a, v189
	v_mul_f32_e32 v186, 0x3fb8aa3b, v186
	v_mul_f32_e32 v187, 0x3fb8aa3b, v187
	v_mul_f32_e32 v188, 0x3fb8aa3b, v188
	v_mul_f32_e32 v189, 0x3fb8aa3b, v189
	v_exp_f32_e32 v186, v186
	v_exp_f32_e32 v187, v187
	v_exp_f32_e32 v188, v188
	v_exp_f32_e32 v189, v189
	v_add_f32_e32 v186, 1.0, v186
	v_add_f32_e32 v187, 1.0, v187
	v_add_f32_e32 v188, 1.0, v188
	v_add_f32_e32 v189, 1.0, v189
	v_rcp_f32_e32 v186, v186
	v_rcp_f32_e32 v187, v187
	v_rcp_f32_e32 v188, v188
	v_rcp_f32_e32 v189, v189
	v_mul_f32_e32 v182, v182, v186
	v_mul_f32_e32 v183, v183, v187
	v_mul_f32_e32 v184, v184, v188
	v_mul_f32_e32 v185, v185, v189
	v_cvt_pk_bf16_f32 v148, v182, v183
	v_cvt_pk_bf16_f32 v149, v184, v185
	global_store_dwordx2 v159, v[148:149], s[12:13]
	s_add_u32 s12, s12, 65536
	s_addc_u32 s13, s13, 0
	s_waitcnt vmcnt(7)
	v_mfma_f32_32x32x16_bf16 v[16:31], v[144:147], v[84:87], 0
	v_mfma_f32_32x32x16_bf16 v[32:47], v[144:147], v[88:91], 0
	v_mfma_f32_32x32x16_bf16 v[48:63], v[144:147], v[92:95], 0
	v_mfma_f32_32x32x16_bf16 v[64:79], v[144:147], v[96:99], 0
	ds_write_b128 v162, v[144:147]
	global_load_dwordx4 v[6:9], v153, s[42:43]
	global_load_dwordx4 v[10:13], v157, s[42:43]
	s_add_u32 s42, s42, 2048
	s_addc_u32 s43, s43, 0
	s_nop 11
	global_load_dwordx4 v[144:147], v150, s[10:11]
	s_add_u32 s34, s34, 1024
	s_addc_u32 s35, s35, 0
	s_add_u32 s10, s10, 1024
	s_addc_u32 s11, s11, 0
	v_permlane32_swap_b32_e32 v16, v48
	v_permlane32_swap_b32_e32 v17, v49
	v_permlane32_swap_b32_e32 v18, v50
	v_permlane32_swap_b32_e32 v19, v51
	v_permlane32_swap_b32_e32 v20, v52
	v_permlane32_swap_b32_e32 v21, v53
	v_permlane32_swap_b32_e32 v22, v54
	v_permlane32_swap_b32_e32 v23, v55
	v_permlane32_swap_b32_e32 v24, v56
	v_permlane32_swap_b32_e32 v25, v57
	v_permlane32_swap_b32_e32 v26, v58
	v_permlane32_swap_b32_e32 v27, v59
	v_permlane32_swap_b32_e32 v28, v60
	v_permlane32_swap_b32_e32 v29, v61
	v_permlane32_swap_b32_e32 v30, v62
	v_permlane32_swap_b32_e32 v31, v63
	v_permlane32_swap_b32_e32 v32, v64
	v_permlane32_swap_b32_e32 v33, v65
	v_permlane32_swap_b32_e32 v34, v66
	v_permlane32_swap_b32_e32 v35, v67
	v_permlane32_swap_b32_e32 v36, v68
	v_permlane32_swap_b32_e32 v37, v69
	v_permlane32_swap_b32_e32 v38, v70
	v_permlane32_swap_b32_e32 v39, v71
	v_permlane32_swap_b32_e32 v40, v72
	v_permlane32_swap_b32_e32 v41, v73
	v_permlane32_swap_b32_e32 v42, v74
	v_permlane32_swap_b32_e32 v43, v75
	v_permlane32_swap_b32_e32 v44, v76
	v_permlane32_swap_b32_e32 v45, v77
	v_permlane32_swap_b32_e32 v46, v78
	v_permlane32_swap_b32_e32 v47, v79
	v_fmac_f32_e32 v16, v116, v120
	v_fmac_f32_e32 v32, v118, v121
	v_fmac_f32_dpp v16, v120, v122 quad_perm:[1,0,3,2] row_mask:0xf bank_mask:0xf
	v_fmac_f32_dpp v32, v121, v123 quad_perm:[1,0,3,2] row_mask:0xf bank_mask:0xf
	v_cvt_pk_bf16_f32 v148, v16, v32
	ds_write_b32 v151, v148
	v_fmac_f32_e32 v17, v116, v16
	v_fmac_f32_e32 v33, v118, v32
	v_fmac_f32_dpp v17, v16, v122 quad_perm:[1,0,3,2] row_mask:0xf bank_mask:0xf
	v_fmac_f32_dpp v33, v32, v123 quad_perm:[1,0,3,2] row_mask:0xf bank_mask:0xf
	v_cvt_pk_bf16_f32 v149, v17, v33
	ds_write_b32 v151, v149 offset:272
	v_fmac_f32_e32 v18, v116, v17
	v_fmac_f32_e32 v34, v118, v33
	v_fmac_f32_dpp v18, v17, v122 quad_perm:[1,0,3,2] row_mask:0xf bank_mask:0xf
	v_fmac_f32_dpp v34, v33, v123 quad_perm:[1,0,3,2] row_mask:0xf bank_mask:0xf
	v_cvt_pk_bf16_f32 v148, v18, v34
	ds_write_b32 v151, v148 offset:544
	v_fmac_f32_e32 v19, v116, v18
	v_fmac_f32_e32 v35, v118, v34
	v_fmac_f32_dpp v19, v18, v122 quad_perm:[1,0,3,2] row_mask:0xf bank_mask:0xf
	v_fmac_f32_dpp v35, v34, v123 quad_perm:[1,0,3,2] row_mask:0xf bank_mask:0xf
	v_cvt_pk_bf16_f32 v149, v19, v35
	ds_write_b32 v151, v149 offset:816
	v_fmac_f32_e32 v48, v116, v19
	v_fmac_f32_e32 v64, v118, v35
	v_fmac_f32_dpp v48, v19, v122 quad_perm:[1,0,3,2] row_mask:0xf bank_mask:0xf
	v_fmac_f32_dpp v64, v35, v123 quad_perm:[1,0,3,2] row_mask:0xf bank_mask:0xf
	v_cvt_pk_bf16_f32 v148, v48, v64
	ds_write_b32 v151, v148 offset:1088
	v_fmac_f32_e32 v49, v116, v48
	v_fmac_f32_e32 v65, v118, v64
	v_fmac_f32_dpp v49, v48, v122 quad_perm:[1,0,3,2] row_mask:0xf bank_mask:0xf
	v_fmac_f32_dpp v65, v64, v123 quad_perm:[1,0,3,2] row_mask:0xf bank_mask:0xf
	v_cvt_pk_bf16_f32 v149, v49, v65
	ds_write_b32 v151, v149 offset:1360
	v_fmac_f32_e32 v50, v116, v49
	v_fmac_f32_e32 v66, v118, v65
	v_fmac_f32_dpp v50, v49, v122 quad_perm:[1,0,3,2] row_mask:0xf bank_mask:0xf
	v_fmac_f32_dpp v66, v65, v123 quad_perm:[1,0,3,2] row_mask:0xf bank_mask:0xf
	v_cvt_pk_bf16_f32 v148, v50, v66
	ds_write_b32 v151, v148 offset:1632
	v_fmac_f32_e32 v51, v116, v50
	v_fmac_f32_e32 v67, v118, v66
	v_fmac_f32_dpp v51, v50, v122 quad_perm:[1,0,3,2] row_mask:0xf bank_mask:0xf
	v_fmac_f32_dpp v67, v66, v123 quad_perm:[1,0,3,2] row_mask:0xf bank_mask:0xf
	v_cvt_pk_bf16_f32 v149, v51, v67
	ds_write_b32 v151, v149 offset:1904
	v_fmac_f32_e32 v20, v116, v51
	v_fmac_f32_e32 v36, v118, v67
	v_fmac_f32_dpp v20, v51, v122 quad_perm:[1,0,3,2] row_mask:0xf bank_mask:0xf
	v_fmac_f32_dpp v36, v67, v123 quad_perm:[1,0,3,2] row_mask:0xf bank_mask:0xf
	v_cvt_pk_bf16_f32 v148, v20, v36
	ds_write_b32 v151, v148 offset:2176
	v_fmac_f32_e32 v21, v116, v20
	v_fmac_f32_e32 v37, v118, v36
	v_fmac_f32_dpp v21, v20, v122 quad_perm:[1,0,3,2] row_mask:0xf bank_mask:0xf
	v_fmac_f32_dpp v37, v36, v123 quad_perm:[1,0,3,2] row_mask:0xf bank_mask:0xf
	v_cvt_pk_bf16_f32 v149, v21, v37
	ds_write_b32 v151, v149 offset:2448
	v_fmac_f32_e32 v22, v116, v21
	v_fmac_f32_e32 v38, v118, v37
	v_fmac_f32_dpp v22, v21, v122 quad_perm:[1,0,3,2] row_mask:0xf bank_mask:0xf
	v_fmac_f32_dpp v38, v37, v123 quad_perm:[1,0,3,2] row_mask:0xf bank_mask:0xf
	v_cvt_pk_bf16_f32 v148, v22, v38
	ds_write_b32 v151, v148 offset:2720
	v_fmac_f32_e32 v23, v116, v22
	v_fmac_f32_e32 v39, v118, v38
	v_fmac_f32_dpp v23, v22, v122 quad_perm:[1,0,3,2] row_mask:0xf bank_mask:0xf
	v_fmac_f32_dpp v39, v38, v123 quad_perm:[1,0,3,2] row_mask:0xf bank_mask:0xf
	v_cvt_pk_bf16_f32 v149, v23, v39
	ds_write_b32 v151, v149 offset:2992
	v_fmac_f32_e32 v52, v116, v23
	v_fmac_f32_e32 v68, v118, v39
	v_fmac_f32_dpp v52, v23, v122 quad_perm:[1,0,3,2] row_mask:0xf bank_mask:0xf
	v_fmac_f32_dpp v68, v39, v123 quad_perm:[1,0,3,2] row_mask:0xf bank_mask:0xf
	v_cvt_pk_bf16_f32 v148, v52, v68
	ds_write_b32 v151, v148 offset:3264
	v_fmac_f32_e32 v53, v116, v52
	v_fmac_f32_e32 v69, v118, v68
	v_fmac_f32_dpp v53, v52, v122 quad_perm:[1,0,3,2] row_mask:0xf bank_mask:0xf
	v_fmac_f32_dpp v69, v68, v123 quad_perm:[1,0,3,2] row_mask:0xf bank_mask:0xf
	v_cvt_pk_bf16_f32 v149, v53, v69
	ds_write_b32 v151, v149 offset:3536
	v_fmac_f32_e32 v54, v116, v53
	v_fmac_f32_e32 v70, v118, v69
	v_fmac_f32_dpp v54, v53, v122 quad_perm:[1,0,3,2] row_mask:0xf bank_mask:0xf
	v_fmac_f32_dpp v70, v69, v123 quad_perm:[1,0,3,2] row_mask:0xf bank_mask:0xf
	v_cvt_pk_bf16_f32 v148, v54, v70
	ds_write_b32 v151, v148 offset:3808
	v_fmac_f32_e32 v55, v116, v54
	v_fmac_f32_e32 v71, v118, v70
	v_fmac_f32_dpp v55, v54, v122 quad_perm:[1,0,3,2] row_mask:0xf bank_mask:0xf
	v_fmac_f32_dpp v71, v70, v123 quad_perm:[1,0,3,2] row_mask:0xf bank_mask:0xf
	v_cvt_pk_bf16_f32 v149, v55, v71
	ds_write_b32 v151, v149 offset:4080
	v_fmac_f32_e32 v24, v116, v55
	v_fmac_f32_e32 v40, v118, v71
	v_fmac_f32_dpp v24, v55, v122 quad_perm:[1,0,3,2] row_mask:0xf bank_mask:0xf
	v_fmac_f32_dpp v40, v71, v123 quad_perm:[1,0,3,2] row_mask:0xf bank_mask:0xf
	v_cvt_pk_bf16_f32 v148, v24, v40
	ds_write_b32 v151, v148 offset:4352
	v_fmac_f32_e32 v25, v116, v24
	v_fmac_f32_e32 v41, v118, v40
	v_fmac_f32_dpp v25, v24, v122 quad_perm:[1,0,3,2] row_mask:0xf bank_mask:0xf
	v_fmac_f32_dpp v41, v40, v123 quad_perm:[1,0,3,2] row_mask:0xf bank_mask:0xf
	v_cvt_pk_bf16_f32 v149, v25, v41
	ds_write_b32 v151, v149 offset:4624
	v_fmac_f32_e32 v26, v116, v25
	v_fmac_f32_e32 v42, v118, v41
	v_fmac_f32_dpp v26, v25, v122 quad_perm:[1,0,3,2] row_mask:0xf bank_mask:0xf
	v_fmac_f32_dpp v42, v41, v123 quad_perm:[1,0,3,2] row_mask:0xf bank_mask:0xf
	v_cvt_pk_bf16_f32 v148, v26, v42
	ds_write_b32 v151, v148 offset:4896
	v_fmac_f32_e32 v27, v116, v26
	v_fmac_f32_e32 v43, v118, v42
	v_fmac_f32_dpp v27, v26, v122 quad_perm:[1,0,3,2] row_mask:0xf bank_mask:0xf
	v_fmac_f32_dpp v43, v42, v123 quad_perm:[1,0,3,2] row_mask:0xf bank_mask:0xf
	v_cvt_pk_bf16_f32 v149, v27, v43
	ds_write_b32 v151, v149 offset:5168
	v_fmac_f32_e32 v56, v116, v27
	v_fmac_f32_e32 v72, v118, v43
	v_fmac_f32_dpp v56, v27, v122 quad_perm:[1,0,3,2] row_mask:0xf bank_mask:0xf
	v_fmac_f32_dpp v72, v43, v123 quad_perm:[1,0,3,2] row_mask:0xf bank_mask:0xf
	v_cvt_pk_bf16_f32 v148, v56, v72
	ds_write_b32 v151, v148 offset:5440
	v_fmac_f32_e32 v57, v116, v56
	v_fmac_f32_e32 v73, v118, v72
	v_fmac_f32_dpp v57, v56, v122 quad_perm:[1,0,3,2] row_mask:0xf bank_mask:0xf
	v_fmac_f32_dpp v73, v72, v123 quad_perm:[1,0,3,2] row_mask:0xf bank_mask:0xf
	v_cvt_pk_bf16_f32 v149, v57, v73
	ds_write_b32 v151, v149 offset:5712
	v_fmac_f32_e32 v58, v116, v57
	v_fmac_f32_e32 v74, v118, v73
	v_fmac_f32_dpp v58, v57, v122 quad_perm:[1,0,3,2] row_mask:0xf bank_mask:0xf
	v_fmac_f32_dpp v74, v73, v123 quad_perm:[1,0,3,2] row_mask:0xf bank_mask:0xf
	v_cvt_pk_bf16_f32 v148, v58, v74
	ds_write_b32 v151, v148 offset:5984
	v_fmac_f32_e32 v59, v116, v58
	v_fmac_f32_e32 v75, v118, v74
	v_fmac_f32_dpp v59, v58, v122 quad_perm:[1,0,3,2] row_mask:0xf bank_mask:0xf
	v_fmac_f32_dpp v75, v74, v123 quad_perm:[1,0,3,2] row_mask:0xf bank_mask:0xf
	v_cvt_pk_bf16_f32 v149, v59, v75
	ds_write_b32 v151, v149 offset:6256
	v_fmac_f32_e32 v28, v116, v59
	v_fmac_f32_e32 v44, v118, v75
	v_fmac_f32_dpp v28, v59, v122 quad_perm:[1,0,3,2] row_mask:0xf bank_mask:0xf
	v_fmac_f32_dpp v44, v75, v123 quad_perm:[1,0,3,2] row_mask:0xf bank_mask:0xf
	v_cvt_pk_bf16_f32 v148, v28, v44
	ds_write_b32 v151, v148 offset:6528
	v_fmac_f32_e32 v29, v116, v28
	v_fmac_f32_e32 v45, v118, v44
	v_fmac_f32_dpp v29, v28, v122 quad_perm:[1,0,3,2] row_mask:0xf bank_mask:0xf
	v_fmac_f32_dpp v45, v44, v123 quad_perm:[1,0,3,2] row_mask:0xf bank_mask:0xf
	v_cvt_pk_bf16_f32 v149, v29, v45
	ds_write_b32 v151, v149 offset:6800
	v_fmac_f32_e32 v30, v116, v29
	v_fmac_f32_e32 v46, v118, v45
	v_fmac_f32_dpp v30, v29, v122 quad_perm:[1,0,3,2] row_mask:0xf bank_mask:0xf
	v_fmac_f32_dpp v46, v45, v123 quad_perm:[1,0,3,2] row_mask:0xf bank_mask:0xf
	v_cvt_pk_bf16_f32 v148, v30, v46
	ds_write_b32 v151, v148 offset:7072
	v_fmac_f32_e32 v31, v116, v30
	v_fmac_f32_e32 v47, v118, v46
	v_fmac_f32_dpp v31, v30, v122 quad_perm:[1,0,3,2] row_mask:0xf bank_mask:0xf
	v_fmac_f32_dpp v47, v46, v123 quad_perm:[1,0,3,2] row_mask:0xf bank_mask:0xf
	v_cvt_pk_bf16_f32 v149, v31, v47
	ds_write_b32 v151, v149 offset:7344
	v_fmac_f32_e32 v60, v116, v31
	v_fmac_f32_e32 v76, v118, v47
	v_fmac_f32_dpp v60, v31, v122 quad_perm:[1,0,3,2] row_mask:0xf bank_mask:0xf
	v_fmac_f32_dpp v76, v47, v123 quad_perm:[1,0,3,2] row_mask:0xf bank_mask:0xf
	v_cvt_pk_bf16_f32 v148, v60, v76
	ds_write_b32 v151, v148 offset:7616
	v_fmac_f32_e32 v61, v116, v60
	v_fmac_f32_e32 v77, v118, v76
	v_fmac_f32_dpp v61, v60, v122 quad_perm:[1,0,3,2] row_mask:0xf bank_mask:0xf
	v_fmac_f32_dpp v77, v76, v123 quad_perm:[1,0,3,2] row_mask:0xf bank_mask:0xf
	v_cvt_pk_bf16_f32 v149, v61, v77
	ds_write_b32 v151, v149 offset:7888
	v_fmac_f32_e32 v62, v116, v61
	v_fmac_f32_e32 v78, v118, v77
	v_fmac_f32_dpp v62, v61, v122 quad_perm:[1,0,3,2] row_mask:0xf bank_mask:0xf
	v_fmac_f32_dpp v78, v77, v123 quad_perm:[1,0,3,2] row_mask:0xf bank_mask:0xf
	v_cvt_pk_bf16_f32 v148, v62, v78
	ds_write_b32 v151, v148 offset:8160
	v_fmac_f32_e32 v63, v116, v62
	v_fmac_f32_e32 v79, v118, v78
	v_fmac_f32_dpp v63, v62, v122 quad_perm:[1,0,3,2] row_mask:0xf bank_mask:0xf
	v_fmac_f32_dpp v79, v78, v123 quad_perm:[1,0,3,2] row_mask:0xf bank_mask:0xf
	v_cvt_pk_bf16_f32 v149, v63, v79
	ds_write_b32 v151, v149 offset:8432
	v_mov_b32_e32 v120, v63
	v_mov_b32_e32 v121, v79
	ds_read_b128 v[124:127], v152
	ds_read_b128 v[128:131], v152 offset:64
	ds_read_b128 v[132:135], v152 offset:128
	ds_read_b128 v[136:139], v152 offset:192
	ds_read_b64 v[160:161], v163
	s_waitcnt lgkmcnt(4)
	v_mfma_f32_16x16x32_bf16 v[140:143], v[100:103], v[124:127], 0
	s_waitcnt lgkmcnt(3)
	v_mfma_f32_16x16x32_bf16 v[140:143], v[104:107], v[128:131], v[140:143]
	s_waitcnt lgkmcnt(2)
	v_mfma_f32_16x16x32_bf16 v[140:143], v[108:111], v[132:135], v[140:143]
	s_waitcnt lgkmcnt(1)
	v_mfma_f32_16x16x32_bf16 v[140:143], v[112:115], v[136:139], v[140:143]
	s_nop 9
	s_waitcnt vmcnt(7) lgkmcnt(0)
	v_add_f32_e32 v182, v172, v140
	v_add_f32_e32 v183, v173, v141
	v_add_f32_e32 v184, v174, v142
	v_add_f32_e32 v185, v175, v143
	v_lshlrev_b32_e32 v186, 16, v160
	v_and_b32_e32 v187, 0xffff0000, v160
	v_lshlrev_b32_e32 v188, 16, v161
	v_and_b32_e32 v189, 0xffff0000, v161
	v_fmac_f32_e32 v182, v164, v186
	v_fmac_f32_e32 v183, v165, v187
	v_fmac_f32_e32 v184, v166, v188
	v_fmac_f32_e32 v185, v167, v189
	v_mul_f32_e32 v186, 0x3d372713, v182
	v_mul_f32_e32 v187, 0x3d372713, v183
	v_mul_f32_e32 v188, 0x3d372713, v184
	v_mul_f32_e32 v189, 0x3d372713, v185
	v_mul_f32_e32 v186, v182, v186
	v_mul_f32_e32 v187, v183, v187
	v_mul_f32_e32 v188, v184, v188
	v_mul_f32_e32 v189, v185, v189
	v_fma_f32 v186, v182, v186, v182
	v_fma_f32 v187, v183, v187, v183
	v_fma_f32 v188, v184, v188, v184
	v_fma_f32 v189, v185, v189, v185
	v_mul_f32_e32 v186, 0xbfcc422a, v186
	v_mul_f32_e32 v187, 0xbfcc422a, v187
	v_mul_f32_e32 v188, 0xbfcc422a, v188
	v_mul_f32_e32 v189, 0xbfcc422a, v189
	v_mul_f32_e32 v186, 0x3fb8aa3b, v186
	v_mul_f32_e32 v187, 0x3fb8aa3b, v187
	v_mul_f32_e32 v188, 0x3fb8aa3b, v188
	v_mul_f32_e32 v189, 0x3fb8aa3b, v189
	v_exp_f32_e32 v186, v186
	v_exp_f32_e32 v187, v187
	v_exp_f32_e32 v188, v188
	v_exp_f32_e32 v189, v189
	v_add_f32_e32 v186, 1.0, v186
	v_add_f32_e32 v187, 1.0, v187
	v_add_f32_e32 v188, 1.0, v188
	v_add_f32_e32 v189, 1.0, v189
	v_rcp_f32_e32 v186, v186
	v_rcp_f32_e32 v187, v187
	v_rcp_f32_e32 v188, v188
	v_rcp_f32_e32 v189, v189
	v_mul_f32_e32 v182, v182, v186
	v_mul_f32_e32 v183, v183, v187
	v_mul_f32_e32 v184, v184, v188
	v_mul_f32_e32 v185, v185, v189
	v_cvt_pk_bf16_f32 v148, v182, v183
	v_cvt_pk_bf16_f32 v149, v184, v185
	global_store_dwordx2 v156, v[148:149], s[12:13]
	ds_read_b128 v[124:127], v152 offset:4352
	ds_read_b128 v[128:131], v152 offset:4416
	ds_read_b128 v[132:135], v152 offset:4480
	ds_read_b128 v[136:139], v152 offset:4544
	ds_read_b64 v[160:161], v163 offset:512
	s_waitcnt lgkmcnt(4)
	v_mfma_f32_16x16x32_bf16 v[140:143], v[100:103], v[124:127], 0
	s_waitcnt lgkmcnt(3)
	v_mfma_f32_16x16x32_bf16 v[140:143], v[104:107], v[128:131], v[140:143]
	s_waitcnt lgkmcnt(2)
	v_mfma_f32_16x16x32_bf16 v[140:143], v[108:111], v[132:135], v[140:143]
	s_waitcnt lgkmcnt(1)
	v_mfma_f32_16x16x32_bf16 v[140:143], v[112:115], v[136:139], v[140:143]
	s_nop 9
	s_waitcnt vmcnt(7) lgkmcnt(0)
	v_add_f32_e32 v182, v176, v140
	v_add_f32_e32 v183, v177, v141
	v_add_f32_e32 v184, v178, v142
	v_add_f32_e32 v185, v179, v143
	v_lshlrev_b32_e32 v186, 16, v160
	v_and_b32_e32 v187, 0xffff0000, v160
	v_lshlrev_b32_e32 v188, 16, v161
	v_and_b32_e32 v189, 0xffff0000, v161
	v_fmac_f32_e32 v182, v164, v186
	v_fmac_f32_e32 v183, v165, v187
	v_fmac_f32_e32 v184, v166, v188
	v_fmac_f32_e32 v185, v167, v189
	v_mul_f32_e32 v186, 0x3d372713, v182
	v_mul_f32_e32 v187, 0x3d372713, v183
	v_mul_f32_e32 v188, 0x3d372713, v184
	v_mul_f32_e32 v189, 0x3d372713, v185
	v_mul_f32_e32 v186, v182, v186
	v_mul_f32_e32 v187, v183, v187
	v_mul_f32_e32 v188, v184, v188
	v_mul_f32_e32 v189, v185, v189
	v_fma_f32 v186, v182, v186, v182
	v_fma_f32 v187, v183, v187, v183
	v_fma_f32 v188, v184, v188, v184
	v_fma_f32 v189, v185, v189, v185
	v_mul_f32_e32 v186, 0xbfcc422a, v186
	v_mul_f32_e32 v187, 0xbfcc422a, v187
	v_mul_f32_e32 v188, 0xbfcc422a, v188
	v_mul_f32_e32 v189, 0xbfcc422a, v189
	v_mul_f32_e32 v186, 0x3fb8aa3b, v186
	v_mul_f32_e32 v187, 0x3fb8aa3b, v187
	v_mul_f32_e32 v188, 0x3fb8aa3b, v188
	v_mul_f32_e32 v189, 0x3fb8aa3b, v189
	v_exp_f32_e32 v186, v186
	v_exp_f32_e32 v187, v187
	v_exp_f32_e32 v188, v188
	v_exp_f32_e32 v189, v189
	v_add_f32_e32 v186, 1.0, v186
	v_add_f32_e32 v187, 1.0, v187
	v_add_f32_e32 v188, 1.0, v188
	v_add_f32_e32 v189, 1.0, v189
	v_rcp_f32_e32 v186, v186
	v_rcp_f32_e32 v187, v187
	v_rcp_f32_e32 v188, v188
	v_rcp_f32_e32 v189, v189
	v_mul_f32_e32 v182, v182, v186
	v_mul_f32_e32 v183, v183, v187
	v_mul_f32_e32 v184, v184, v188
	v_mul_f32_e32 v185, v185, v189
	v_cvt_pk_bf16_f32 v148, v182, v183
	v_cvt_pk_bf16_f32 v149, v184, v185
	global_store_dwordx2 v159, v[148:149], s[12:13]
	s_add_u32 s12, s12, 65536
	s_addc_u32 s13, s13, 0
	s_add_u32 s14, s14, 2
	s_cmp_lt_u32 s14, 32
	s_cbranch_scc1 .Lssm_tileB_d0m0
	s_waitcnt vmcnt(0) lgkmcnt(0)
	s_branch .Lssm_lat_join
.Lssm_lat_bwd:
	s_add_u32 s28, s24, 64
	s_lshl_b32 s29, s28, 13
	s_add_u32 s29, s29, 0x200000
	s_add_u32 s10, s62, s29
	s_addc_u32 s11, s63, 0
	global_load_dwordx4 v[84:87], v177, s[10:11]
	global_load_dwordx4 v[88:91], v177, s[10:11] offset:2048
	s_add_u32 s12, s10, 0x1000
	s_addc_u32 s13, s11, 0
	global_load_dwordx4 v[92:95], v177, s[12:13]
	global_load_dwordx4 v[96:99], v177, s[12:13] offset:2048
	s_lshl_b32 s29, s28, 12
	s_add_u32 s29, s29, 0x300000
	s_add_u32 s16, s62, s29
	s_addc_u32 s17, s63, 0
	global_load_dwordx2 v[2:3], v178, s[16:17]
	global_load_dwordx2 v[4:5], v178, s[16:17] offset:1024
	global_load_dwordx2 v[6:7], v178, s[16:17] offset:512
	global_load_dwordx2 v[8:9], v178, s[16:17] offset:1536
	global_load_dwordx2 v[10:11], v178, s[16:17] offset:2048
	global_load_dwordx2 v[12:13], v178, s[16:17] offset:3072
	global_load_dwordx2 v[14:15], v178, s[16:17] offset:2560
	global_load_dwordx2 v[16:17], v178, s[16:17] offset:3584
	s_lshl_b32 s29, s28, 9
	s_add_u32 s29, s29, 0x100000
	s_add_u32 s18, s62, s29
	s_addc_u32 s19, s63, 0
	global_load_dwordx2 v[116:117], v179, s[18:19]
	global_load_dwordx2 v[118:119], v179, s[18:19] offset:128
	s_lshl_b32 s30, s23, 1
	s_add_u32 s30, s30, 1
	s_lshl_b32 s30, s30, 15
	s_lshl_b32 s31, s24, 8
	s_add_u32 s30, s30, s31
	v_readlane_b32 s34, v254, 10
	v_readlane_b32 s35, v254, 11
	s_nop 3
	s_add_u32 s34, s34, s30
	s_addc_u32 s35, s35, 0
	global_load_dword v120, v180, s[34:35]
	global_load_dword v121, v180, s[34:35] offset:64
	v_readlane_b32 s34, v254, 28
	v_readlane_b32 s35, v254, 29
	s_nop 3
	s_lshl_b32 s31, s24, 6
	s_add_u32 s34, s34, s31
	s_addc_u32 s35, s35, 0
	global_load_dwordx4 v[164:167], v181, s[34:35]
	s_lshl_b32 s31, s25, 5
	s_lshl_b32 s29, s24, 19
	s_add_u32 s31, s31, s29
	s_add_u32 s31, s31, 0x16800000
	s_add_u32 s4, s62, s31
	s_addc_u32 s5, s63, 0
	s_lshl_b32 s31, s22, 1
	s_add_u32 s31, s31, 1
	s_lshl_b32 s31, s31, 15
	s_add_u32 s31, s31, 0x4800000
	s_add_u32 s6, s62, s31
	s_addc_u32 s7, s63, 0
	s_add_u32 s34, s4, 31744
	s_addc_u32 s35, s5, 0
	global_load_dwordx4 v[80:83], v150, s[34:35]
	s_mov_b64 s[10:11], s[34:35]
	s_sub_u32 s10, s10, 1024
	s_subb_u32 s11, s11, 0
	global_load_dwordx4 v[144:147], v150, s[10:11]
	s_mov_b64 s[34:35], s[10:11]
	s_sub_u32 s10, s10, 1024
	s_subb_u32 s11, s11, 0
	s_add_u32 s12, s6, 30720
	s_addc_u32 s13, s7, 0
	s_mov_b32 s14, 0
	s_mov_b32 s40, 0xffff0000
	s_waitcnt vmcnt(0)
	v_and_b32_e32 v182, 0xffff, v2
	v_lshrrev_b32_e32 v183, 16, v2
	v_and_b32_e32 v184, 0xffff, v3
	v_lshrrev_b32_e32 v185, 16, v3
	v_lshl_or_b32 v100, v4, 16, v182
	v_and_or_b32 v101, v4, s40, v183
	v_lshl_or_b32 v102, v5, 16, v184
	v_and_or_b32 v103, v5, s40, v185
	v_and_b32_e32 v182, 0xffff, v6
	v_lshrrev_b32_e32 v183, 16, v6
	v_and_b32_e32 v184, 0xffff, v7
	v_lshrrev_b32_e32 v185, 16, v7
	v_lshl_or_b32 v104, v8, 16, v182
	v_and_or_b32 v105, v8, s40, v183
	v_lshl_or_b32 v106, v9, 16, v184
	v_and_or_b32 v107, v9, s40, v185
	v_and_b32_e32 v182, 0xffff, v10
	v_lshrrev_b32_e32 v183, 16, v10
	v_and_b32_e32 v184, 0xffff, v11
	v_lshrrev_b32_e32 v185, 16, v11
	v_lshl_or_b32 v108, v12, 16, v182
	v_and_or_b32 v109, v12, s40, v183
	v_lshl_or_b32 v110, v13, 16, v184
	v_and_or_b32 v111, v13, s40, v185
	v_and_b32_e32 v182, 0xffff, v14
	v_lshrrev_b32_e32 v183, 16, v14
	v_and_b32_e32 v184, 0xffff, v15
	v_lshrrev_b32_e32 v185, 16, v15
	v_lshl_or_b32 v112, v16, 16, v182
	v_and_or_b32 v113, v16, s40, v183
	v_lshl_or_b32 v114, v17, 16, v184
	v_and_or_b32 v115, v17, s40, v185
	v_cmp_eq_u32_e32 vcc, 1, v174
	v_xor_b32_e32 v182, 0x80000000, v117
	v_xor_b32_e32 v183, 0x80000000, v119
	s_nop 1
	v_cndmask_b32_e32 v122, v182, v117, vcc
	v_cndmask_b32_e32 v123, v183, v119, vcc
.Lssm_tileA_d1m0:
	s_waitcnt vmcnt(5)
	v_mfma_f32_32x32x16_bf16 v[16:31], v[80:83], v[84:87], 0
	v_mfma_f32_32x32x16_bf16 v[32:47], v[80:83], v[88:91], 0
	v_mfma_f32_32x32x16_bf16 v[48:63], v[80:83], v[92:95], 0
	v_mfma_f32_32x32x16_bf16 v[64:79], v[80:83], v[96:99], 0
	s_nop 11
	global_load_dwordx4 v[80:83], v150, s[10:11]
	s_sub_u32 s34, s34, 1024
	s_subb_u32 s35, s35, 0
	s_sub_u32 s10, s10, 1024
	s_subb_u32 s11, s11, 0
	v_permlane32_swap_b32_e32 v16, v48
	v_permlane32_swap_b32_e32 v17, v49
	v_permlane32_swap_b32_e32 v18, v50
	v_permlane32_swap_b32_e32 v19, v51
	v_permlane32_swap_b32_e32 v20, v52
	v_permlane32_swap_b32_e32 v21, v53
	v_permlane32_swap_b32_e32 v22, v54
	v_permlane32_swap_b32_e32 v23, v55
	v_permlane32_swap_b32_e32 v24, v56
	v_permlane32_swap_b32_e32 v25, v57
	v_permlane32_swap_b32_e32 v26, v58
	v_permlane32_swap_b32_e32 v27, v59
	v_permlane32_swap_b32_e32 v28, v60
	v_permlane32_swap_b32_e32 v29, v61
	v_permlane32_swap_b32_e32 v30, v62
	v_permlane32_swap_b32_e32 v31, v63
	v_permlane32_swap_b32_e32 v32, v64
	v_permlane32_swap_b32_e32 v33, v65
	v_permlane32_swap_b32_e32 v34, v66
	v_permlane32_swap_b32_e32 v35, v67
	v_permlane32_swap_b32_e32 v36, v68
	v_permlane32_swap_b32_e32 v37, v69
	v_permlane32_swap_b32_e32 v38, v70
	v_permlane32_swap_b32_e32 v39, v71
	v_permlane32_swap_b32_e32 v40, v72
	v_permlane32_swap_b32_e32 v41, v73
	v_permlane32_swap_b32_e32 v42, v74
	v_permlane32_swap_b32_e32 v43, v75
	v_permlane32_swap_b32_e32 v44, v76
	v_permlane32_swap_b32_e32 v45, v77
	v_permlane32_swap_b32_e32 v46, v78
	v_permlane32_swap_b32_e32 v47, v79
	v_fmac_f32_e32 v63, v116, v120
	v_fmac_f32_e32 v79, v118, v121
	v_fmac_f32_dpp v63, v120, v122 quad_perm:[1,0,3,2] row_mask:0xf bank_mask:0xf
	v_fmac_f32_dpp v79, v121, v123 quad_perm:[1,0,3,2] row_mask:0xf bank_mask:0xf
	v_cvt_pk_bf16_f32 v148, v63, v79
	ds_write_b32 v151, v148 offset:8432
	v_fmac_f32_e32 v62, v116, v63
	v_fmac_f32_e32 v78, v118, v79
	v_fmac_f32_dpp v62, v63, v122 quad_perm:[1,0,3,2] row_mask:0xf bank_mask:0xf
	v_fmac_f32_dpp v78, v79, v123 quad_perm:[1,0,3,2] row_mask:0xf bank_mask:0xf
	v_cvt_pk_bf16_f32 v149, v62, v78
	ds_write_b32 v151, v149 offset:8160
	v_fmac_f32_e32 v61, v116, v62
	v_fmac_f32_e32 v77, v118, v78
	v_fmac_f32_dpp v61, v62, v122 quad_perm:[1,0,3,2] row_mask:0xf bank_mask:0xf
	v_fmac_f32_dpp v77, v78, v123 quad_perm:[1,0,3,2] row_mask:0xf bank_mask:0xf
	v_cvt_pk_bf16_f32 v148, v61, v77
	ds_write_b32 v151, v148 offset:7888
	v_fmac_f32_e32 v60, v116, v61
	v_fmac_f32_e32 v76, v118, v77
	v_fmac_f32_dpp v60, v61, v122 quad_perm:[1,0,3,2] row_mask:0xf bank_mask:0xf
	v_fmac_f32_dpp v76, v77, v123 quad_perm:[1,0,3,2] row_mask:0xf bank_mask:0xf
	v_cvt_pk_bf16_f32 v149, v60, v76
	ds_write_b32 v151, v149 offset:7616
	v_fmac_f32_e32 v31, v116, v60
	v_fmac_f32_e32 v47, v118, v76
	v_fmac_f32_dpp v31, v60, v122 quad_perm:[1,0,3,2] row_mask:0xf bank_mask:0xf
	v_fmac_f32_dpp v47, v76, v123 quad_perm:[1,0,3,2] row_mask:0xf bank_mask:0xf
	v_cvt_pk_bf16_f32 v148, v31, v47
	ds_write_b32 v151, v148 offset:7344
	v_fmac_f32_e32 v30, v116, v31
	v_fmac_f32_e32 v46, v118, v47
	v_fmac_f32_dpp v30, v31, v122 quad_perm:[1,0,3,2] row_mask:0xf bank_mask:0xf
	v_fmac_f32_dpp v46, v47, v123 quad_perm:[1,0,3,2] row_mask:0xf bank_mask:0xf
	v_cvt_pk_bf16_f32 v149, v30, v46
	ds_write_b32 v151, v149 offset:7072
	v_fmac_f32_e32 v29, v116, v30
	v_fmac_f32_e32 v45, v118, v46
	v_fmac_f32_dpp v29, v30, v122 quad_perm:[1,0,3,2] row_mask:0xf bank_mask:0xf
	v_fmac_f32_dpp v45, v46, v123 quad_perm:[1,0,3,2] row_mask:0xf bank_mask:0xf
	v_cvt_pk_bf16_f32 v148, v29, v45
	ds_write_b32 v151, v148 offset:6800
	v_fmac_f32_e32 v28, v116, v29
	v_fmac_f32_e32 v44, v118, v45
	v_fmac_f32_dpp v28, v29, v122 quad_perm:[1,0,3,2] row_mask:0xf bank_mask:0xf
	v_fmac_f32_dpp v44, v45, v123 quad_perm:[1,0,3,2] row_mask:0xf bank_mask:0xf
	v_cvt_pk_bf16_f32 v149, v28, v44
	ds_write_b32 v151, v149 offset:6528
	v_fmac_f32_e32 v59, v116, v28
	v_fmac_f32_e32 v75, v118, v44
	v_fmac_f32_dpp v59, v28, v122 quad_perm:[1,0,3,2] row_mask:0xf bank_mask:0xf
	v_fmac_f32_dpp v75, v44, v123 quad_perm:[1,0,3,2] row_mask:0xf bank_mask:0xf
	v_cvt_pk_bf16_f32 v148, v59, v75
	ds_write_b32 v151, v148 offset:6256
	v_fmac_f32_e32 v58, v116, v59
	v_fmac_f32_e32 v74, v118, v75
	v_fmac_f32_dpp v58, v59, v122 quad_perm:[1,0,3,2] row_mask:0xf bank_mask:0xf
	v_fmac_f32_dpp v74, v75, v123 quad_perm:[1,0,3,2] row_mask:0xf bank_mask:0xf
	v_cvt_pk_bf16_f32 v149, v58, v74
	ds_write_b32 v151, v149 offset:5984
	v_fmac_f32_e32 v57, v116, v58
	v_fmac_f32_e32 v73, v118, v74
	v_fmac_f32_dpp v57, v58, v122 quad_perm:[1,0,3,2] row_mask:0xf bank_mask:0xf
	v_fmac_f32_dpp v73, v74, v123 quad_perm:[1,0,3,2] row_mask:0xf bank_mask:0xf
	v_cvt_pk_bf16_f32 v148, v57, v73
	ds_write_b32 v151, v148 offset:5712
	v_fmac_f32_e32 v56, v116, v57
	v_fmac_f32_e32 v72, v118, v73
	v_fmac_f32_dpp v56, v57, v122 quad_perm:[1,0,3,2] row_mask:0xf bank_mask:0xf
	v_fmac_f32_dpp v72, v73, v123 quad_perm:[1,0,3,2] row_mask:0xf bank_mask:0xf
	v_cvt_pk_bf16_f32 v149, v56, v72
	ds_write_b32 v151, v149 offset:5440
	v_fmac_f32_e32 v27, v116, v56
	v_fmac_f32_e32 v43, v118, v72
	v_fmac_f32_dpp v27, v56, v122 quad_perm:[1,0,3,2] row_mask:0xf bank_mask:0xf
	v_fmac_f32_dpp v43, v72, v123 quad_perm:[1,0,3,2] row_mask:0xf bank_mask:0xf
	v_cvt_pk_bf16_f32 v148, v27, v43
	ds_write_b32 v151, v148 offset:5168
	v_fmac_f32_e32 v26, v116, v27
	v_fmac_f32_e32 v42, v118, v43
	v_fmac_f32_dpp v26, v27, v122 quad_perm:[1,0,3,2] row_mask:0xf bank_mask:0xf
	v_fmac_f32_dpp v42, v43, v123 quad_perm:[1,0,3,2] row_mask:0xf bank_mask:0xf
	v_cvt_pk_bf16_f32 v149, v26, v42
	ds_write_b32 v151, v149 offset:4896
	v_fmac_f32_e32 v25, v116, v26
	v_fmac_f32_e32 v41, v118, v42
	v_fmac_f32_dpp v25, v26, v122 quad_perm:[1,0,3,2] row_mask:0xf bank_mask:0xf
	v_fmac_f32_dpp v41, v42, v123 quad_perm:[1,0,3,2] row_mask:0xf bank_mask:0xf
	v_cvt_pk_bf16_f32 v148, v25, v41
	ds_write_b32 v151, v148 offset:4624
	v_fmac_f32_e32 v24, v116, v25
	v_fmac_f32_e32 v40, v118, v41
	v_fmac_f32_dpp v24, v25, v122 quad_perm:[1,0,3,2] row_mask:0xf bank_mask:0xf
	v_fmac_f32_dpp v40, v41, v123 quad_perm:[1,0,3,2] row_mask:0xf bank_mask:0xf
	v_cvt_pk_bf16_f32 v149, v24, v40
	ds_write_b32 v151, v149 offset:4352
	v_fmac_f32_e32 v55, v116, v24
	v_fmac_f32_e32 v71, v118, v40
	v_fmac_f32_dpp v55, v24, v122 quad_perm:[1,0,3,2] row_mask:0xf bank_mask:0xf
	v_fmac_f32_dpp v71, v40, v123 quad_perm:[1,0,3,2] row_mask:0xf bank_mask:0xf
	v_cvt_pk_bf16_f32 v148, v55, v71
	ds_write_b32 v151, v148 offset:4080
	v_fmac_f32_e32 v54, v116, v55
	v_fmac_f32_e32 v70, v118, v71
	v_fmac_f32_dpp v54, v55, v122 quad_perm:[1,0,3,2] row_mask:0xf bank_mask:0xf
	v_fmac_f32_dpp v70, v71, v123 quad_perm:[1,0,3,2] row_mask:0xf bank_mask:0xf
	v_cvt_pk_bf16_f32 v149, v54, v70
	ds_write_b32 v151, v149 offset:3808
	v_fmac_f32_e32 v53, v116, v54
	v_fmac_f32_e32 v69, v118, v70
	v_fmac_f32_dpp v53, v54, v122 quad_perm:[1,0,3,2] row_mask:0xf bank_mask:0xf
	v_fmac_f32_dpp v69, v70, v123 quad_perm:[1,0,3,2] row_mask:0xf bank_mask:0xf
	v_cvt_pk_bf16_f32 v148, v53, v69
	ds_write_b32 v151, v148 offset:3536
	v_fmac_f32_e32 v52, v116, v53
	v_fmac_f32_e32 v68, v118, v69
	v_fmac_f32_dpp v52, v53, v122 quad_perm:[1,0,3,2] row_mask:0xf bank_mask:0xf
	v_fmac_f32_dpp v68, v69, v123 quad_perm:[1,0,3,2] row_mask:0xf bank_mask:0xf
	v_cvt_pk_bf16_f32 v149, v52, v68
	ds_write_b32 v151, v149 offset:3264
	v_fmac_f32_e32 v23, v116, v52
	v_fmac_f32_e32 v39, v118, v68
	v_fmac_f32_dpp v23, v52, v122 quad_perm:[1,0,3,2] row_mask:0xf bank_mask:0xf
	v_fmac_f32_dpp v39, v68, v123 quad_perm:[1,0,3,2] row_mask:0xf bank_mask:0xf
	v_cvt_pk_bf16_f32 v148, v23, v39
	ds_write_b32 v151, v148 offset:2992
	v_fmac_f32_e32 v22, v116, v23
	v_fmac_f32_e32 v38, v118, v39
	v_fmac_f32_dpp v22, v23, v122 quad_perm:[1,0,3,2] row_mask:0xf bank_mask:0xf
	v_fmac_f32_dpp v38, v39, v123 quad_perm:[1,0,3,2] row_mask:0xf bank_mask:0xf
	v_cvt_pk_bf16_f32 v149, v22, v38
	ds_write_b32 v151, v149 offset:2720
	v_fmac_f32_e32 v21, v116, v22
	v_fmac_f32_e32 v37, v118, v38
	v_fmac_f32_dpp v21, v22, v122 quad_perm:[1,0,3,2] row_mask:0xf bank_mask:0xf
	v_fmac_f32_dpp v37, v38, v123 quad_perm:[1,0,3,2] row_mask:0xf bank_mask:0xf
	v_cvt_pk_bf16_f32 v148, v21, v37
	ds_write_b32 v151, v148 offset:2448
	v_fmac_f32_e32 v20, v116, v21
	v_fmac_f32_e32 v36, v118, v37
	v_fmac_f32_dpp v20, v21, v122 quad_perm:[1,0,3,2] row_mask:0xf bank_mask:0xf
	v_fmac_f32_dpp v36, v37, v123 quad_perm:[1,0,3,2] row_mask:0xf bank_mask:0xf
	v_cvt_pk_bf16_f32 v149, v20, v36
	ds_write_b32 v151, v149 offset:2176
	v_fmac_f32_e32 v51, v116, v20
	v_fmac_f32_e32 v67, v118, v36
	v_fmac_f32_dpp v51, v20, v122 quad_perm:[1,0,3,2] row_mask:0xf bank_mask:0xf
	v_fmac_f32_dpp v67, v36, v123 quad_perm:[1,0,3,2] row_mask:0xf bank_mask:0xf
	v_cvt_pk_bf16_f32 v148, v51, v67
	ds_write_b32 v151, v148 offset:1904
	v_fmac_f32_e32 v50, v116, v51
	v_fmac_f32_e32 v66, v118, v67
	v_fmac_f32_dpp v50, v51, v122 quad_perm:[1,0,3,2] row_mask:0xf bank_mask:0xf
	v_fmac_f32_dpp v66, v67, v123 quad_perm:[1,0,3,2] row_mask:0xf bank_mask:0xf
	v_cvt_pk_bf16_f32 v149, v50, v66
	ds_write_b32 v151, v149 offset:1632
	v_fmac_f32_e32 v49, v116, v50
	v_fmac_f32_e32 v65, v118, v66
	v_fmac_f32_dpp v49, v50, v122 quad_perm:[1,0,3,2] row_mask:0xf bank_mask:0xf
	v_fmac_f32_dpp v65, v66, v123 quad_perm:[1,0,3,2] row_mask:0xf bank_mask:0xf
	v_cvt_pk_bf16_f32 v148, v49, v65
	ds_write_b32 v151, v148 offset:1360
	v_fmac_f32_e32 v48, v116, v49
	v_fmac_f32_e32 v64, v118, v65
	v_fmac_f32_dpp v48, v49, v122 quad_perm:[1,0,3,2] row_mask:0xf bank_mask:0xf
	v_fmac_f32_dpp v64, v65, v123 quad_perm:[1,0,3,2] row_mask:0xf bank_mask:0xf
	v_cvt_pk_bf16_f32 v149, v48, v64
	ds_write_b32 v151, v149 offset:1088
	v_fmac_f32_e32 v19, v116, v48
	v_fmac_f32_e32 v35, v118, v64
	v_fmac_f32_dpp v19, v48, v122 quad_perm:[1,0,3,2] row_mask:0xf bank_mask:0xf
	v_fmac_f32_dpp v35, v64, v123 quad_perm:[1,0,3,2] row_mask:0xf bank_mask:0xf
	v_cvt_pk_bf16_f32 v148, v19, v35
	ds_write_b32 v151, v148 offset:816
	v_fmac_f32_e32 v18, v116, v19
	v_fmac_f32_e32 v34, v118, v35
	v_fmac_f32_dpp v18, v19, v122 quad_perm:[1,0,3,2] row_mask:0xf bank_mask:0xf
	v_fmac_f32_dpp v34, v35, v123 quad_perm:[1,0,3,2] row_mask:0xf bank_mask:0xf
	v_cvt_pk_bf16_f32 v149, v18, v34
	ds_write_b32 v151, v149 offset:544
	v_fmac_f32_e32 v17, v116, v18
	v_fmac_f32_e32 v33, v118, v34
	v_fmac_f32_dpp v17, v18, v122 quad_perm:[1,0,3,2] row_mask:0xf bank_mask:0xf
	v_fmac_f32_dpp v33, v34, v123 quad_perm:[1,0,3,2] row_mask:0xf bank_mask:0xf
	v_cvt_pk_bf16_f32 v148, v17, v33
	ds_write_b32 v151, v148 offset:272
	v_fmac_f32_e32 v16, v116, v17
	v_fmac_f32_e32 v32, v118, v33
	v_fmac_f32_dpp v16, v17, v122 quad_perm:[1,0,3,2] row_mask:0xf bank_mask:0xf
	v_fmac_f32_dpp v32, v33, v123 quad_perm:[1,0,3,2] row_mask:0xf bank_mask:0xf
	v_cvt_pk_bf16_f32 v149, v16, v32
	ds_write_b32 v151, v149
	v_mov_b32_e32 v120, v16
	v_mov_b32_e32 v121, v32
	ds_read_b128 v[124:127], v152
	ds_read_b128 v[128:131], v152 offset:64
	ds_read_b128 v[132:135], v152 offset:128
	ds_read_b128 v[136:139], v152 offset:192
	s_waitcnt lgkmcnt(3)
	v_mfma_f32_16x16x32_bf16 v[140:143], v[100:103], v[124:127], 0
	s_waitcnt lgkmcnt(2)
	v_mfma_f32_16x16x32_bf16 v[140:143], v[104:107], v[128:131], v[140:143]
	s_waitcnt lgkmcnt(1)
	v_mfma_f32_16x16x32_bf16 v[140:143], v[108:111], v[132:135], v[140:143]
	s_waitcnt lgkmcnt(0)
	v_mfma_f32_16x16x32_bf16 v[140:143], v[112:115], v[136:139], v[140:143]
	s_nop 9
	global_store_dwordx4 v153, v[140:143], s[12:13]
	s_nop 1
	ds_read_b128 v[124:127], v152 offset:4352
	ds_read_b128 v[128:131], v152 offset:4416
	ds_read_b128 v[132:135], v152 offset:4480
	ds_read_b128 v[136:139], v152 offset:4544
	s_waitcnt lgkmcnt(3)
	v_mfma_f32_16x16x32_bf16 v[140:143], v[100:103], v[124:127], 0
	s_waitcnt lgkmcnt(2)
	v_mfma_f32_16x16x32_bf16 v[140:143], v[104:107], v[128:131], v[140:143]
	s_waitcnt lgkmcnt(1)
	v_mfma_f32_16x16x32_bf16 v[140:143], v[108:111], v[132:135], v[140:143]
	s_waitcnt lgkmcnt(0)
	v_mfma_f32_16x16x32_bf16 v[140:143], v[112:115], v[136:139], v[140:143]
	s_nop 9
	global_store_dwordx4 v157, v[140:143], s[12:13]
	s_nop 1
	s_sub_u32 s12, s12, 2048
	s_subb_u32 s13, s13, 0
	s_waitcnt vmcnt(5)
	v_mfma_f32_32x32x16_bf16 v[16:31], v[144:147], v[84:87], 0
	v_mfma_f32_32x32x16_bf16 v[32:47], v[144:147], v[88:91], 0
	v_mfma_f32_32x32x16_bf16 v[48:63], v[144:147], v[92:95], 0
	v_mfma_f32_32x32x16_bf16 v[64:79], v[144:147], v[96:99], 0
	s_nop 11
	global_load_dwordx4 v[144:147], v150, s[10:11]
	s_sub_u32 s34, s34, 1024
	s_subb_u32 s35, s35, 0
	s_sub_u32 s10, s10, 1024
	s_subb_u32 s11, s11, 0
	v_permlane32_swap_b32_e32 v16, v48
	v_permlane32_swap_b32_e32 v17, v49
	v_permlane32_swap_b32_e32 v18, v50
	v_permlane32_swap_b32_e32 v19, v51
	v_permlane32_swap_b32_e32 v20, v52
	v_permlane32_swap_b32_e32 v21, v53
	v_permlane32_swap_b32_e32 v22, v54
	v_permlane32_swap_b32_e32 v23, v55
	v_permlane32_swap_b32_e32 v24, v56
	v_permlane32_swap_b32_e32 v25, v57
	v_permlane32_swap_b32_e32 v26, v58
	v_permlane32_swap_b32_e32 v27, v59
	v_permlane32_swap_b32_e32 v28, v60
	v_permlane32_swap_b32_e32 v29, v61
	v_permlane32_swap_b32_e32 v30, v62
	v_permlane32_swap_b32_e32 v31, v63
	v_permlane32_swap_b32_e32 v32, v64
	v_permlane32_swap_b32_e32 v33, v65
	v_permlane32_swap_b32_e32 v34, v66
	v_permlane32_swap_b32_e32 v35, v67
	v_permlane32_swap_b32_e32 v36, v68
	v_permlane32_swap_b32_e32 v37, v69
	v_permlane32_swap_b32_e32 v38, v70
	v_permlane32_swap_b32_e32 v39, v71
	v_permlane32_swap_b32_e32 v40, v72
	v_permlane32_swap_b32_e32 v41, v73
	v_permlane32_swap_b32_e32 v42, v74
	v_permlane32_swap_b32_e32 v43, v75
	v_permlane32_swap_b32_e32 v44, v76
	v_permlane32_swap_b32_e32 v45, v77
	v_permlane32_swap_b32_e32 v46, v78
	v_permlane32_swap_b32_e32 v47, v79
	v_fmac_f32_e32 v63, v116, v120
	v_fmac_f32_e32 v79, v118, v121
	v_fmac_f32_dpp v63, v120, v122 quad_perm:[1,0,3,2] row_mask:0xf bank_mask:0xf
	v_fmac_f32_dpp v79, v121, v123 quad_perm:[1,0,3,2] row_mask:0xf bank_mask:0xf
	v_cvt_pk_bf16_f32 v148, v63, v79
	ds_write_b32 v151, v148 offset:8432
	v_fmac_f32_e32 v62, v116, v63
	v_fmac_f32_e32 v78, v118, v79
	v_fmac_f32_dpp v62, v63, v122 quad_perm:[1,0,3,2] row_mask:0xf bank_mask:0xf
	v_fmac_f32_dpp v78, v79, v123 quad_perm:[1,0,3,2] row_mask:0xf bank_mask:0xf
	v_cvt_pk_bf16_f32 v149, v62, v78
	ds_write_b32 v151, v149 offset:8160
	v_fmac_f32_e32 v61, v116, v62
	v_fmac_f32_e32 v77, v118, v78
	v_fmac_f32_dpp v61, v62, v122 quad_perm:[1,0,3,2] row_mask:0xf bank_mask:0xf
	v_fmac_f32_dpp v77, v78, v123 quad_perm:[1,0,3,2] row_mask:0xf bank_mask:0xf
	v_cvt_pk_bf16_f32 v148, v61, v77
	ds_write_b32 v151, v148 offset:7888
	v_fmac_f32_e32 v60, v116, v61
	v_fmac_f32_e32 v76, v118, v77
	v_fmac_f32_dpp v60, v61, v122 quad_perm:[1,0,3,2] row_mask:0xf bank_mask:0xf
	v_fmac_f32_dpp v76, v77, v123 quad_perm:[1,0,3,2] row_mask:0xf bank_mask:0xf
	v_cvt_pk_bf16_f32 v149, v60, v76
	ds_write_b32 v151, v149 offset:7616
	v_fmac_f32_e32 v31, v116, v60
	v_fmac_f32_e32 v47, v118, v76
	v_fmac_f32_dpp v31, v60, v122 quad_perm:[1,0,3,2] row_mask:0xf bank_mask:0xf
	v_fmac_f32_dpp v47, v76, v123 quad_perm:[1,0,3,2] row_mask:0xf bank_mask:0xf
	v_cvt_pk_bf16_f32 v148, v31, v47
	ds_write_b32 v151, v148 offset:7344
	v_fmac_f32_e32 v30, v116, v31
	v_fmac_f32_e32 v46, v118, v47
	v_fmac_f32_dpp v30, v31, v122 quad_perm:[1,0,3,2] row_mask:0xf bank_mask:0xf
	v_fmac_f32_dpp v46, v47, v123 quad_perm:[1,0,3,2] row_mask:0xf bank_mask:0xf
	v_cvt_pk_bf16_f32 v149, v30, v46
	ds_write_b32 v151, v149 offset:7072
	v_fmac_f32_e32 v29, v116, v30
	v_fmac_f32_e32 v45, v118, v46
	v_fmac_f32_dpp v29, v30, v122 quad_perm:[1,0,3,2] row_mask:0xf bank_mask:0xf
	v_fmac_f32_dpp v45, v46, v123 quad_perm:[1,0,3,2] row_mask:0xf bank_mask:0xf
	v_cvt_pk_bf16_f32 v148, v29, v45
	ds_write_b32 v151, v148 offset:6800
	v_fmac_f32_e32 v28, v116, v29
	v_fmac_f32_e32 v44, v118, v45
	v_fmac_f32_dpp v28, v29, v122 quad_perm:[1,0,3,2] row_mask:0xf bank_mask:0xf
	v_fmac_f32_dpp v44, v45, v123 quad_perm:[1,0,3,2] row_mask:0xf bank_mask:0xf
	v_cvt_pk_bf16_f32 v149, v28, v44
	ds_write_b32 v151, v149 offset:6528
	v_fmac_f32_e32 v59, v116, v28
	v_fmac_f32_e32 v75, v118, v44
	v_fmac_f32_dpp v59, v28, v122 quad_perm:[1,0,3,2] row_mask:0xf bank_mask:0xf
	v_fmac_f32_dpp v75, v44, v123 quad_perm:[1,0,3,2] row_mask:0xf bank_mask:0xf
	v_cvt_pk_bf16_f32 v148, v59, v75
	ds_write_b32 v151, v148 offset:6256
	v_fmac_f32_e32 v58, v116, v59
	v_fmac_f32_e32 v74, v118, v75
	v_fmac_f32_dpp v58, v59, v122 quad_perm:[1,0,3,2] row_mask:0xf bank_mask:0xf
	v_fmac_f32_dpp v74, v75, v123 quad_perm:[1,0,3,2] row_mask:0xf bank_mask:0xf
	v_cvt_pk_bf16_f32 v149, v58, v74
	ds_write_b32 v151, v149 offset:5984
	v_fmac_f32_e32 v57, v116, v58
	v_fmac_f32_e32 v73, v118, v74
	v_fmac_f32_dpp v57, v58, v122 quad_perm:[1,0,3,2] row_mask:0xf bank_mask:0xf
	v_fmac_f32_dpp v73, v74, v123 quad_perm:[1,0,3,2] row_mask:0xf bank_mask:0xf
	v_cvt_pk_bf16_f32 v148, v57, v73
	ds_write_b32 v151, v148 offset:5712
	v_fmac_f32_e32 v56, v116, v57
	v_fmac_f32_e32 v72, v118, v73
	v_fmac_f32_dpp v56, v57, v122 quad_perm:[1,0,3,2] row_mask:0xf bank_mask:0xf
	v_fmac_f32_dpp v72, v73, v123 quad_perm:[1,0,3,2] row_mask:0xf bank_mask:0xf
	v_cvt_pk_bf16_f32 v149, v56, v72
	ds_write_b32 v151, v149 offset:5440
	v_fmac_f32_e32 v27, v116, v56
	v_fmac_f32_e32 v43, v118, v72
	v_fmac_f32_dpp v27, v56, v122 quad_perm:[1,0,3,2] row_mask:0xf bank_mask:0xf
	v_fmac_f32_dpp v43, v72, v123 quad_perm:[1,0,3,2] row_mask:0xf bank_mask:0xf
	v_cvt_pk_bf16_f32 v148, v27, v43
	ds_write_b32 v151, v148 offset:5168
	v_fmac_f32_e32 v26, v116, v27
	v_fmac_f32_e32 v42, v118, v43
	v_fmac_f32_dpp v26, v27, v122 quad_perm:[1,0,3,2] row_mask:0xf bank_mask:0xf
	v_fmac_f32_dpp v42, v43, v123 quad_perm:[1,0,3,2] row_mask:0xf bank_mask:0xf
	v_cvt_pk_bf16_f32 v149, v26, v42
	ds_write_b32 v151, v149 offset:4896
	v_fmac_f32_e32 v25, v116, v26
	v_fmac_f32_e32 v41, v118, v42
	v_fmac_f32_dpp v25, v26, v122 quad_perm:[1,0,3,2] row_mask:0xf bank_mask:0xf
	v_fmac_f32_dpp v41, v42, v123 quad_perm:[1,0,3,2] row_mask:0xf bank_mask:0xf
	v_cvt_pk_bf16_f32 v148, v25, v41
	ds_write_b32 v151, v148 offset:4624
	v_fmac_f32_e32 v24, v116, v25
	v_fmac_f32_e32 v40, v118, v41
	v_fmac_f32_dpp v24, v25, v122 quad_perm:[1,0,3,2] row_mask:0xf bank_mask:0xf
	v_fmac_f32_dpp v40, v41, v123 quad_perm:[1,0,3,2] row_mask:0xf bank_mask:0xf
	v_cvt_pk_bf16_f32 v149, v24, v40
	ds_write_b32 v151, v149 offset:4352
	v_fmac_f32_e32 v55, v116, v24
	v_fmac_f32_e32 v71, v118, v40
	v_fmac_f32_dpp v55, v24, v122 quad_perm:[1,0,3,2] row_mask:0xf bank_mask:0xf
	v_fmac_f32_dpp v71, v40, v123 quad_perm:[1,0,3,2] row_mask:0xf bank_mask:0xf
	v_cvt_pk_bf16_f32 v148, v55, v71
	ds_write_b32 v151, v148 offset:4080
	v_fmac_f32_e32 v54, v116, v55
	v_fmac_f32_e32 v70, v118, v71
	v_fmac_f32_dpp v54, v55, v122 quad_perm:[1,0,3,2] row_mask:0xf bank_mask:0xf
	v_fmac_f32_dpp v70, v71, v123 quad_perm:[1,0,3,2] row_mask:0xf bank_mask:0xf
	v_cvt_pk_bf16_f32 v149, v54, v70
	ds_write_b32 v151, v149 offset:3808
	v_fmac_f32_e32 v53, v116, v54
	v_fmac_f32_e32 v69, v118, v70
	v_fmac_f32_dpp v53, v54, v122 quad_perm:[1,0,3,2] row_mask:0xf bank_mask:0xf
	v_fmac_f32_dpp v69, v70, v123 quad_perm:[1,0,3,2] row_mask:0xf bank_mask:0xf
	v_cvt_pk_bf16_f32 v148, v53, v69
	ds_write_b32 v151, v148 offset:3536
	v_fmac_f32_e32 v52, v116, v53
	v_fmac_f32_e32 v68, v118, v69
	v_fmac_f32_dpp v52, v53, v122 quad_perm:[1,0,3,2] row_mask:0xf bank_mask:0xf
	v_fmac_f32_dpp v68, v69, v123 quad_perm:[1,0,3,2] row_mask:0xf bank_mask:0xf
	v_cvt_pk_bf16_f32 v149, v52, v68
	ds_write_b32 v151, v149 offset:3264
	v_fmac_f32_e32 v23, v116, v52
	v_fmac_f32_e32 v39, v118, v68
	v_fmac_f32_dpp v23, v52, v122 quad_perm:[1,0,3,2] row_mask:0xf bank_mask:0xf
	v_fmac_f32_dpp v39, v68, v123 quad_perm:[1,0,3,2] row_mask:0xf bank_mask:0xf
	v_cvt_pk_bf16_f32 v148, v23, v39
	ds_write_b32 v151, v148 offset:2992
	v_fmac_f32_e32 v22, v116, v23
	v_fmac_f32_e32 v38, v118, v39
	v_fmac_f32_dpp v22, v23, v122 quad_perm:[1,0,3,2] row_mask:0xf bank_mask:0xf
	v_fmac_f32_dpp v38, v39, v123 quad_perm:[1,0,3,2] row_mask:0xf bank_mask:0xf
	v_cvt_pk_bf16_f32 v149, v22, v38
	ds_write_b32 v151, v149 offset:2720
	v_fmac_f32_e32 v21, v116, v22
	v_fmac_f32_e32 v37, v118, v38
	v_fmac_f32_dpp v21, v22, v122 quad_perm:[1,0,3,2] row_mask:0xf bank_mask:0xf
	v_fmac_f32_dpp v37, v38, v123 quad_perm:[1,0,3,2] row_mask:0xf bank_mask:0xf
	v_cvt_pk_bf16_f32 v148, v21, v37
	ds_write_b32 v151, v148 offset:2448
	v_fmac_f32_e32 v20, v116, v21
	v_fmac_f32_e32 v36, v118, v37
	v_fmac_f32_dpp v20, v21, v122 quad_perm:[1,0,3,2] row_mask:0xf bank_mask:0xf
	v_fmac_f32_dpp v36, v37, v123 quad_perm:[1,0,3,2] row_mask:0xf bank_mask:0xf
	v_cvt_pk_bf16_f32 v149, v20, v36
	ds_write_b32 v151, v149 offset:2176
	v_fmac_f32_e32 v51, v116, v20
	v_fmac_f32_e32 v67, v118, v36
	v_fmac_f32_dpp v51, v20, v122 quad_perm:[1,0,3,2] row_mask:0xf bank_mask:0xf
	v_fmac_f32_dpp v67, v36, v123 quad_perm:[1,0,3,2] row_mask:0xf bank_mask:0xf
	v_cvt_pk_bf16_f32 v148, v51, v67
	ds_write_b32 v151, v148 offset:1904
	v_fmac_f32_e32 v50, v116, v51
	v_fmac_f32_e32 v66, v118, v67
	v_fmac_f32_dpp v50, v51, v122 quad_perm:[1,0,3,2] row_mask:0xf bank_mask:0xf
	v_fmac_f32_dpp v66, v67, v123 quad_perm:[1,0,3,2] row_mask:0xf bank_mask:0xf
	v_cvt_pk_bf16_f32 v149, v50, v66
	ds_write_b32 v151, v149 offset:1632
	v_fmac_f32_e32 v49, v116, v50
	v_fmac_f32_e32 v65, v118, v66
	v_fmac_f32_dpp v49, v50, v122 quad_perm:[1,0,3,2] row_mask:0xf bank_mask:0xf
	v_fmac_f32_dpp v65, v66, v123 quad_perm:[1,0,3,2] row_mask:0xf bank_mask:0xf
	v_cvt_pk_bf16_f32 v148, v49, v65
	ds_write_b32 v151, v148 offset:1360
	v_fmac_f32_e32 v48, v116, v49
	v_fmac_f32_e32 v64, v118, v65
	v_fmac_f32_dpp v48, v49, v122 quad_perm:[1,0,3,2] row_mask:0xf bank_mask:0xf
	v_fmac_f32_dpp v64, v65, v123 quad_perm:[1,0,3,2] row_mask:0xf bank_mask:0xf
	v_cvt_pk_bf16_f32 v149, v48, v64
	ds_write_b32 v151, v149 offset:1088
	v_fmac_f32_e32 v19, v116, v48
	v_fmac_f32_e32 v35, v118, v64
	v_fmac_f32_dpp v19, v48, v122 quad_perm:[1,0,3,2] row_mask:0xf bank_mask:0xf
	v_fmac_f32_dpp v35, v64, v123 quad_perm:[1,0,3,2] row_mask:0xf bank_mask:0xf
	v_cvt_pk_bf16_f32 v148, v19, v35
	ds_write_b32 v151, v148 offset:816
	v_fmac_f32_e32 v18, v116, v19
	v_fmac_f32_e32 v34, v118, v35
	v_fmac_f32_dpp v18, v19, v122 quad_perm:[1,0,3,2] row_mask:0xf bank_mask:0xf
	v_fmac_f32_dpp v34, v35, v123 quad_perm:[1,0,3,2] row_mask:0xf bank_mask:0xf
	v_cvt_pk_bf16_f32 v149, v18, v34
	ds_write_b32 v151, v149 offset:544
	v_fmac_f32_e32 v17, v116, v18
	v_fmac_f32_e32 v33, v118, v34
	v_fmac_f32_dpp v17, v18, v122 quad_perm:[1,0,3,2] row_mask:0xf bank_mask:0xf
	v_fmac_f32_dpp v33, v34, v123 quad_perm:[1,0,3,2] row_mask:0xf bank_mask:0xf
	v_cvt_pk_bf16_f32 v148, v17, v33
	ds_write_b32 v151, v148 offset:272
	v_fmac_f32_e32 v16, v116, v17
	v_fmac_f32_e32 v32, v118, v33
	v_fmac_f32_dpp v16, v17, v122 quad_perm:[1,0,3,2] row_mask:0xf bank_mask:0xf
	v_fmac_f32_dpp v32, v33, v123 quad_perm:[1,0,3,2] row_mask:0xf bank_mask:0xf
	v_cvt_pk_bf16_f32 v149, v16, v32
	ds_write_b32 v151, v149
	v_mov_b32_e32 v120, v16
	v_mov_b32_e32 v121, v32
	ds_read_b128 v[124:127], v152
	ds_read_b128 v[128:131], v152 offset:64
	ds_read_b128 v[132:135], v152 offset:128
	ds_read_b128 v[136:139], v152 offset:192
	s_waitcnt lgkmcnt(3)
	v_mfma_f32_16x16x32_bf16 v[140:143], v[100:103], v[124:127], 0
	s_waitcnt lgkmcnt(2)
	v_mfma_f32_16x16x32_bf16 v[140:143], v[104:107], v[128:131], v[140:143]
	s_waitcnt lgkmcnt(1)
	v_mfma_f32_16x16x32_bf16 v[140:143], v[108:111], v[132:135], v[140:143]
	s_waitcnt lgkmcnt(0)
	v_mfma_f32_16x16x32_bf16 v[140:143], v[112:115], v[136:139], v[140:143]
	s_nop 9
	global_store_dwordx4 v153, v[140:143], s[12:13]
	s_nop 1
	ds_read_b128 v[124:127], v152 offset:4352
	ds_read_b128 v[128:131], v152 offset:4416
	ds_read_b128 v[132:135], v152 offset:4480
	ds_read_b128 v[136:139], v152 offset:4544
	s_waitcnt lgkmcnt(3)
	v_mfma_f32_16x16x32_bf16 v[140:143], v[100:103], v[124:127], 0
	s_waitcnt lgkmcnt(2)
	v_mfma_f32_16x16x32_bf16 v[140:143], v[104:107], v[128:131], v[140:143]
	s_waitcnt lgkmcnt(1)
	v_mfma_f32_16x16x32_bf16 v[140:143], v[108:111], v[132:135], v[140:143]
	s_waitcnt lgkmcnt(0)
	v_mfma_f32_16x16x32_bf16 v[140:143], v[112:115], v[136:139], v[140:143]
	s_nop 9
	global_store_dwordx4 v157, v[140:143], s[12:13]
	s_nop 1
	s_sub_u32 s12, s12, 2048
	s_subb_u32 s13, s13, 0
	s_add_u32 s14, s14, 2
	s_cmp_lt_u32 s14, 16
	s_cbranch_scc1 .Lssm_tileA_d1m0
	s_waitcnt vmcnt(0) lgkmcnt(0)
	s_lshr_b32 s21, s89, 1
	s_lshl_b32 s21, s21, 2
	s_add_u32 s37, s21, 0x21000
	v_mov_b32_e32 v182, s37
	v_mov_b32_e32 v183, 1
	v_cmp_eq_u32_e32 vcc, 0, v191
	s_and_saveexec_b64 s[0:1], vcc
	ds_add_u32 v182, v183
	s_mov_b64 exec, s[0:1]
	s_waitcnt lgkmcnt(0)
	s_mov_b32 s38, 0

.Lssm_spin_done_d1m0:
	s_mov_b64 s[42:43], s[6:7]
	s_sub_u32 s42, s42, 2048
	s_subb_u32 s43, s43, 0
	s_lshl_b32 s31, s25, 11
	s_lshl_b32 s29, s24, 5
	s_add_u32 s31, s31, s29
	s_add_u32 s31, s31, 344915968
	s_add_u32 s12, s62, s31
	s_addc_u32 s13, s63, 0
	s_mov_b64 s[64:65], s[34:35]
	s_add_u32 s64, s64, 1024
	s_addc_u32 s65, s65, 0
	global_load_dwordx4 v[6:9], v153, s[42:43]
	global_load_dwordx4 v[10:13], v157, s[42:43]
	s_sub_u32 s42, s42, 2048
	s_subb_u32 s43, s43, 0
	s_waitcnt vmcnt(0)
.Lssm_tileB_d1m0:
	s_waitcnt vmcnt(7)
	v_mfma_f32_32x32x16_bf16 v[16:31], v[80:83], v[84:87], 0
	v_mfma_f32_32x32x16_bf16 v[32:47], v[80:83], v[88:91], 0
	v_mfma_f32_32x32x16_bf16 v[48:63], v[80:83], v[92:95], 0
	v_mfma_f32_32x32x16_bf16 v[64:79], v[80:83], v[96:99], 0
	ds_write_b128 v162, v[80:83]
	global_load_dwordx4 v[172:175], v153, s[42:43]
	global_load_dwordx4 v[176:179], v157, s[42:43]
	s_sub_u32 s42, s42, 2048
	s_subb_u32 s43, s43, 0
	s_nop 11
	global_load_dwordx4 v[80:83], v150, s[10:11]
	s_sub_u32 s34, s34, 1024
	s_subb_u32 s35, s35, 0
	s_sub_u32 s10, s10, 1024
	s_subb_u32 s11, s11, 0
	v_permlane32_swap_b32_e32 v16, v48
	v_permlane32_swap_b32_e32 v17, v49
	v_permlane32_swap_b32_e32 v18, v50
	v_permlane32_swap_b32_e32 v19, v51
	v_permlane32_swap_b32_e32 v20, v52
	v_permlane32_swap_b32_e32 v21, v53
	v_permlane32_swap_b32_e32 v22, v54
	v_permlane32_swap_b32_e32 v23, v55
	v_permlane32_swap_b32_e32 v24, v56
	v_permlane32_swap_b32_e32 v25, v57
	v_permlane32_swap_b32_e32 v26, v58
	v_permlane32_swap_b32_e32 v27, v59
	v_permlane32_swap_b32_e32 v28, v60
	v_permlane32_swap_b32_e32 v29, v61
	v_permlane32_swap_b32_e32 v30, v62
	v_permlane32_swap_b32_e32 v31, v63
	v_permlane32_swap_b32_e32 v32, v64
	v_permlane32_swap_b32_e32 v33, v65
	v_permlane32_swap_b32_e32 v34, v66
	v_permlane32_swap_b32_e32 v35, v67
	v_permlane32_swap_b32_e32 v36, v68
	v_permlane32_swap_b32_e32 v37, v69
	v_permlane32_swap_b32_e32 v38, v70
	v_permlane32_swap_b32_e32 v39, v71
	v_permlane32_swap_b32_e32 v40, v72
	v_permlane32_swap_b32_e32 v41, v73
	v_permlane32_swap_b32_e32 v42, v74
	v_permlane32_swap_b32_e32 v43, v75
	v_permlane32_swap_b32_e32 v44, v76
	v_permlane32_swap_b32_e32 v45, v77
	v_permlane32_swap_b32_e32 v46, v78
	v_permlane32_swap_b32_e32 v47, v79
	v_fmac_f32_e32 v63, v116, v120
	v_fmac_f32_e32 v79, v118, v121
	v_fmac_f32_dpp v63, v120, v122 quad_perm:[1,0,3,2] row_mask:0xf bank_mask:0xf
	v_fmac_f32_dpp v79, v121, v123 quad_perm:[1,0,3,2] row_mask:0xf bank_mask:0xf
	v_cvt_pk_bf16_f32 v148, v63, v79
	ds_write_b32 v151, v148 offset:8432
	v_fmac_f32_e32 v62, v116, v63
	v_fmac_f32_e32 v78, v118, v79
	v_fmac_f32_dpp v62, v63, v122 quad_perm:[1,0,3,2] row_mask:0xf bank_mask:0xf
	v_fmac_f32_dpp v78, v79, v123 quad_perm:[1,0,3,2] row_mask:0xf bank_mask:0xf
	v_cvt_pk_bf16_f32 v149, v62, v78
	ds_write_b32 v151, v149 offset:8160
	v_fmac_f32_e32 v61, v116, v62
	v_fmac_f32_e32 v77, v118, v78
	v_fmac_f32_dpp v61, v62, v122 quad_perm:[1,0,3,2] row_mask:0xf bank_mask:0xf
	v_fmac_f32_dpp v77, v78, v123 quad_perm:[1,0,3,2] row_mask:0xf bank_mask:0xf
	v_cvt_pk_bf16_f32 v148, v61, v77
	ds_write_b32 v151, v148 offset:7888
	v_fmac_f32_e32 v60, v116, v61
	v_fmac_f32_e32 v76, v118, v77
	v_fmac_f32_dpp v60, v61, v122 quad_perm:[1,0,3,2] row_mask:0xf bank_mask:0xf
	v_fmac_f32_dpp v76, v77, v123 quad_perm:[1,0,3,2] row_mask:0xf bank_mask:0xf
	v_cvt_pk_bf16_f32 v149, v60, v76
	ds_write_b32 v151, v149 offset:7616
	v_fmac_f32_e32 v31, v116, v60
	v_fmac_f32_e32 v47, v118, v76
	v_fmac_f32_dpp v31, v60, v122 quad_perm:[1,0,3,2] row_mask:0xf bank_mask:0xf
	v_fmac_f32_dpp v47, v76, v123 quad_perm:[1,0,3,2] row_mask:0xf bank_mask:0xf
	v_cvt_pk_bf16_f32 v148, v31, v47
	ds_write_b32 v151, v148 offset:7344
	v_fmac_f32_e32 v30, v116, v31
	v_fmac_f32_e32 v46, v118, v47
	v_fmac_f32_dpp v30, v31, v122 quad_perm:[1,0,3,2] row_mask:0xf bank_mask:0xf
	v_fmac_f32_dpp v46, v47, v123 quad_perm:[1,0,3,2] row_mask:0xf bank_mask:0xf
	v_cvt_pk_bf16_f32 v149, v30, v46
	ds_write_b32 v151, v149 offset:7072
	v_fmac_f32_e32 v29, v116, v30
	v_fmac_f32_e32 v45, v118, v46
	v_fmac_f32_dpp v29, v30, v122 quad_perm:[1,0,3,2] row_mask:0xf bank_mask:0xf
	v_fmac_f32_dpp v45, v46, v123 quad_perm:[1,0,3,2] row_mask:0xf bank_mask:0xf
	v_cvt_pk_bf16_f32 v148, v29, v45
	ds_write_b32 v151, v148 offset:6800
	v_fmac_f32_e32 v28, v116, v29
	v_fmac_f32_e32 v44, v118, v45
	v_fmac_f32_dpp v28, v29, v122 quad_perm:[1,0,3,2] row_mask:0xf bank_mask:0xf
	v_fmac_f32_dpp v44, v45, v123 quad_perm:[1,0,3,2] row_mask:0xf bank_mask:0xf
	v_cvt_pk_bf16_f32 v149, v28, v44
	ds_write_b32 v151, v149 offset:6528
	v_fmac_f32_e32 v59, v116, v28
	v_fmac_f32_e32 v75, v118, v44
	v_fmac_f32_dpp v59, v28, v122 quad_perm:[1,0,3,2] row_mask:0xf bank_mask:0xf
	v_fmac_f32_dpp v75, v44, v123 quad_perm:[1,0,3,2] row_mask:0xf bank_mask:0xf
	v_cvt_pk_bf16_f32 v148, v59, v75
	ds_write_b32 v151, v148 offset:6256
	v_fmac_f32_e32 v58, v116, v59
	v_fmac_f32_e32 v74, v118, v75
	v_fmac_f32_dpp v58, v59, v122 quad_perm:[1,0,3,2] row_mask:0xf bank_mask:0xf
	v_fmac_f32_dpp v74, v75, v123 quad_perm:[1,0,3,2] row_mask:0xf bank_mask:0xf
	v_cvt_pk_bf16_f32 v149, v58, v74
	ds_write_b32 v151, v149 offset:5984
	v_fmac_f32_e32 v57, v116, v58
	v_fmac_f32_e32 v73, v118, v74
	v_fmac_f32_dpp v57, v58, v122 quad_perm:[1,0,3,2] row_mask:0xf bank_mask:0xf
	v_fmac_f32_dpp v73, v74, v123 quad_perm:[1,0,3,2] row_mask:0xf bank_mask:0xf
	v_cvt_pk_bf16_f32 v148, v57, v73
	ds_write_b32 v151, v148 offset:5712
	v_fmac_f32_e32 v56, v116, v57
	v_fmac_f32_e32 v72, v118, v73
	v_fmac_f32_dpp v56, v57, v122 quad_perm:[1,0,3,2] row_mask:0xf bank_mask:0xf
	v_fmac_f32_dpp v72, v73, v123 quad_perm:[1,0,3,2] row_mask:0xf bank_mask:0xf
	v_cvt_pk_bf16_f32 v149, v56, v72
	ds_write_b32 v151, v149 offset:5440
	v_fmac_f32_e32 v27, v116, v56
	v_fmac_f32_e32 v43, v118, v72
	v_fmac_f32_dpp v27, v56, v122 quad_perm:[1,0,3,2] row_mask:0xf bank_mask:0xf
	v_fmac_f32_dpp v43, v72, v123 quad_perm:[1,0,3,2] row_mask:0xf bank_mask:0xf
	v_cvt_pk_bf16_f32 v148, v27, v43
	ds_write_b32 v151, v148 offset:5168
	v_fmac_f32_e32 v26, v116, v27
	v_fmac_f32_e32 v42, v118, v43
	v_fmac_f32_dpp v26, v27, v122 quad_perm:[1,0,3,2] row_mask:0xf bank_mask:0xf
	v_fmac_f32_dpp v42, v43, v123 quad_perm:[1,0,3,2] row_mask:0xf bank_mask:0xf
	v_cvt_pk_bf16_f32 v149, v26, v42
	ds_write_b32 v151, v149 offset:4896
	v_fmac_f32_e32 v25, v116, v26
	v_fmac_f32_e32 v41, v118, v42
	v_fmac_f32_dpp v25, v26, v122 quad_perm:[1,0,3,2] row_mask:0xf bank_mask:0xf
	v_fmac_f32_dpp v41, v42, v123 quad_perm:[1,0,3,2] row_mask:0xf bank_mask:0xf
	v_cvt_pk_bf16_f32 v148, v25, v41
	ds_write_b32 v151, v148 offset:4624
	v_fmac_f32_e32 v24, v116, v25
	v_fmac_f32_e32 v40, v118, v41
	v_fmac_f32_dpp v24, v25, v122 quad_perm:[1,0,3,2] row_mask:0xf bank_mask:0xf
	v_fmac_f32_dpp v40, v41, v123 quad_perm:[1,0,3,2] row_mask:0xf bank_mask:0xf
	v_cvt_pk_bf16_f32 v149, v24, v40
	ds_write_b32 v151, v149 offset:4352
	v_fmac_f32_e32 v55, v116, v24
	v_fmac_f32_e32 v71, v118, v40
	v_fmac_f32_dpp v55, v24, v122 quad_perm:[1,0,3,2] row_mask:0xf bank_mask:0xf
	v_fmac_f32_dpp v71, v40, v123 quad_perm:[1,0,3,2] row_mask:0xf bank_mask:0xf
	v_cvt_pk_bf16_f32 v148, v55, v71
	ds_write_b32 v151, v148 offset:4080
	v_fmac_f32_e32 v54, v116, v55
	v_fmac_f32_e32 v70, v118, v71
	v_fmac_f32_dpp v54, v55, v122 quad_perm:[1,0,3,2] row_mask:0xf bank_mask:0xf
	v_fmac_f32_dpp v70, v71, v123 quad_perm:[1,0,3,2] row_mask:0xf bank_mask:0xf
	v_cvt_pk_bf16_f32 v149, v54, v70
	ds_write_b32 v151, v149 offset:3808
	v_fmac_f32_e32 v53, v116, v54
	v_fmac_f32_e32 v69, v118, v70
	v_fmac_f32_dpp v53, v54, v122 quad_perm:[1,0,3,2] row_mask:0xf bank_mask:0xf
	v_fmac_f32_dpp v69, v70, v123 quad_perm:[1,0,3,2] row_mask:0xf bank_mask:0xf
	v_cvt_pk_bf16_f32 v148, v53, v69
	ds_write_b32 v151, v148 offset:3536
	v_fmac_f32_e32 v52, v116, v53
	v_fmac_f32_e32 v68, v118, v69
	v_fmac_f32_dpp v52, v53, v122 quad_perm:[1,0,3,2] row_mask:0xf bank_mask:0xf
	v_fmac_f32_dpp v68, v69, v123 quad_perm:[1,0,3,2] row_mask:0xf bank_mask:0xf
	v_cvt_pk_bf16_f32 v149, v52, v68
	ds_write_b32 v151, v149 offset:3264
	v_fmac_f32_e32 v23, v116, v52
	v_fmac_f32_e32 v39, v118, v68
	v_fmac_f32_dpp v23, v52, v122 quad_perm:[1,0,3,2] row_mask:0xf bank_mask:0xf
	v_fmac_f32_dpp v39, v68, v123 quad_perm:[1,0,3,2] row_mask:0xf bank_mask:0xf
	v_cvt_pk_bf16_f32 v148, v23, v39
	ds_write_b32 v151, v148 offset:2992
	v_fmac_f32_e32 v22, v116, v23
	v_fmac_f32_e32 v38, v118, v39
	v_fmac_f32_dpp v22, v23, v122 quad_perm:[1,0,3,2] row_mask:0xf bank_mask:0xf
	v_fmac_f32_dpp v38, v39, v123 quad_perm:[1,0,3,2] row_mask:0xf bank_mask:0xf
	v_cvt_pk_bf16_f32 v149, v22, v38
	ds_write_b32 v151, v149 offset:2720
	v_fmac_f32_e32 v21, v116, v22
	v_fmac_f32_e32 v37, v118, v38
	v_fmac_f32_dpp v21, v22, v122 quad_perm:[1,0,3,2] row_mask:0xf bank_mask:0xf
	v_fmac_f32_dpp v37, v38, v123 quad_perm:[1,0,3,2] row_mask:0xf bank_mask:0xf
	v_cvt_pk_bf16_f32 v148, v21, v37
	ds_write_b32 v151, v148 offset:2448
	v_fmac_f32_e32 v20, v116, v21
	v_fmac_f32_e32 v36, v118, v37
	v_fmac_f32_dpp v20, v21, v122 quad_perm:[1,0,3,2] row_mask:0xf bank_mask:0xf
	v_fmac_f32_dpp v36, v37, v123 quad_perm:[1,0,3,2] row_mask:0xf bank_mask:0xf
	v_cvt_pk_bf16_f32 v149, v20, v36
	ds_write_b32 v151, v149 offset:2176
	v_fmac_f32_e32 v51, v116, v20
	v_fmac_f32_e32 v67, v118, v36
	v_fmac_f32_dpp v51, v20, v122 quad_perm:[1,0,3,2] row_mask:0xf bank_mask:0xf
	v_fmac_f32_dpp v67, v36, v123 quad_perm:[1,0,3,2] row_mask:0xf bank_mask:0xf
	v_cvt_pk_bf16_f32 v148, v51, v67
	ds_write_b32 v151, v148 offset:1904
	v_fmac_f32_e32 v50, v116, v51
	v_fmac_f32_e32 v66, v118, v67
	v_fmac_f32_dpp v50, v51, v122 quad_perm:[1,0,3,2] row_mask:0xf bank_mask:0xf
	v_fmac_f32_dpp v66, v67, v123 quad_perm:[1,0,3,2] row_mask:0xf bank_mask:0xf
	v_cvt_pk_bf16_f32 v149, v50, v66
	ds_write_b32 v151, v149 offset:1632
	v_fmac_f32_e32 v49, v116, v50
	v_fmac_f32_e32 v65, v118, v66
	v_fmac_f32_dpp v49, v50, v122 quad_perm:[1,0,3,2] row_mask:0xf bank_mask:0xf
	v_fmac_f32_dpp v65, v66, v123 quad_perm:[1,0,3,2] row_mask:0xf bank_mask:0xf
	v_cvt_pk_bf16_f32 v148, v49, v65
	ds_write_b32 v151, v148 offset:1360
	v_fmac_f32_e32 v48, v116, v49
	v_fmac_f32_e32 v64, v118, v65
	v_fmac_f32_dpp v48, v49, v122 quad_perm:[1,0,3,2] row_mask:0xf bank_mask:0xf
	v_fmac_f32_dpp v64, v65, v123 quad_perm:[1,0,3,2] row_mask:0xf bank_mask:0xf
	v_cvt_pk_bf16_f32 v149, v48, v64
	ds_write_b32 v151, v149 offset:1088
	v_fmac_f32_e32 v19, v116, v48
	v_fmac_f32_e32 v35, v118, v64
	v_fmac_f32_dpp v19, v48, v122 quad_perm:[1,0,3,2] row_mask:0xf bank_mask:0xf
	v_fmac_f32_dpp v35, v64, v123 quad_perm:[1,0,3,2] row_mask:0xf bank_mask:0xf
	v_cvt_pk_bf16_f32 v148, v19, v35
	ds_write_b32 v151, v148 offset:816
	v_fmac_f32_e32 v18, v116, v19
	v_fmac_f32_e32 v34, v118, v35
	v_fmac_f32_dpp v18, v19, v122 quad_perm:[1,0,3,2] row_mask:0xf bank_mask:0xf
	v_fmac_f32_dpp v34, v35, v123 quad_perm:[1,0,3,2] row_mask:0xf bank_mask:0xf
	v_cvt_pk_bf16_f32 v149, v18, v34
	ds_write_b32 v151, v149 offset:544
	v_fmac_f32_e32 v17, v116, v18
	v_fmac_f32_e32 v33, v118, v34
	v_fmac_f32_dpp v17, v18, v122 quad_perm:[1,0,3,2] row_mask:0xf bank_mask:0xf
	v_fmac_f32_dpp v33, v34, v123 quad_perm:[1,0,3,2] row_mask:0xf bank_mask:0xf
	v_cvt_pk_bf16_f32 v148, v17, v33
	ds_write_b32 v151, v148 offset:272
	v_fmac_f32_e32 v16, v116, v17
	v_fmac_f32_e32 v32, v118, v33
	v_fmac_f32_dpp v16, v17, v122 quad_perm:[1,0,3,2] row_mask:0xf bank_mask:0xf
	v_fmac_f32_dpp v32, v33, v123 quad_perm:[1,0,3,2] row_mask:0xf bank_mask:0xf
	v_cvt_pk_bf16_f32 v149, v16, v32
	ds_write_b32 v151, v149
	v_mov_b32_e32 v120, v16
	v_mov_b32_e32 v121, v32
	ds_read_b128 v[124:127], v152
	ds_read_b128 v[128:131], v152 offset:64
	ds_read_b128 v[132:135], v152 offset:128
	ds_read_b128 v[136:139], v152 offset:192
	ds_read_b64 v[160:161], v163
	s_waitcnt lgkmcnt(4)
	v_mfma_f32_16x16x32_bf16 v[140:143], v[100:103], v[124:127], 0
	s_waitcnt lgkmcnt(3)
	v_mfma_f32_16x16x32_bf16 v[140:143], v[104:107], v[128:131], v[140:143]
	s_waitcnt lgkmcnt(2)
	v_mfma_f32_16x16x32_bf16 v[140:143], v[108:111], v[132:135], v[140:143]
	s_waitcnt lgkmcnt(1)
	v_mfma_f32_16x16x32_bf16 v[140:143], v[112:115], v[136:139], v[140:143]
	s_nop 9
	s_waitcnt vmcnt(7) lgkmcnt(0)
	v_add_f32_e32 v182, v6, v140
	v_add_f32_e32 v183, v7, v141
	v_add_f32_e32 v184, v8, v142
	v_add_f32_e32 v185, v9, v143
	v_lshlrev_b32_e32 v186, 16, v160
	v_and_b32_e32 v187, 0xffff0000, v160
	v_lshlrev_b32_e32 v188, 16, v161
	v_and_b32_e32 v189, 0xffff0000, v161
	v_fmac_f32_e32 v182, v164, v186
	v_fmac_f32_e32 v183, v165, v187
	v_fmac_f32_e32 v184, v166, v188
	v_fmac_f32_e32 v185, v167, v189
	v_mul_f32_e32 v186, 0x3d372713, v182
	v_mul_f32_e32 v187, 0x3d372713, v183
	v_mul_f32_e32 v188, 0x3d372713, v184
	v_mul_f32_e32 v189, 0x3d372713, v185
	v_mul_f32_e32 v186, v182, v186
	v_mul_f32_e32 v187, v183, v187
	v_mul_f32_e32 v188, v184, v188
	v_mul_f32_e32 v189, v185, v189
	v_fma_f32 v186, v182, v186, v182
	v_fma_f32 v187, v183, v187, v183
	v_fma_f32 v188, v184, v188, v184
	v_fma_f32 v189, v185, v189, v185
	v_mul_f32_e32 v186, 0xbfcc422a, v186
	v_mul_f32_e32 v187, 0xbfcc422a, v187
	v_mul_f32_e32 v188, 0xbfcc422a, v188
	v_mul_f32_e32 v189, 0xbfcc422a, v189
	v_mul_f32_e32 v186, 0x3fb8aa3b, v186
	v_mul_f32_e32 v187, 0x3fb8aa3b, v187
	v_mul_f32_e32 v188, 0x3fb8aa3b, v188
	v_mul_f32_e32 v189, 0x3fb8aa3b, v189
	v_exp_f32_e32 v186, v186
	v_exp_f32_e32 v187, v187
	v_exp_f32_e32 v188, v188
	v_exp_f32_e32 v189, v189
	v_add_f32_e32 v186, 1.0, v186
	v_add_f32_e32 v187, 1.0, v187
	v_add_f32_e32 v188, 1.0, v188
	v_add_f32_e32 v189, 1.0, v189
	v_rcp_f32_e32 v186, v186
	v_rcp_f32_e32 v187, v187
	v_rcp_f32_e32 v188, v188
	v_rcp_f32_e32 v189, v189
	v_mul_f32_e32 v182, v182, v186
	v_mul_f32_e32 v183, v183, v187
	v_mul_f32_e32 v184, v184, v188
	v_mul_f32_e32 v185, v185, v189
	v_cvt_pk_bf16_f32 v148, v182, v183
	v_cvt_pk_bf16_f32 v149, v184, v185
	global_store_dwordx2 v156, v[148:149], s[12:13]
	ds_read_b128 v[124:127], v152 offset:4352
	ds_read_b128 v[128:131], v152 offset:4416
	ds_read_b128 v[132:135], v152 offset:4480
	ds_read_b128 v[136:139], v152 offset:4544
	ds_read_b64 v[160:161], v163 offset:512
	s_waitcnt lgkmcnt(4)
	v_mfma_f32_16x16x32_bf16 v[140:143], v[100:103], v[124:127], 0
	s_waitcnt lgkmcnt(3)
	v_mfma_f32_16x16x32_bf16 v[140:143], v[104:107], v[128:131], v[140:143]
	s_waitcnt lgkmcnt(2)
	v_mfma_f32_16x16x32_bf16 v[140:143], v[108:111], v[132:135], v[140:143]
	s_waitcnt lgkmcnt(1)
	v_mfma_f32_16x16x32_bf16 v[140:143], v[112:115], v[136:139], v[140:143]
	s_nop 9
	s_waitcnt vmcnt(7) lgkmcnt(0)
	v_add_f32_e32 v182, v10, v140
	v_add_f32_e32 v183, v11, v141
	v_add_f32_e32 v184, v12, v142
	v_add_f32_e32 v185, v13, v143
	v_lshlrev_b32_e32 v186, 16, v160
	v_and_b32_e32 v187, 0xffff0000, v160
	v_lshlrev_b32_e32 v188, 16, v161
	v_and_b32_e32 v189, 0xffff0000, v161
	v_fmac_f32_e32 v182, v164, v186
	v_fmac_f32_e32 v183, v165, v187
	v_fmac_f32_e32 v184, v166, v188
	v_fmac_f32_e32 v185, v167, v189
	v_mul_f32_e32 v186, 0x3d372713, v182
	v_mul_f32_e32 v187, 0x3d372713, v183
	v_mul_f32_e32 v188, 0x3d372713, v184
	v_mul_f32_e32 v189, 0x3d372713, v185
	v_mul_f32_e32 v186, v182, v186
	v_mul_f32_e32 v187, v183, v187
	v_mul_f32_e32 v188, v184, v188
	v_mul_f32_e32 v189, v185, v189
	v_fma_f32 v186, v182, v186, v182
	v_fma_f32 v187, v183, v187, v183
	v_fma_f32 v188, v184, v188, v184
	v_fma_f32 v189, v185, v189, v185
	v_mul_f32_e32 v186, 0xbfcc422a, v186
	v_mul_f32_e32 v187, 0xbfcc422a, v187
	v_mul_f32_e32 v188, 0xbfcc422a, v188
	v_mul_f32_e32 v189, 0xbfcc422a, v189
	v_mul_f32_e32 v186, 0x3fb8aa3b, v186
	v_mul_f32_e32 v187, 0x3fb8aa3b, v187
	v_mul_f32_e32 v188, 0x3fb8aa3b, v188
	v_mul_f32_e32 v189, 0x3fb8aa3b, v189
	v_exp_f32_e32 v186, v186
	v_exp_f32_e32 v187, v187
	v_exp_f32_e32 v188, v188
	v_exp_f32_e32 v189, v189
	v_add_f32_e32 v186, 1.0, v186
	v_add_f32_e32 v187, 1.0, v187
	v_add_f32_e32 v188, 1.0, v188
	v_add_f32_e32 v189, 1.0, v189
	v_rcp_f32_e32 v186, v186
	v_rcp_f32_e32 v187, v187
	v_rcp_f32_e32 v188, v188
	v_rcp_f32_e32 v189, v189
	v_mul_f32_e32 v182, v182, v186
	v_mul_f32_e32 v183, v183, v187
	v_mul_f32_e32 v184, v184, v188
	v_mul_f32_e32 v185, v185, v189
	v_cvt_pk_bf16_f32 v148, v182, v183
	v_cvt_pk_bf16_f32 v149, v184, v185
	global_store_dwordx2 v159, v[148:149], s[12:13]
	s_sub_u32 s12, s12, 65536
	s_subb_u32 s13, s13, 0
	s_waitcnt vmcnt(7)
	v_mfma_f32_32x32x16_bf16 v[16:31], v[144:147], v[84:87], 0
	v_mfma_f32_32x32x16_bf16 v[32:47], v[144:147], v[88:91], 0
	v_mfma_f32_32x32x16_bf16 v[48:63], v[144:147], v[92:95], 0
	v_mfma_f32_32x32x16_bf16 v[64:79], v[144:147], v[96:99], 0
	ds_write_b128 v162, v[144:147]
	global_load_dwordx4 v[6:9], v153, s[42:43]
	global_load_dwordx4 v[10:13], v157, s[42:43]
	s_sub_u32 s42, s42, 2048
	s_subb_u32 s43, s43, 0
	s_nop 11
	global_load_dwordx4 v[144:147], v150, s[10:11]
	s_sub_u32 s34, s34, 1024
	s_subb_u32 s35, s35, 0
	s_sub_u32 s10, s10, 1024
	s_subb_u32 s11, s11, 0
	v_permlane32_swap_b32_e32 v16, v48
	v_permlane32_swap_b32_e32 v17, v49
	v_permlane32_swap_b32_e32 v18, v50
	v_permlane32_swap_b32_e32 v19, v51
	v_permlane32_swap_b32_e32 v20, v52
	v_permlane32_swap_b32_e32 v21, v53
	v_permlane32_swap_b32_e32 v22, v54
	v_permlane32_swap_b32_e32 v23, v55
	v_permlane32_swap_b32_e32 v24, v56
	v_permlane32_swap_b32_e32 v25, v57
	v_permlane32_swap_b32_e32 v26, v58
	v_permlane32_swap_b32_e32 v27, v59
	v_permlane32_swap_b32_e32 v28, v60
	v_permlane32_swap_b32_e32 v29, v61
	v_permlane32_swap_b32_e32 v30, v62
	v_permlane32_swap_b32_e32 v31, v63
	v_permlane32_swap_b32_e32 v32, v64
	v_permlane32_swap_b32_e32 v33, v65
	v_permlane32_swap_b32_e32 v34, v66
	v_permlane32_swap_b32_e32 v35, v67
	v_permlane32_swap_b32_e32 v36, v68
	v_permlane32_swap_b32_e32 v37, v69
	v_permlane32_swap_b32_e32 v38, v70
	v_permlane32_swap_b32_e32 v39, v71
	v_permlane32_swap_b32_e32 v40, v72
	v_permlane32_swap_b32_e32 v41, v73
	v_permlane32_swap_b32_e32 v42, v74
	v_permlane32_swap_b32_e32 v43, v75
	v_permlane32_swap_b32_e32 v44, v76
	v_permlane32_swap_b32_e32 v45, v77
	v_permlane32_swap_b32_e32 v46, v78
	v_permlane32_swap_b32_e32 v47, v79
	v_fmac_f32_e32 v63, v116, v120
	v_fmac_f32_e32 v79, v118, v121
	v_fmac_f32_dpp v63, v120, v122 quad_perm:[1,0,3,2] row_mask:0xf bank_mask:0xf
	v_fmac_f32_dpp v79, v121, v123 quad_perm:[1,0,3,2] row_mask:0xf bank_mask:0xf
	v_cvt_pk_bf16_f32 v148, v63, v79
	ds_write_b32 v151, v148 offset:8432
	v_fmac_f32_e32 v62, v116, v63
	v_fmac_f32_e32 v78, v118, v79
	v_fmac_f32_dpp v62, v63, v122 quad_perm:[1,0,3,2] row_mask:0xf bank_mask:0xf
	v_fmac_f32_dpp v78, v79, v123 quad_perm:[1,0,3,2] row_mask:0xf bank_mask:0xf
	v_cvt_pk_bf16_f32 v149, v62, v78
	ds_write_b32 v151, v149 offset:8160
	v_fmac_f32_e32 v61, v116, v62
	v_fmac_f32_e32 v77, v118, v78
	v_fmac_f32_dpp v61, v62, v122 quad_perm:[1,0,3,2] row_mask:0xf bank_mask:0xf
	v_fmac_f32_dpp v77, v78, v123 quad_perm:[1,0,3,2] row_mask:0xf bank_mask:0xf
	v_cvt_pk_bf16_f32 v148, v61, v77
	ds_write_b32 v151, v148 offset:7888
	v_fmac_f32_e32 v60, v116, v61
	v_fmac_f32_e32 v76, v118, v77
	v_fmac_f32_dpp v60, v61, v122 quad_perm:[1,0,3,2] row_mask:0xf bank_mask:0xf
	v_fmac_f32_dpp v76, v77, v123 quad_perm:[1,0,3,2] row_mask:0xf bank_mask:0xf
	v_cvt_pk_bf16_f32 v149, v60, v76
	ds_write_b32 v151, v149 offset:7616
	v_fmac_f32_e32 v31, v116, v60
	v_fmac_f32_e32 v47, v118, v76
	v_fmac_f32_dpp v31, v60, v122 quad_perm:[1,0,3,2] row_mask:0xf bank_mask:0xf
	v_fmac_f32_dpp v47, v76, v123 quad_perm:[1,0,3,2] row_mask:0xf bank_mask:0xf
	v_cvt_pk_bf16_f32 v148, v31, v47
	ds_write_b32 v151, v148 offset:7344
	v_fmac_f32_e32 v30, v116, v31
	v_fmac_f32_e32 v46, v118, v47
	v_fmac_f32_dpp v30, v31, v122 quad_perm:[1,0,3,2] row_mask:0xf bank_mask:0xf
	v_fmac_f32_dpp v46, v47, v123 quad_perm:[1,0,3,2] row_mask:0xf bank_mask:0xf
	v_cvt_pk_bf16_f32 v149, v30, v46
	ds_write_b32 v151, v149 offset:7072
	v_fmac_f32_e32 v29, v116, v30
	v_fmac_f32_e32 v45, v118, v46
	v_fmac_f32_dpp v29, v30, v122 quad_perm:[1,0,3,2] row_mask:0xf bank_mask:0xf
	v_fmac_f32_dpp v45, v46, v123 quad_perm:[1,0,3,2] row_mask:0xf bank_mask:0xf
	v_cvt_pk_bf16_f32 v148, v29, v45
	ds_write_b32 v151, v148 offset:6800
	v_fmac_f32_e32 v28, v116, v29
	v_fmac_f32_e32 v44, v118, v45
	v_fmac_f32_dpp v28, v29, v122 quad_perm:[1,0,3,2] row_mask:0xf bank_mask:0xf
	v_fmac_f32_dpp v44, v45, v123 quad_perm:[1,0,3,2] row_mask:0xf bank_mask:0xf
	v_cvt_pk_bf16_f32 v149, v28, v44
	ds_write_b32 v151, v149 offset:6528
	v_fmac_f32_e32 v59, v116, v28
	v_fmac_f32_e32 v75, v118, v44
	v_fmac_f32_dpp v59, v28, v122 quad_perm:[1,0,3,2] row_mask:0xf bank_mask:0xf
	v_fmac_f32_dpp v75, v44, v123 quad_perm:[1,0,3,2] row_mask:0xf bank_mask:0xf
	v_cvt_pk_bf16_f32 v148, v59, v75
	ds_write_b32 v151, v148 offset:6256
	v_fmac_f32_e32 v58, v116, v59
	v_fmac_f32_e32 v74, v118, v75
	v_fmac_f32_dpp v58, v59, v122 quad_perm:[1,0,3,2] row_mask:0xf bank_mask:0xf
	v_fmac_f32_dpp v74, v75, v123 quad_perm:[1,0,3,2] row_mask:0xf bank_mask:0xf
	v_cvt_pk_bf16_f32 v149, v58, v74
	ds_write_b32 v151, v149 offset:5984
	v_fmac_f32_e32 v57, v116, v58
	v_fmac_f32_e32 v73, v118, v74
	v_fmac_f32_dpp v57, v58, v122 quad_perm:[1,0,3,2] row_mask:0xf bank_mask:0xf
	v_fmac_f32_dpp v73, v74, v123 quad_perm:[1,0,3,2] row_mask:0xf bank_mask:0xf
	v_cvt_pk_bf16_f32 v148, v57, v73
	ds_write_b32 v151, v148 offset:5712
	v_fmac_f32_e32 v56, v116, v57
	v_fmac_f32_e32 v72, v118, v73
	v_fmac_f32_dpp v56, v57, v122 quad_perm:[1,0,3,2] row_mask:0xf bank_mask:0xf
	v_fmac_f32_dpp v72, v73, v123 quad_perm:[1,0,3,2] row_mask:0xf bank_mask:0xf
	v_cvt_pk_bf16_f32 v149, v56, v72
	ds_write_b32 v151, v149 offset:5440
	v_fmac_f32_e32 v27, v116, v56
	v_fmac_f32_e32 v43, v118, v72
	v_fmac_f32_dpp v27, v56, v122 quad_perm:[1,0,3,2] row_mask:0xf bank_mask:0xf
	v_fmac_f32_dpp v43, v72, v123 quad_perm:[1,0,3,2] row_mask:0xf bank_mask:0xf
	v_cvt_pk_bf16_f32 v148, v27, v43
	ds_write_b32 v151, v148 offset:5168
	v_fmac_f32_e32 v26, v116, v27
	v_fmac_f32_e32 v42, v118, v43
	v_fmac_f32_dpp v26, v27, v122 quad_perm:[1,0,3,2] row_mask:0xf bank_mask:0xf
	v_fmac_f32_dpp v42, v43, v123 quad_perm:[1,0,3,2] row_mask:0xf bank_mask:0xf
	v_cvt_pk_bf16_f32 v149, v26, v42
	ds_write_b32 v151, v149 offset:4896
	v_fmac_f32_e32 v25, v116, v26
	v_fmac_f32_e32 v41, v118, v42
	v_fmac_f32_dpp v25, v26, v122 quad_perm:[1,0,3,2] row_mask:0xf bank_mask:0xf
	v_fmac_f32_dpp v41, v42, v123 quad_perm:[1,0,3,2] row_mask:0xf bank_mask:0xf
	v_cvt_pk_bf16_f32 v148, v25, v41
	ds_write_b32 v151, v148 offset:4624
	v_fmac_f32_e32 v24, v116, v25
	v_fmac_f32_e32 v40, v118, v41
	v_fmac_f32_dpp v24, v25, v122 quad_perm:[1,0,3,2] row_mask:0xf bank_mask:0xf
	v_fmac_f32_dpp v40, v41, v123 quad_perm:[1,0,3,2] row_mask:0xf bank_mask:0xf
	v_cvt_pk_bf16_f32 v149, v24, v40
	ds_write_b32 v151, v149 offset:4352
	v_fmac_f32_e32 v55, v116, v24
	v_fmac_f32_e32 v71, v118, v40
	v_fmac_f32_dpp v55, v24, v122 quad_perm:[1,0,3,2] row_mask:0xf bank_mask:0xf
	v_fmac_f32_dpp v71, v40, v123 quad_perm:[1,0,3,2] row_mask:0xf bank_mask:0xf
	v_cvt_pk_bf16_f32 v148, v55, v71
	ds_write_b32 v151, v148 offset:4080
	v_fmac_f32_e32 v54, v116, v55
	v_fmac_f32_e32 v70, v118, v71
	v_fmac_f32_dpp v54, v55, v122 quad_perm:[1,0,3,2] row_mask:0xf bank_mask:0xf
	v_fmac_f32_dpp v70, v71, v123 quad_perm:[1,0,3,2] row_mask:0xf bank_mask:0xf
	v_cvt_pk_bf16_f32 v149, v54, v70
	ds_write_b32 v151, v149 offset:3808
	v_fmac_f32_e32 v53, v116, v54
	v_fmac_f32_e32 v69, v118, v70
	v_fmac_f32_dpp v53, v54, v122 quad_perm:[1,0,3,2] row_mask:0xf bank_mask:0xf
	v_fmac_f32_dpp v69, v70, v123 quad_perm:[1,0,3,2] row_mask:0xf bank_mask:0xf
	v_cvt_pk_bf16_f32 v148, v53, v69
	ds_write_b32 v151, v148 offset:3536
	v_fmac_f32_e32 v52, v116, v53
	v_fmac_f32_e32 v68, v118, v69
	v_fmac_f32_dpp v52, v53, v122 quad_perm:[1,0,3,2] row_mask:0xf bank_mask:0xf
	v_fmac_f32_dpp v68, v69, v123 quad_perm:[1,0,3,2] row_mask:0xf bank_mask:0xf
	v_cvt_pk_bf16_f32 v149, v52, v68
	ds_write_b32 v151, v149 offset:3264
	v_fmac_f32_e32 v23, v116, v52
	v_fmac_f32_e32 v39, v118, v68
	v_fmac_f32_dpp v23, v52, v122 quad_perm:[1,0,3,2] row_mask:0xf bank_mask:0xf
	v_fmac_f32_dpp v39, v68, v123 quad_perm:[1,0,3,2] row_mask:0xf bank_mask:0xf
	v_cvt_pk_bf16_f32 v148, v23, v39
	ds_write_b32 v151, v148 offset:2992
	v_fmac_f32_e32 v22, v116, v23
	v_fmac_f32_e32 v38, v118, v39
	v_fmac_f32_dpp v22, v23, v122 quad_perm:[1,0,3,2] row_mask:0xf bank_mask:0xf
	v_fmac_f32_dpp v38, v39, v123 quad_perm:[1,0,3,2] row_mask:0xf bank_mask:0xf
	v_cvt_pk_bf16_f32 v149, v22, v38
	ds_write_b32 v151, v149 offset:2720
	v_fmac_f32_e32 v21, v116, v22
	v_fmac_f32_e32 v37, v118, v38
	v_fmac_f32_dpp v21, v22, v122 quad_perm:[1,0,3,2] row_mask:0xf bank_mask:0xf
	v_fmac_f32_dpp v37, v38, v123 quad_perm:[1,0,3,2] row_mask:0xf bank_mask:0xf
	v_cvt_pk_bf16_f32 v148, v21, v37
	ds_write_b32 v151, v148 offset:2448
	v_fmac_f32_e32 v20, v116, v21
	v_fmac_f32_e32 v36, v118, v37
	v_fmac_f32_dpp v20, v21, v122 quad_perm:[1,0,3,2] row_mask:0xf bank_mask:0xf
	v_fmac_f32_dpp v36, v37, v123 quad_perm:[1,0,3,2] row_mask:0xf bank_mask:0xf
	v_cvt_pk_bf16_f32 v149, v20, v36
	ds_write_b32 v151, v149 offset:2176
	v_fmac_f32_e32 v51, v116, v20
	v_fmac_f32_e32 v67, v118, v36
	v_fmac_f32_dpp v51, v20, v122 quad_perm:[1,0,3,2] row_mask:0xf bank_mask:0xf
	v_fmac_f32_dpp v67, v36, v123 quad_perm:[1,0,3,2] row_mask:0xf bank_mask:0xf
	v_cvt_pk_bf16_f32 v148, v51, v67
	ds_write_b32 v151, v148 offset:1904
	v_fmac_f32_e32 v50, v116, v51
	v_fmac_f32_e32 v66, v118, v67
	v_fmac_f32_dpp v50, v51, v122 quad_perm:[1,0,3,2] row_mask:0xf bank_mask:0xf
	v_fmac_f32_dpp v66, v67, v123 quad_perm:[1,0,3,2] row_mask:0xf bank_mask:0xf
	v_cvt_pk_bf16_f32 v149, v50, v66
	ds_write_b32 v151, v149 offset:1632
	v_fmac_f32_e32 v49, v116, v50
	v_fmac_f32_e32 v65, v118, v66
	v_fmac_f32_dpp v49, v50, v122 quad_perm:[1,0,3,2] row_mask:0xf bank_mask:0xf
	v_fmac_f32_dpp v65, v66, v123 quad_perm:[1,0,3,2] row_mask:0xf bank_mask:0xf
	v_cvt_pk_bf16_f32 v148, v49, v65
	ds_write_b32 v151, v148 offset:1360
	v_fmac_f32_e32 v48, v116, v49
	v_fmac_f32_e32 v64, v118, v65
	v_fmac_f32_dpp v48, v49, v122 quad_perm:[1,0,3,2] row_mask:0xf bank_mask:0xf
	v_fmac_f32_dpp v64, v65, v123 quad_perm:[1,0,3,2] row_mask:0xf bank_mask:0xf
	v_cvt_pk_bf16_f32 v149, v48, v64
	ds_write_b32 v151, v149 offset:1088
	v_fmac_f32_e32 v19, v116, v48
	v_fmac_f32_e32 v35, v118, v64
	v_fmac_f32_dpp v19, v48, v122 quad_perm:[1,0,3,2] row_mask:0xf bank_mask:0xf
	v_fmac_f32_dpp v35, v64, v123 quad_perm:[1,0,3,2] row_mask:0xf bank_mask:0xf
	v_cvt_pk_bf16_f32 v148, v19, v35
	ds_write_b32 v151, v148 offset:816
	v_fmac_f32_e32 v18, v116, v19
	v_fmac_f32_e32 v34, v118, v35
	v_fmac_f32_dpp v18, v19, v122 quad_perm:[1,0,3,2] row_mask:0xf bank_mask:0xf
	v_fmac_f32_dpp v34, v35, v123 quad_perm:[1,0,3,2] row_mask:0xf bank_mask:0xf
	v_cvt_pk_bf16_f32 v149, v18, v34
	ds_write_b32 v151, v149 offset:544
	v_fmac_f32_e32 v17, v116, v18
	v_fmac_f32_e32 v33, v118, v34
	v_fmac_f32_dpp v17, v18, v122 quad_perm:[1,0,3,2] row_mask:0xf bank_mask:0xf
	v_fmac_f32_dpp v33, v34, v123 quad_perm:[1,0,3,2] row_mask:0xf bank_mask:0xf
	v_cvt_pk_bf16_f32 v148, v17, v33
	ds_write_b32 v151, v148 offset:272
	v_fmac_f32_e32 v16, v116, v17
	v_fmac_f32_e32 v32, v118, v33
	v_fmac_f32_dpp v16, v17, v122 quad_perm:[1,0,3,2] row_mask:0xf bank_mask:0xf
	v_fmac_f32_dpp v32, v33, v123 quad_perm:[1,0,3,2] row_mask:0xf bank_mask:0xf
	v_cvt_pk_bf16_f32 v149, v16, v32
	ds_write_b32 v151, v149
	v_mov_b32_e32 v120, v16
	v_mov_b32_e32 v121, v32
	ds_read_b128 v[124:127], v152
	ds_read_b128 v[128:131], v152 offset:64
	ds_read_b128 v[132:135], v152 offset:128
	ds_read_b128 v[136:139], v152 offset:192
	ds_read_b64 v[160:161], v163
	s_waitcnt lgkmcnt(4)
	v_mfma_f32_16x16x32_bf16 v[140:143], v[100:103], v[124:127], 0
	s_waitcnt lgkmcnt(3)
	v_mfma_f32_16x16x32_bf16 v[140:143], v[104:107], v[128:131], v[140:143]
	s_waitcnt lgkmcnt(2)
	v_mfma_f32_16x16x32_bf16 v[140:143], v[108:111], v[132:135], v[140:143]
	s_waitcnt lgkmcnt(1)
	v_mfma_f32_16x16x32_bf16 v[140:143], v[112:115], v[136:139], v[140:143]
	s_nop 9
	s_waitcnt vmcnt(7) lgkmcnt(0)
	v_add_f32_e32 v182, v172, v140
	v_add_f32_e32 v183, v173, v141
	v_add_f32_e32 v184, v174, v142
	v_add_f32_e32 v185, v175, v143
	v_lshlrev_b32_e32 v186, 16, v160
	v_and_b32_e32 v187, 0xffff0000, v160
	v_lshlrev_b32_e32 v188, 16, v161
	v_and_b32_e32 v189, 0xffff0000, v161
	v_fmac_f32_e32 v182, v164, v186
	v_fmac_f32_e32 v183, v165, v187
	v_fmac_f32_e32 v184, v166, v188
	v_fmac_f32_e32 v185, v167, v189
	v_mul_f32_e32 v186, 0x3d372713, v182
	v_mul_f32_e32 v187, 0x3d372713, v183
	v_mul_f32_e32 v188, 0x3d372713, v184
	v_mul_f32_e32 v189, 0x3d372713, v185
	v_mul_f32_e32 v186, v182, v186
	v_mul_f32_e32 v187, v183, v187
	v_mul_f32_e32 v188, v184, v188
	v_mul_f32_e32 v189, v185, v189
	v_fma_f32 v186, v182, v186, v182
	v_fma_f32 v187, v183, v187, v183
	v_fma_f32 v188, v184, v188, v184
	v_fma_f32 v189, v185, v189, v185
	v_mul_f32_e32 v186, 0xbfcc422a, v186
	v_mul_f32_e32 v187, 0xbfcc422a, v187
	v_mul_f32_e32 v188, 0xbfcc422a, v188
	v_mul_f32_e32 v189, 0xbfcc422a, v189
	v_mul_f32_e32 v186, 0x3fb8aa3b, v186
	v_mul_f32_e32 v187, 0x3fb8aa3b, v187
	v_mul_f32_e32 v188, 0x3fb8aa3b, v188
	v_mul_f32_e32 v189, 0x3fb8aa3b, v189
	v_exp_f32_e32 v186, v186
	v_exp_f32_e32 v187, v187
	v_exp_f32_e32 v188, v188
	v_exp_f32_e32 v189, v189
	v_add_f32_e32 v186, 1.0, v186
	v_add_f32_e32 v187, 1.0, v187
	v_add_f32_e32 v188, 1.0, v188
	v_add_f32_e32 v189, 1.0, v189
	v_rcp_f32_e32 v186, v186
	v_rcp_f32_e32 v187, v187
	v_rcp_f32_e32 v188, v188
	v_rcp_f32_e32 v189, v189
	v_mul_f32_e32 v182, v182, v186
	v_mul_f32_e32 v183, v183, v187
	v_mul_f32_e32 v184, v184, v188
	v_mul_f32_e32 v185, v185, v189
	v_cvt_pk_bf16_f32 v148, v182, v183
	v_cvt_pk_bf16_f32 v149, v184, v185
	global_store_dwordx2 v156, v[148:149], s[12:13]
	ds_read_b128 v[124:127], v152 offset:4352
	ds_read_b128 v[128:131], v152 offset:4416
	ds_read_b128 v[132:135], v152 offset:4480
	ds_read_b128 v[136:139], v152 offset:4544
	ds_read_b64 v[160:161], v163 offset:512
	s_waitcnt lgkmcnt(4)
	v_mfma_f32_16x16x32_bf16 v[140:143], v[100:103], v[124:127], 0
	s_waitcnt lgkmcnt(3)
	v_mfma_f32_16x16x32_bf16 v[140:143], v[104:107], v[128:131], v[140:143]
	s_waitcnt lgkmcnt(2)
	v_mfma_f32_16x16x32_bf16 v[140:143], v[108:111], v[132:135], v[140:143]
	s_waitcnt lgkmcnt(1)
	v_mfma_f32_16x16x32_bf16 v[140:143], v[112:115], v[136:139], v[140:143]
	s_nop 9
	s_waitcnt vmcnt(7) lgkmcnt(0)
	v_add_f32_e32 v182, v176, v140
	v_add_f32_e32 v183, v177, v141
	v_add_f32_e32 v184, v178, v142
	v_add_f32_e32 v185, v179, v143
	v_lshlrev_b32_e32 v186, 16, v160
	v_and_b32_e32 v187, 0xffff0000, v160
	v_lshlrev_b32_e32 v188, 16, v161
	v_and_b32_e32 v189, 0xffff0000, v161
	v_fmac_f32_e32 v182, v164, v186
	v_fmac_f32_e32 v183, v165, v187
	v_fmac_f32_e32 v184, v166, v188
	v_fmac_f32_e32 v185, v167, v189
	v_mul_f32_e32 v186, 0x3d372713, v182
	v_mul_f32_e32 v187, 0x3d372713, v183
	v_mul_f32_e32 v188, 0x3d372713, v184
	v_mul_f32_e32 v189, 0x3d372713, v185
	v_mul_f32_e32 v186, v182, v186
	v_mul_f32_e32 v187, v183, v187
	v_mul_f32_e32 v188, v184, v188
	v_mul_f32_e32 v189, v185, v189
	v_fma_f32 v186, v182, v186, v182
	v_fma_f32 v187, v183, v187, v183
	v_fma_f32 v188, v184, v188, v184
	v_fma_f32 v189, v185, v189, v185
	v_mul_f32_e32 v186, 0xbfcc422a, v186
	v_mul_f32_e32 v187, 0xbfcc422a, v187
	v_mul_f32_e32 v188, 0xbfcc422a, v188
	v_mul_f32_e32 v189, 0xbfcc422a, v189
	v_mul_f32_e32 v186, 0x3fb8aa3b, v186
	v_mul_f32_e32 v187, 0x3fb8aa3b, v187
	v_mul_f32_e32 v188, 0x3fb8aa3b, v188
	v_mul_f32_e32 v189, 0x3fb8aa3b, v189
	v_exp_f32_e32 v186, v186
	v_exp_f32_e32 v187, v187
	v_exp_f32_e32 v188, v188
	v_exp_f32_e32 v189, v189
	v_add_f32_e32 v186, 1.0, v186
	v_add_f32_e32 v187, 1.0, v187
	v_add_f32_e32 v188, 1.0, v188
	v_add_f32_e32 v189, 1.0, v189
	v_rcp_f32_e32 v186, v186
	v_rcp_f32_e32 v187, v187
	v_rcp_f32_e32 v188, v188
	v_rcp_f32_e32 v189, v189
	v_mul_f32_e32 v182, v182, v186
	v_mul_f32_e32 v183, v183, v187
	v_mul_f32_e32 v184, v184, v188
	v_mul_f32_e32 v185, v185, v189
	v_cvt_pk_bf16_f32 v148, v182, v183
	v_cvt_pk_bf16_f32 v149, v184, v185
	global_store_dwordx2 v159, v[148:149], s[12:13]
	s_sub_u32 s12, s12, 65536
	s_subb_u32 s13, s13, 0
	s_add_u32 s14, s14, 2
	s_cmp_lt_u32 s14, 32
	s_cbranch_scc1 .Lssm_tileB_d1m0
	s_waitcnt vmcnt(0) lgkmcnt(0)

.Lssm_ctx_loop:
	s_lshl_b32 s22, s2, 3
	s_sub_u32 s21, s89, 4
	s_add_u32 s22, s22, s21
	s_lshl_b32 s21, s27, 2
	s_add_u32 s22, s22, s21
	s_lshr_b32 s23, s22, 6
	s_and_b32 s24, s22, 63
	s_lshl_b32 s25, s23, 8
	s_add_u32 s28, s24, 0
	s_lshl_b32 s29, s28, 13
	s_add_u32 s29, s29, 0x200000
	s_add_u32 s10, s62, s29
	s_addc_u32 s11, s63, 0
	global_load_dwordx4 v[84:87], v177, s[10:11]
	global_load_dwordx4 v[88:91], v177, s[10:11] offset:2048
	s_add_u32 s12, s10, 0x1000
	s_addc_u32 s13, s11, 0
	global_load_dwordx4 v[92:95], v177, s[12:13]
	global_load_dwordx4 v[96:99], v177, s[12:13] offset:2048
	s_lshl_b32 s29, s28, 12
	s_add_u32 s29, s29, 0x300000
	s_add_u32 s16, s62, s29
	s_addc_u32 s17, s63, 0
	global_load_dwordx2 v[2:3], v178, s[16:17]
	global_load_dwordx2 v[4:5], v178, s[16:17] offset:1024
	global_load_dwordx2 v[6:7], v178, s[16:17] offset:512
	global_load_dwordx2 v[8:9], v178, s[16:17] offset:1536
	global_load_dwordx2 v[10:11], v178, s[16:17] offset:2048
	global_load_dwordx2 v[12:13], v178, s[16:17] offset:3072
	global_load_dwordx2 v[14:15], v178, s[16:17] offset:2560
	global_load_dwordx2 v[16:17], v178, s[16:17] offset:3584
	s_lshl_b32 s29, s28, 9
	s_add_u32 s29, s29, 0x100000
	s_add_u32 s18, s62, s29
	s_addc_u32 s19, s63, 0
	global_load_dwordx2 v[116:117], v179, s[18:19]
	global_load_dwordx2 v[118:119], v179, s[18:19] offset:128
	s_lshl_b32 s30, s23, 1
	s_lshl_b32 s30, s30, 15
	s_lshl_b32 s31, s24, 8
	s_add_u32 s30, s30, s31
	v_mov_b32_e32 v120, 0
	v_mov_b32_e32 v121, 0
	s_lshl_b32 s31, s25, 5
	s_lshl_b32 s29, s24, 19
	s_add_u32 s31, s31, s29
	s_add_u32 s31, s31, 0x16800000
	s_add_u32 s4, s62, s31
	s_addc_u32 s5, s63, 0
	s_add_u32 s34, s4, 0
	s_addc_u32 s35, s5, 0
	global_load_dwordx4 v[80:83], v150, s[34:35]
	s_mov_b64 s[10:11], s[34:35]
	s_add_u32 s10, s10, 1024
	s_addc_u32 s11, s11, 0
	global_load_dwordx4 v[144:147], v150, s[10:11]
	s_mov_b64 s[34:35], s[10:11]
	s_add_u32 s10, s10, 1024
	s_addc_u32 s11, s11, 0
	s_mov_b32 s36, 0
	s_mov_b32 s14, 0
	s_mov_b32 s40, 0xffff0000
	s_waitcnt vmcnt(0)
	v_and_b32_e32 v182, 0xffff, v2
	v_lshrrev_b32_e32 v183, 16, v2
	v_and_b32_e32 v184, 0xffff, v3
	v_lshrrev_b32_e32 v185, 16, v3
	v_lshl_or_b32 v100, v4, 16, v182
	v_and_or_b32 v101, v4, s40, v183
	v_lshl_or_b32 v102, v5, 16, v184
	v_and_or_b32 v103, v5, s40, v185
	v_and_b32_e32 v182, 0xffff, v6
	v_lshrrev_b32_e32 v183, 16, v6
	v_and_b32_e32 v184, 0xffff, v7
	v_lshrrev_b32_e32 v185, 16, v7
	v_lshl_or_b32 v104, v8, 16, v182
	v_and_or_b32 v105, v8, s40, v183
	v_lshl_or_b32 v106, v9, 16, v184
	v_and_or_b32 v107, v9, s40, v185
	v_and_b32_e32 v182, 0xffff, v10
	v_lshrrev_b32_e32 v183, 16, v10
	v_and_b32_e32 v184, 0xffff, v11
	v_lshrrev_b32_e32 v185, 16, v11
	v_lshl_or_b32 v108, v12, 16, v182
	v_and_or_b32 v109, v12, s40, v183
	v_lshl_or_b32 v110, v13, 16, v184
	v_and_or_b32 v111, v13, s40, v185
	v_and_b32_e32 v182, 0xffff, v14
	v_lshrrev_b32_e32 v183, 16, v14
	v_and_b32_e32 v184, 0xffff, v15
	v_lshrrev_b32_e32 v185, 16, v15
	v_lshl_or_b32 v112, v16, 16, v182
	v_and_or_b32 v113, v16, s40, v183
	v_lshl_or_b32 v114, v17, 16, v184
	v_and_or_b32 v115, v17, s40, v185
	v_cmp_eq_u32_e32 vcc, 1, v174
	v_xor_b32_e32 v182, 0x80000000, v117
	v_xor_b32_e32 v183, 0x80000000, v119
	s_nop 1
	v_cndmask_b32_e32 v122, v182, v117, vcc
	v_cndmask_b32_e32 v123, v183, v119, vcc
.Lssm_tile_d0m1:
	s_waitcnt vmcnt(1)
	v_mfma_f32_32x32x16_bf16 v[16:31], v[80:83], v[84:87], 0
	v_mfma_f32_32x32x16_bf16 v[32:47], v[80:83], v[88:91], 0
	v_mfma_f32_32x32x16_bf16 v[48:63], v[80:83], v[92:95], 0
	v_mfma_f32_32x32x16_bf16 v[64:79], v[80:83], v[96:99], 0
	v_add_u32_e32 v171, s36, v155
	s_nop 11
	global_load_dwordx4 v[80:83], v150, s[10:11]
	s_add_u32 s34, s34, 1024
	s_addc_u32 s35, s35, 0
	s_add_u32 s10, s10, 1024
	s_addc_u32 s11, s11, 0
	v_permlane32_swap_b32_e32 v16, v48
	v_permlane32_swap_b32_e32 v17, v49
	v_permlane32_swap_b32_e32 v18, v50
	v_permlane32_swap_b32_e32 v19, v51
	v_permlane32_swap_b32_e32 v20, v52
	v_permlane32_swap_b32_e32 v21, v53
	v_permlane32_swap_b32_e32 v22, v54
	v_permlane32_swap_b32_e32 v23, v55
	v_permlane32_swap_b32_e32 v24, v56
	v_permlane32_swap_b32_e32 v25, v57
	v_permlane32_swap_b32_e32 v26, v58
	v_permlane32_swap_b32_e32 v27, v59
	v_permlane32_swap_b32_e32 v28, v60
	v_permlane32_swap_b32_e32 v29, v61
	v_permlane32_swap_b32_e32 v30, v62
	v_permlane32_swap_b32_e32 v31, v63
	v_permlane32_swap_b32_e32 v32, v64
	v_permlane32_swap_b32_e32 v33, v65
	v_permlane32_swap_b32_e32 v34, v66
	v_permlane32_swap_b32_e32 v35, v67
	v_permlane32_swap_b32_e32 v36, v68
	v_permlane32_swap_b32_e32 v37, v69
	v_permlane32_swap_b32_e32 v38, v70
	v_permlane32_swap_b32_e32 v39, v71
	v_permlane32_swap_b32_e32 v40, v72
	v_permlane32_swap_b32_e32 v41, v73
	v_permlane32_swap_b32_e32 v42, v74
	v_permlane32_swap_b32_e32 v43, v75
	v_permlane32_swap_b32_e32 v44, v76
	v_permlane32_swap_b32_e32 v45, v77
	v_permlane32_swap_b32_e32 v46, v78
	v_permlane32_swap_b32_e32 v47, v79
	v_fmac_f32_e32 v16, v116, v120
	v_fmac_f32_e32 v32, v118, v121
	v_fmac_f32_dpp v16, v120, v122 quad_perm:[1,0,3,2] row_mask:0xf bank_mask:0xf
	v_fmac_f32_dpp v32, v121, v123 quad_perm:[1,0,3,2] row_mask:0xf bank_mask:0xf
	v_cvt_pk_bf16_f32 v148, v16, v32
	ds_write_b32 v151, v148
	v_fmac_f32_e32 v17, v116, v16
	v_fmac_f32_e32 v33, v118, v32
	v_fmac_f32_dpp v17, v16, v122 quad_perm:[1,0,3,2] row_mask:0xf bank_mask:0xf
	v_fmac_f32_dpp v33, v32, v123 quad_perm:[1,0,3,2] row_mask:0xf bank_mask:0xf
	v_cvt_pk_bf16_f32 v149, v17, v33
	ds_write_b32 v151, v149 offset:272
	v_fmac_f32_e32 v18, v116, v17
	v_fmac_f32_e32 v34, v118, v33
	v_fmac_f32_dpp v18, v17, v122 quad_perm:[1,0,3,2] row_mask:0xf bank_mask:0xf
	v_fmac_f32_dpp v34, v33, v123 quad_perm:[1,0,3,2] row_mask:0xf bank_mask:0xf
	v_cvt_pk_bf16_f32 v148, v18, v34
	ds_write_b32 v151, v148 offset:544
	v_fmac_f32_e32 v19, v116, v18
	v_fmac_f32_e32 v35, v118, v34
	v_fmac_f32_dpp v19, v18, v122 quad_perm:[1,0,3,2] row_mask:0xf bank_mask:0xf
	v_fmac_f32_dpp v35, v34, v123 quad_perm:[1,0,3,2] row_mask:0xf bank_mask:0xf
	v_cvt_pk_bf16_f32 v149, v19, v35
	ds_write_b32 v151, v149 offset:816
	v_fmac_f32_e32 v48, v116, v19
	v_fmac_f32_e32 v64, v118, v35
	v_fmac_f32_dpp v48, v19, v122 quad_perm:[1,0,3,2] row_mask:0xf bank_mask:0xf
	v_fmac_f32_dpp v64, v35, v123 quad_perm:[1,0,3,2] row_mask:0xf bank_mask:0xf
	v_cvt_pk_bf16_f32 v148, v48, v64
	ds_write_b32 v151, v148 offset:1088
	v_fmac_f32_e32 v49, v116, v48
	v_fmac_f32_e32 v65, v118, v64
	v_fmac_f32_dpp v49, v48, v122 quad_perm:[1,0,3,2] row_mask:0xf bank_mask:0xf
	v_fmac_f32_dpp v65, v64, v123 quad_perm:[1,0,3,2] row_mask:0xf bank_mask:0xf
	v_cvt_pk_bf16_f32 v149, v49, v65
	ds_write_b32 v151, v149 offset:1360
	v_fmac_f32_e32 v50, v116, v49
	v_fmac_f32_e32 v66, v118, v65
	v_fmac_f32_dpp v50, v49, v122 quad_perm:[1,0,3,2] row_mask:0xf bank_mask:0xf
	v_fmac_f32_dpp v66, v65, v123 quad_perm:[1,0,3,2] row_mask:0xf bank_mask:0xf
	v_cvt_pk_bf16_f32 v148, v50, v66
	ds_write_b32 v151, v148 offset:1632
	v_fmac_f32_e32 v51, v116, v50
	v_fmac_f32_e32 v67, v118, v66
	v_fmac_f32_dpp v51, v50, v122 quad_perm:[1,0,3,2] row_mask:0xf bank_mask:0xf
	v_fmac_f32_dpp v67, v66, v123 quad_perm:[1,0,3,2] row_mask:0xf bank_mask:0xf
	v_cvt_pk_bf16_f32 v149, v51, v67
	ds_write_b32 v151, v149 offset:1904
	v_fmac_f32_e32 v20, v116, v51
	v_fmac_f32_e32 v36, v118, v67
	v_fmac_f32_dpp v20, v51, v122 quad_perm:[1,0,3,2] row_mask:0xf bank_mask:0xf
	v_fmac_f32_dpp v36, v67, v123 quad_perm:[1,0,3,2] row_mask:0xf bank_mask:0xf
	v_cvt_pk_bf16_f32 v148, v20, v36
	ds_write_b32 v151, v148 offset:2176
	v_fmac_f32_e32 v21, v116, v20
	v_fmac_f32_e32 v37, v118, v36
	v_fmac_f32_dpp v21, v20, v122 quad_perm:[1,0,3,2] row_mask:0xf bank_mask:0xf
	v_fmac_f32_dpp v37, v36, v123 quad_perm:[1,0,3,2] row_mask:0xf bank_mask:0xf
	v_cvt_pk_bf16_f32 v149, v21, v37
	ds_write_b32 v151, v149 offset:2448
	v_fmac_f32_e32 v22, v116, v21
	v_fmac_f32_e32 v38, v118, v37
	v_fmac_f32_dpp v22, v21, v122 quad_perm:[1,0,3,2] row_mask:0xf bank_mask:0xf
	v_fmac_f32_dpp v38, v37, v123 quad_perm:[1,0,3,2] row_mask:0xf bank_mask:0xf
	v_cvt_pk_bf16_f32 v148, v22, v38
	ds_write_b32 v151, v148 offset:2720
	v_fmac_f32_e32 v23, v116, v22
	v_fmac_f32_e32 v39, v118, v38
	v_fmac_f32_dpp v23, v22, v122 quad_perm:[1,0,3,2] row_mask:0xf bank_mask:0xf
	v_fmac_f32_dpp v39, v38, v123 quad_perm:[1,0,3,2] row_mask:0xf bank_mask:0xf
	v_cvt_pk_bf16_f32 v149, v23, v39
	ds_write_b32 v151, v149 offset:2992
	v_fmac_f32_e32 v52, v116, v23
	v_fmac_f32_e32 v68, v118, v39
	v_fmac_f32_dpp v52, v23, v122 quad_perm:[1,0,3,2] row_mask:0xf bank_mask:0xf
	v_fmac_f32_dpp v68, v39, v123 quad_perm:[1,0,3,2] row_mask:0xf bank_mask:0xf
	v_cvt_pk_bf16_f32 v148, v52, v68
	ds_write_b32 v151, v148 offset:3264
	v_fmac_f32_e32 v53, v116, v52
	v_fmac_f32_e32 v69, v118, v68
	v_fmac_f32_dpp v53, v52, v122 quad_perm:[1,0,3,2] row_mask:0xf bank_mask:0xf
	v_fmac_f32_dpp v69, v68, v123 quad_perm:[1,0,3,2] row_mask:0xf bank_mask:0xf
	v_cvt_pk_bf16_f32 v149, v53, v69
	ds_write_b32 v151, v149 offset:3536
	v_fmac_f32_e32 v54, v116, v53
	v_fmac_f32_e32 v70, v118, v69
	v_fmac_f32_dpp v54, v53, v122 quad_perm:[1,0,3,2] row_mask:0xf bank_mask:0xf
	v_fmac_f32_dpp v70, v69, v123 quad_perm:[1,0,3,2] row_mask:0xf bank_mask:0xf
	v_cvt_pk_bf16_f32 v148, v54, v70
	ds_write_b32 v151, v148 offset:3808
	v_fmac_f32_e32 v55, v116, v54
	v_fmac_f32_e32 v71, v118, v70
	v_fmac_f32_dpp v55, v54, v122 quad_perm:[1,0,3,2] row_mask:0xf bank_mask:0xf
	v_fmac_f32_dpp v71, v70, v123 quad_perm:[1,0,3,2] row_mask:0xf bank_mask:0xf
	v_cvt_pk_bf16_f32 v149, v55, v71
	ds_write_b32 v151, v149 offset:4080
	v_fmac_f32_e32 v24, v116, v55
	v_fmac_f32_e32 v40, v118, v71
	v_fmac_f32_dpp v24, v55, v122 quad_perm:[1,0,3,2] row_mask:0xf bank_mask:0xf
	v_fmac_f32_dpp v40, v71, v123 quad_perm:[1,0,3,2] row_mask:0xf bank_mask:0xf
	v_cvt_pk_bf16_f32 v148, v24, v40
	ds_write_b32 v151, v148 offset:4352
	v_fmac_f32_e32 v25, v116, v24
	v_fmac_f32_e32 v41, v118, v40
	v_fmac_f32_dpp v25, v24, v122 quad_perm:[1,0,3,2] row_mask:0xf bank_mask:0xf
	v_fmac_f32_dpp v41, v40, v123 quad_perm:[1,0,3,2] row_mask:0xf bank_mask:0xf
	v_cvt_pk_bf16_f32 v149, v25, v41
	ds_write_b32 v151, v149 offset:4624
	v_fmac_f32_e32 v26, v116, v25
	v_fmac_f32_e32 v42, v118, v41
	v_fmac_f32_dpp v26, v25, v122 quad_perm:[1,0,3,2] row_mask:0xf bank_mask:0xf
	v_fmac_f32_dpp v42, v41, v123 quad_perm:[1,0,3,2] row_mask:0xf bank_mask:0xf
	v_cvt_pk_bf16_f32 v148, v26, v42
	ds_write_b32 v151, v148 offset:4896
	v_fmac_f32_e32 v27, v116, v26
	v_fmac_f32_e32 v43, v118, v42
	v_fmac_f32_dpp v27, v26, v122 quad_perm:[1,0,3,2] row_mask:0xf bank_mask:0xf
	v_fmac_f32_dpp v43, v42, v123 quad_perm:[1,0,3,2] row_mask:0xf bank_mask:0xf
	v_cvt_pk_bf16_f32 v149, v27, v43
	ds_write_b32 v151, v149 offset:5168
	v_fmac_f32_e32 v56, v116, v27
	v_fmac_f32_e32 v72, v118, v43
	v_fmac_f32_dpp v56, v27, v122 quad_perm:[1,0,3,2] row_mask:0xf bank_mask:0xf
	v_fmac_f32_dpp v72, v43, v123 quad_perm:[1,0,3,2] row_mask:0xf bank_mask:0xf
	v_cvt_pk_bf16_f32 v148, v56, v72
	ds_write_b32 v151, v148 offset:5440
	v_fmac_f32_e32 v57, v116, v56
	v_fmac_f32_e32 v73, v118, v72
	v_fmac_f32_dpp v57, v56, v122 quad_perm:[1,0,3,2] row_mask:0xf bank_mask:0xf
	v_fmac_f32_dpp v73, v72, v123 quad_perm:[1,0,3,2] row_mask:0xf bank_mask:0xf
	v_cvt_pk_bf16_f32 v149, v57, v73
	ds_write_b32 v151, v149 offset:5712
	v_fmac_f32_e32 v58, v116, v57
	v_fmac_f32_e32 v74, v118, v73
	v_fmac_f32_dpp v58, v57, v122 quad_perm:[1,0,3,2] row_mask:0xf bank_mask:0xf
	v_fmac_f32_dpp v74, v73, v123 quad_perm:[1,0,3,2] row_mask:0xf bank_mask:0xf
	v_cvt_pk_bf16_f32 v148, v58, v74
	ds_write_b32 v151, v148 offset:5984
	v_fmac_f32_e32 v59, v116, v58
	v_fmac_f32_e32 v75, v118, v74
	v_fmac_f32_dpp v59, v58, v122 quad_perm:[1,0,3,2] row_mask:0xf bank_mask:0xf
	v_fmac_f32_dpp v75, v74, v123 quad_perm:[1,0,3,2] row_mask:0xf bank_mask:0xf
	v_cvt_pk_bf16_f32 v149, v59, v75
	ds_write_b32 v151, v149 offset:6256
	v_fmac_f32_e32 v28, v116, v59
	v_fmac_f32_e32 v44, v118, v75
	v_fmac_f32_dpp v28, v59, v122 quad_perm:[1,0,3,2] row_mask:0xf bank_mask:0xf
	v_fmac_f32_dpp v44, v75, v123 quad_perm:[1,0,3,2] row_mask:0xf bank_mask:0xf
	v_cvt_pk_bf16_f32 v148, v28, v44
	ds_write_b32 v151, v148 offset:6528
	v_fmac_f32_e32 v29, v116, v28
	v_fmac_f32_e32 v45, v118, v44
	v_fmac_f32_dpp v29, v28, v122 quad_perm:[1,0,3,2] row_mask:0xf bank_mask:0xf
	v_fmac_f32_dpp v45, v44, v123 quad_perm:[1,0,3,2] row_mask:0xf bank_mask:0xf
	v_cvt_pk_bf16_f32 v149, v29, v45
	ds_write_b32 v151, v149 offset:6800
	v_fmac_f32_e32 v30, v116, v29
	v_fmac_f32_e32 v46, v118, v45
	v_fmac_f32_dpp v30, v29, v122 quad_perm:[1,0,3,2] row_mask:0xf bank_mask:0xf
	v_fmac_f32_dpp v46, v45, v123 quad_perm:[1,0,3,2] row_mask:0xf bank_mask:0xf
	v_cvt_pk_bf16_f32 v148, v30, v46
	ds_write_b32 v151, v148 offset:7072
	v_fmac_f32_e32 v31, v116, v30
	v_fmac_f32_e32 v47, v118, v46
	v_fmac_f32_dpp v31, v30, v122 quad_perm:[1,0,3,2] row_mask:0xf bank_mask:0xf
	v_fmac_f32_dpp v47, v46, v123 quad_perm:[1,0,3,2] row_mask:0xf bank_mask:0xf
	v_cvt_pk_bf16_f32 v149, v31, v47
	ds_write_b32 v151, v149 offset:7344
	v_fmac_f32_e32 v60, v116, v31
	v_fmac_f32_e32 v76, v118, v47
	v_fmac_f32_dpp v60, v31, v122 quad_perm:[1,0,3,2] row_mask:0xf bank_mask:0xf
	v_fmac_f32_dpp v76, v47, v123 quad_perm:[1,0,3,2] row_mask:0xf bank_mask:0xf
	v_cvt_pk_bf16_f32 v148, v60, v76
	ds_write_b32 v151, v148 offset:7616
	v_fmac_f32_e32 v61, v116, v60
	v_fmac_f32_e32 v77, v118, v76
	v_fmac_f32_dpp v61, v60, v122 quad_perm:[1,0,3,2] row_mask:0xf bank_mask:0xf
	v_fmac_f32_dpp v77, v76, v123 quad_perm:[1,0,3,2] row_mask:0xf bank_mask:0xf
	v_cvt_pk_bf16_f32 v149, v61, v77
	ds_write_b32 v151, v149 offset:7888
	v_fmac_f32_e32 v62, v116, v61
	v_fmac_f32_e32 v78, v118, v77
	v_fmac_f32_dpp v62, v61, v122 quad_perm:[1,0,3,2] row_mask:0xf bank_mask:0xf
	v_fmac_f32_dpp v78, v77, v123 quad_perm:[1,0,3,2] row_mask:0xf bank_mask:0xf
	v_cvt_pk_bf16_f32 v148, v62, v78
	ds_write_b32 v151, v148 offset:8160
	v_fmac_f32_e32 v63, v116, v62
	v_fmac_f32_e32 v79, v118, v78
	v_fmac_f32_dpp v63, v62, v122 quad_perm:[1,0,3,2] row_mask:0xf bank_mask:0xf
	v_fmac_f32_dpp v79, v78, v123 quad_perm:[1,0,3,2] row_mask:0xf bank_mask:0xf
	v_cvt_pk_bf16_f32 v149, v63, v79
	ds_write_b32 v151, v149 offset:8432
	v_mov_b32_e32 v120, v63
	v_mov_b32_e32 v121, v79
	ds_read_b128 v[124:127], v152
	ds_read_b128 v[128:131], v152 offset:64
	ds_read_b128 v[132:135], v152 offset:128
	ds_read_b128 v[136:139], v152 offset:192
	s_waitcnt lgkmcnt(3)
	v_mfma_f32_16x16x32_bf16 v[140:143], v[100:103], v[124:127], 0
	s_waitcnt lgkmcnt(2)
	v_mfma_f32_16x16x32_bf16 v[140:143], v[104:107], v[128:131], v[140:143]
	s_waitcnt lgkmcnt(1)
	v_mfma_f32_16x16x32_bf16 v[140:143], v[108:111], v[132:135], v[140:143]
	s_waitcnt lgkmcnt(0)
	v_mfma_f32_16x16x32_bf16 v[140:143], v[112:115], v[136:139], v[140:143]
	s_nop 9
	v_cvt_pk_bf16_f32 v182, v140, v141
	v_cvt_pk_bf16_f32 v183, v142, v143
	ds_write_b64 v171, v[182:183]
	ds_read_b128 v[124:127], v152 offset:4352
	ds_read_b128 v[128:131], v152 offset:4416
	ds_read_b128 v[132:135], v152 offset:4480
	ds_read_b128 v[136:139], v152 offset:4544
	s_waitcnt lgkmcnt(3)
	v_mfma_f32_16x16x32_bf16 v[140:143], v[100:103], v[124:127], 0
	s_waitcnt lgkmcnt(2)
	v_mfma_f32_16x16x32_bf16 v[140:143], v[104:107], v[128:131], v[140:143]
	s_waitcnt lgkmcnt(1)
	v_mfma_f32_16x16x32_bf16 v[140:143], v[108:111], v[132:135], v[140:143]
	s_waitcnt lgkmcnt(0)
	v_mfma_f32_16x16x32_bf16 v[140:143], v[112:115], v[136:139], v[140:143]
	s_nop 9
	v_cvt_pk_bf16_f32 v182, v140, v141
	v_cvt_pk_bf16_f32 v183, v142, v143
	ds_write_b64 v171, v[182:183] offset:512
	s_add_u32 s36, s36, 1024
	s_waitcnt vmcnt(1)
	v_mfma_f32_32x32x16_bf16 v[16:31], v[144:147], v[84:87], 0
	v_mfma_f32_32x32x16_bf16 v[32:47], v[144:147], v[88:91], 0
	v_mfma_f32_32x32x16_bf16 v[48:63], v[144:147], v[92:95], 0
	v_mfma_f32_32x32x16_bf16 v[64:79], v[144:147], v[96:99], 0
	v_add_u32_e32 v171, s36, v155
	s_nop 11
	global_load_dwordx4 v[144:147], v150, s[10:11]
	s_add_u32 s34, s34, 1024
	s_addc_u32 s35, s35, 0
	s_add_u32 s10, s10, 1024
	s_addc_u32 s11, s11, 0
	v_permlane32_swap_b32_e32 v16, v48
	v_permlane32_swap_b32_e32 v17, v49
	v_permlane32_swap_b32_e32 v18, v50
	v_permlane32_swap_b32_e32 v19, v51
	v_permlane32_swap_b32_e32 v20, v52
	v_permlane32_swap_b32_e32 v21, v53
	v_permlane32_swap_b32_e32 v22, v54
	v_permlane32_swap_b32_e32 v23, v55
	v_permlane32_swap_b32_e32 v24, v56
	v_permlane32_swap_b32_e32 v25, v57
	v_permlane32_swap_b32_e32 v26, v58
	v_permlane32_swap_b32_e32 v27, v59
	v_permlane32_swap_b32_e32 v28, v60
	v_permlane32_swap_b32_e32 v29, v61
	v_permlane32_swap_b32_e32 v30, v62
	v_permlane32_swap_b32_e32 v31, v63
	v_permlane32_swap_b32_e32 v32, v64
	v_permlane32_swap_b32_e32 v33, v65
	v_permlane32_swap_b32_e32 v34, v66
	v_permlane32_swap_b32_e32 v35, v67
	v_permlane32_swap_b32_e32 v36, v68
	v_permlane32_swap_b32_e32 v37, v69
	v_permlane32_swap_b32_e32 v38, v70
	v_permlane32_swap_b32_e32 v39, v71
	v_permlane32_swap_b32_e32 v40, v72
	v_permlane32_swap_b32_e32 v41, v73
	v_permlane32_swap_b32_e32 v42, v74
	v_permlane32_swap_b32_e32 v43, v75
	v_permlane32_swap_b32_e32 v44, v76
	v_permlane32_swap_b32_e32 v45, v77
	v_permlane32_swap_b32_e32 v46, v78
	v_permlane32_swap_b32_e32 v47, v79
	v_fmac_f32_e32 v16, v116, v120
	v_fmac_f32_e32 v32, v118, v121
	v_fmac_f32_dpp v16, v120, v122 quad_perm:[1,0,3,2] row_mask:0xf bank_mask:0xf
	v_fmac_f32_dpp v32, v121, v123 quad_perm:[1,0,3,2] row_mask:0xf bank_mask:0xf
	v_cvt_pk_bf16_f32 v148, v16, v32
	ds_write_b32 v151, v148
	v_fmac_f32_e32 v17, v116, v16
	v_fmac_f32_e32 v33, v118, v32
	v_fmac_f32_dpp v17, v16, v122 quad_perm:[1,0,3,2] row_mask:0xf bank_mask:0xf
	v_fmac_f32_dpp v33, v32, v123 quad_perm:[1,0,3,2] row_mask:0xf bank_mask:0xf
	v_cvt_pk_bf16_f32 v149, v17, v33
	ds_write_b32 v151, v149 offset:272
	v_fmac_f32_e32 v18, v116, v17
	v_fmac_f32_e32 v34, v118, v33
	v_fmac_f32_dpp v18, v17, v122 quad_perm:[1,0,3,2] row_mask:0xf bank_mask:0xf
	v_fmac_f32_dpp v34, v33, v123 quad_perm:[1,0,3,2] row_mask:0xf bank_mask:0xf
	v_cvt_pk_bf16_f32 v148, v18, v34
	ds_write_b32 v151, v148 offset:544
	v_fmac_f32_e32 v19, v116, v18
	v_fmac_f32_e32 v35, v118, v34
	v_fmac_f32_dpp v19, v18, v122 quad_perm:[1,0,3,2] row_mask:0xf bank_mask:0xf
	v_fmac_f32_dpp v35, v34, v123 quad_perm:[1,0,3,2] row_mask:0xf bank_mask:0xf
	v_cvt_pk_bf16_f32 v149, v19, v35
	ds_write_b32 v151, v149 offset:816
	v_fmac_f32_e32 v48, v116, v19
	v_fmac_f32_e32 v64, v118, v35
	v_fmac_f32_dpp v48, v19, v122 quad_perm:[1,0,3,2] row_mask:0xf bank_mask:0xf
	v_fmac_f32_dpp v64, v35, v123 quad_perm:[1,0,3,2] row_mask:0xf bank_mask:0xf
	v_cvt_pk_bf16_f32 v148, v48, v64
	ds_write_b32 v151, v148 offset:1088
	v_fmac_f32_e32 v49, v116, v48
	v_fmac_f32_e32 v65, v118, v64
	v_fmac_f32_dpp v49, v48, v122 quad_perm:[1,0,3,2] row_mask:0xf bank_mask:0xf
	v_fmac_f32_dpp v65, v64, v123 quad_perm:[1,0,3,2] row_mask:0xf bank_mask:0xf
	v_cvt_pk_bf16_f32 v149, v49, v65
	ds_write_b32 v151, v149 offset:1360
	v_fmac_f32_e32 v50, v116, v49
	v_fmac_f32_e32 v66, v118, v65
	v_fmac_f32_dpp v50, v49, v122 quad_perm:[1,0,3,2] row_mask:0xf bank_mask:0xf
	v_fmac_f32_dpp v66, v65, v123 quad_perm:[1,0,3,2] row_mask:0xf bank_mask:0xf
	v_cvt_pk_bf16_f32 v148, v50, v66
	ds_write_b32 v151, v148 offset:1632
	v_fmac_f32_e32 v51, v116, v50
	v_fmac_f32_e32 v67, v118, v66
	v_fmac_f32_dpp v51, v50, v122 quad_perm:[1,0,3,2] row_mask:0xf bank_mask:0xf
	v_fmac_f32_dpp v67, v66, v123 quad_perm:[1,0,3,2] row_mask:0xf bank_mask:0xf
	v_cvt_pk_bf16_f32 v149, v51, v67
	ds_write_b32 v151, v149 offset:1904
	v_fmac_f32_e32 v20, v116, v51
	v_fmac_f32_e32 v36, v118, v67
	v_fmac_f32_dpp v20, v51, v122 quad_perm:[1,0,3,2] row_mask:0xf bank_mask:0xf
	v_fmac_f32_dpp v36, v67, v123 quad_perm:[1,0,3,2] row_mask:0xf bank_mask:0xf
	v_cvt_pk_bf16_f32 v148, v20, v36
	ds_write_b32 v151, v148 offset:2176
	v_fmac_f32_e32 v21, v116, v20
	v_fmac_f32_e32 v37, v118, v36
	v_fmac_f32_dpp v21, v20, v122 quad_perm:[1,0,3,2] row_mask:0xf bank_mask:0xf
	v_fmac_f32_dpp v37, v36, v123 quad_perm:[1,0,3,2] row_mask:0xf bank_mask:0xf
	v_cvt_pk_bf16_f32 v149, v21, v37
	ds_write_b32 v151, v149 offset:2448
	v_fmac_f32_e32 v22, v116, v21
	v_fmac_f32_e32 v38, v118, v37
	v_fmac_f32_dpp v22, v21, v122 quad_perm:[1,0,3,2] row_mask:0xf bank_mask:0xf
	v_fmac_f32_dpp v38, v37, v123 quad_perm:[1,0,3,2] row_mask:0xf bank_mask:0xf
	v_cvt_pk_bf16_f32 v148, v22, v38
	ds_write_b32 v151, v148 offset:2720
	v_fmac_f32_e32 v23, v116, v22
	v_fmac_f32_e32 v39, v118, v38
	v_fmac_f32_dpp v23, v22, v122 quad_perm:[1,0,3,2] row_mask:0xf bank_mask:0xf
	v_fmac_f32_dpp v39, v38, v123 quad_perm:[1,0,3,2] row_mask:0xf bank_mask:0xf
	v_cvt_pk_bf16_f32 v149, v23, v39
	ds_write_b32 v151, v149 offset:2992
	v_fmac_f32_e32 v52, v116, v23
	v_fmac_f32_e32 v68, v118, v39
	v_fmac_f32_dpp v52, v23, v122 quad_perm:[1,0,3,2] row_mask:0xf bank_mask:0xf
	v_fmac_f32_dpp v68, v39, v123 quad_perm:[1,0,3,2] row_mask:0xf bank_mask:0xf
	v_cvt_pk_bf16_f32 v148, v52, v68
	ds_write_b32 v151, v148 offset:3264
	v_fmac_f32_e32 v53, v116, v52
	v_fmac_f32_e32 v69, v118, v68
	v_fmac_f32_dpp v53, v52, v122 quad_perm:[1,0,3,2] row_mask:0xf bank_mask:0xf
	v_fmac_f32_dpp v69, v68, v123 quad_perm:[1,0,3,2] row_mask:0xf bank_mask:0xf
	v_cvt_pk_bf16_f32 v149, v53, v69
	ds_write_b32 v151, v149 offset:3536
	v_fmac_f32_e32 v54, v116, v53
	v_fmac_f32_e32 v70, v118, v69
	v_fmac_f32_dpp v54, v53, v122 quad_perm:[1,0,3,2] row_mask:0xf bank_mask:0xf
	v_fmac_f32_dpp v70, v69, v123 quad_perm:[1,0,3,2] row_mask:0xf bank_mask:0xf
	v_cvt_pk_bf16_f32 v148, v54, v70
	ds_write_b32 v151, v148 offset:3808
	v_fmac_f32_e32 v55, v116, v54
	v_fmac_f32_e32 v71, v118, v70
	v_fmac_f32_dpp v55, v54, v122 quad_perm:[1,0,3,2] row_mask:0xf bank_mask:0xf
	v_fmac_f32_dpp v71, v70, v123 quad_perm:[1,0,3,2] row_mask:0xf bank_mask:0xf
	v_cvt_pk_bf16_f32 v149, v55, v71
	ds_write_b32 v151, v149 offset:4080
	v_fmac_f32_e32 v24, v116, v55
	v_fmac_f32_e32 v40, v118, v71
	v_fmac_f32_dpp v24, v55, v122 quad_perm:[1,0,3,2] row_mask:0xf bank_mask:0xf
	v_fmac_f32_dpp v40, v71, v123 quad_perm:[1,0,3,2] row_mask:0xf bank_mask:0xf
	v_cvt_pk_bf16_f32 v148, v24, v40
	ds_write_b32 v151, v148 offset:4352
	v_fmac_f32_e32 v25, v116, v24
	v_fmac_f32_e32 v41, v118, v40
	v_fmac_f32_dpp v25, v24, v122 quad_perm:[1,0,3,2] row_mask:0xf bank_mask:0xf
	v_fmac_f32_dpp v41, v40, v123 quad_perm:[1,0,3,2] row_mask:0xf bank_mask:0xf
	v_cvt_pk_bf16_f32 v149, v25, v41
	ds_write_b32 v151, v149 offset:4624
	v_fmac_f32_e32 v26, v116, v25
	v_fmac_f32_e32 v42, v118, v41
	v_fmac_f32_dpp v26, v25, v122 quad_perm:[1,0,3,2] row_mask:0xf bank_mask:0xf
	v_fmac_f32_dpp v42, v41, v123 quad_perm:[1,0,3,2] row_mask:0xf bank_mask:0xf
	v_cvt_pk_bf16_f32 v148, v26, v42
	ds_write_b32 v151, v148 offset:4896
	v_fmac_f32_e32 v27, v116, v26
	v_fmac_f32_e32 v43, v118, v42
	v_fmac_f32_dpp v27, v26, v122 quad_perm:[1,0,3,2] row_mask:0xf bank_mask:0xf
	v_fmac_f32_dpp v43, v42, v123 quad_perm:[1,0,3,2] row_mask:0xf bank_mask:0xf
	v_cvt_pk_bf16_f32 v149, v27, v43
	ds_write_b32 v151, v149 offset:5168
	v_fmac_f32_e32 v56, v116, v27
	v_fmac_f32_e32 v72, v118, v43
	v_fmac_f32_dpp v56, v27, v122 quad_perm:[1,0,3,2] row_mask:0xf bank_mask:0xf
	v_fmac_f32_dpp v72, v43, v123 quad_perm:[1,0,3,2] row_mask:0xf bank_mask:0xf
	v_cvt_pk_bf16_f32 v148, v56, v72
	ds_write_b32 v151, v148 offset:5440
	v_fmac_f32_e32 v57, v116, v56
	v_fmac_f32_e32 v73, v118, v72
	v_fmac_f32_dpp v57, v56, v122 quad_perm:[1,0,3,2] row_mask:0xf bank_mask:0xf
	v_fmac_f32_dpp v73, v72, v123 quad_perm:[1,0,3,2] row_mask:0xf bank_mask:0xf
	v_cvt_pk_bf16_f32 v149, v57, v73
	ds_write_b32 v151, v149 offset:5712
	v_fmac_f32_e32 v58, v116, v57
	v_fmac_f32_e32 v74, v118, v73
	v_fmac_f32_dpp v58, v57, v122 quad_perm:[1,0,3,2] row_mask:0xf bank_mask:0xf
	v_fmac_f32_dpp v74, v73, v123 quad_perm:[1,0,3,2] row_mask:0xf bank_mask:0xf
	v_cvt_pk_bf16_f32 v148, v58, v74
	ds_write_b32 v151, v148 offset:5984
	v_fmac_f32_e32 v59, v116, v58
	v_fmac_f32_e32 v75, v118, v74
	v_fmac_f32_dpp v59, v58, v122 quad_perm:[1,0,3,2] row_mask:0xf bank_mask:0xf
	v_fmac_f32_dpp v75, v74, v123 quad_perm:[1,0,3,2] row_mask:0xf bank_mask:0xf
	v_cvt_pk_bf16_f32 v149, v59, v75
	ds_write_b32 v151, v149 offset:6256
	v_fmac_f32_e32 v28, v116, v59
	v_fmac_f32_e32 v44, v118, v75
	v_fmac_f32_dpp v28, v59, v122 quad_perm:[1,0,3,2] row_mask:0xf bank_mask:0xf
	v_fmac_f32_dpp v44, v75, v123 quad_perm:[1,0,3,2] row_mask:0xf bank_mask:0xf
	v_cvt_pk_bf16_f32 v148, v28, v44
	ds_write_b32 v151, v148 offset:6528
	v_fmac_f32_e32 v29, v116, v28
	v_fmac_f32_e32 v45, v118, v44
	v_fmac_f32_dpp v29, v28, v122 quad_perm:[1,0,3,2] row_mask:0xf bank_mask:0xf
	v_fmac_f32_dpp v45, v44, v123 quad_perm:[1,0,3,2] row_mask:0xf bank_mask:0xf
	v_cvt_pk_bf16_f32 v149, v29, v45
	ds_write_b32 v151, v149 offset:6800
	v_fmac_f32_e32 v30, v116, v29
	v_fmac_f32_e32 v46, v118, v45
	v_fmac_f32_dpp v30, v29, v122 quad_perm:[1,0,3,2] row_mask:0xf bank_mask:0xf
	v_fmac_f32_dpp v46, v45, v123 quad_perm:[1,0,3,2] row_mask:0xf bank_mask:0xf
	v_cvt_pk_bf16_f32 v148, v30, v46
	ds_write_b32 v151, v148 offset:7072
	v_fmac_f32_e32 v31, v116, v30
	v_fmac_f32_e32 v47, v118, v46
	v_fmac_f32_dpp v31, v30, v122 quad_perm:[1,0,3,2] row_mask:0xf bank_mask:0xf
	v_fmac_f32_dpp v47, v46, v123 quad_perm:[1,0,3,2] row_mask:0xf bank_mask:0xf
	v_cvt_pk_bf16_f32 v149, v31, v47
	ds_write_b32 v151, v149 offset:7344
	v_fmac_f32_e32 v60, v116, v31
	v_fmac_f32_e32 v76, v118, v47
	v_fmac_f32_dpp v60, v31, v122 quad_perm:[1,0,3,2] row_mask:0xf bank_mask:0xf
	v_fmac_f32_dpp v76, v47, v123 quad_perm:[1,0,3,2] row_mask:0xf bank_mask:0xf
	v_cvt_pk_bf16_f32 v148, v60, v76
	ds_write_b32 v151, v148 offset:7616
	v_fmac_f32_e32 v61, v116, v60
	v_fmac_f32_e32 v77, v118, v76
	v_fmac_f32_dpp v61, v60, v122 quad_perm:[1,0,3,2] row_mask:0xf bank_mask:0xf
	v_fmac_f32_dpp v77, v76, v123 quad_perm:[1,0,3,2] row_mask:0xf bank_mask:0xf
	v_cvt_pk_bf16_f32 v149, v61, v77
	ds_write_b32 v151, v149 offset:7888
	v_fmac_f32_e32 v62, v116, v61
	v_fmac_f32_e32 v78, v118, v77
	v_fmac_f32_dpp v62, v61, v122 quad_perm:[1,0,3,2] row_mask:0xf bank_mask:0xf
	v_fmac_f32_dpp v78, v77, v123 quad_perm:[1,0,3,2] row_mask:0xf bank_mask:0xf
	v_cvt_pk_bf16_f32 v148, v62, v78
	ds_write_b32 v151, v148 offset:8160
	v_fmac_f32_e32 v63, v116, v62
	v_fmac_f32_e32 v79, v118, v78
	v_fmac_f32_dpp v63, v62, v122 quad_perm:[1,0,3,2] row_mask:0xf bank_mask:0xf
	v_fmac_f32_dpp v79, v78, v123 quad_perm:[1,0,3,2] row_mask:0xf bank_mask:0xf
	v_cvt_pk_bf16_f32 v149, v63, v79
	ds_write_b32 v151, v149 offset:8432
	v_mov_b32_e32 v120, v63
	v_mov_b32_e32 v121, v79
	ds_read_b128 v[124:127], v152
	ds_read_b128 v[128:131], v152 offset:64
	ds_read_b128 v[132:135], v152 offset:128
	ds_read_b128 v[136:139], v152 offset:192
	s_waitcnt lgkmcnt(3)
	v_mfma_f32_16x16x32_bf16 v[140:143], v[100:103], v[124:127], 0
	s_waitcnt lgkmcnt(2)
	v_mfma_f32_16x16x32_bf16 v[140:143], v[104:107], v[128:131], v[140:143]
	s_waitcnt lgkmcnt(1)
	v_mfma_f32_16x16x32_bf16 v[140:143], v[108:111], v[132:135], v[140:143]
	s_waitcnt lgkmcnt(0)
	v_mfma_f32_16x16x32_bf16 v[140:143], v[112:115], v[136:139], v[140:143]
	s_nop 9
	v_cvt_pk_bf16_f32 v182, v140, v141
	v_cvt_pk_bf16_f32 v183, v142, v143
	ds_write_b64 v171, v[182:183]
	ds_read_b128 v[124:127], v152 offset:4352
	ds_read_b128 v[128:131], v152 offset:4416
	ds_read_b128 v[132:135], v152 offset:4480
	ds_read_b128 v[136:139], v152 offset:4544
	s_waitcnt lgkmcnt(3)
	v_mfma_f32_16x16x32_bf16 v[140:143], v[100:103], v[124:127], 0
	s_waitcnt lgkmcnt(2)
	v_mfma_f32_16x16x32_bf16 v[140:143], v[104:107], v[128:131], v[140:143]
	s_waitcnt lgkmcnt(1)
	v_mfma_f32_16x16x32_bf16 v[140:143], v[108:111], v[132:135], v[140:143]
	s_waitcnt lgkmcnt(0)
	v_mfma_f32_16x16x32_bf16 v[140:143], v[112:115], v[136:139], v[140:143]
	s_nop 9
	v_cvt_pk_bf16_f32 v182, v140, v141
	v_cvt_pk_bf16_f32 v183, v142, v143
	ds_write_b64 v171, v[182:183] offset:512
	s_add_u32 s36, s36, 1024
	s_add_u32 s14, s14, 2
	s_cmp_lt_u32 s14, 8
	s_cbranch_scc1 .Lssm_tile_d0m1
	s_add_u32 s30, s30, 0x8000000
	s_add_u32 s16, s60, s30
	s_addc_u32 s17, s61, 0
	global_store_dword v180, v120, s[16:17]
	global_store_dword v180, v121, s[16:17] offset:64
	s_waitcnt vmcnt(0) lgkmcnt(0)
	s_add_u32 s28, s24, 64
	s_lshl_b32 s29, s28, 13
	s_add_u32 s29, s29, 0x200000
	s_add_u32 s10, s62, s29
	s_addc_u32 s11, s63, 0
	global_load_dwordx4 v[84:87], v177, s[10:11]
	global_load_dwordx4 v[88:91], v177, s[10:11] offset:2048
	s_add_u32 s12, s10, 0x1000
	s_addc_u32 s13, s11, 0
	global_load_dwordx4 v[92:95], v177, s[12:13]
	global_load_dwordx4 v[96:99], v177, s[12:13] offset:2048
	s_lshl_b32 s29, s28, 12
	s_add_u32 s29, s29, 0x300000
	s_add_u32 s16, s62, s29
	s_addc_u32 s17, s63, 0
	global_load_dwordx2 v[2:3], v178, s[16:17]
	global_load_dwordx2 v[4:5], v178, s[16:17] offset:1024
	global_load_dwordx2 v[6:7], v178, s[16:17] offset:512
	global_load_dwordx2 v[8:9], v178, s[16:17] offset:1536
	global_load_dwordx2 v[10:11], v178, s[16:17] offset:2048
	global_load_dwordx2 v[12:13], v178, s[16:17] offset:3072
	global_load_dwordx2 v[14:15], v178, s[16:17] offset:2560
	global_load_dwordx2 v[16:17], v178, s[16:17] offset:3584
	s_lshl_b32 s29, s28, 9
	s_add_u32 s29, s29, 0x100000
	s_add_u32 s18, s62, s29
	s_addc_u32 s19, s63, 0
	global_load_dwordx2 v[116:117], v179, s[18:19]
	global_load_dwordx2 v[118:119], v179, s[18:19] offset:128
	s_lshl_b32 s30, s23, 1
	s_add_u32 s30, s30, 1
	s_lshl_b32 s30, s30, 15
	s_lshl_b32 s31, s24, 8
	s_add_u32 s30, s30, s31
	v_mov_b32_e32 v120, 0
	v_mov_b32_e32 v121, 0
	v_readlane_b32 s34, v254, 28
	v_readlane_b32 s35, v254, 29
	s_nop 3
	s_lshl_b32 s31, s24, 6
	s_add_u32 s34, s34, s31
	s_addc_u32 s35, s35, 0
	global_load_dwordx4 v[164:167], v181, s[34:35]
	s_lshl_b32 s31, s25, 5
	s_lshl_b32 s29, s24, 19
	s_add_u32 s31, s31, s29
	s_add_u32 s31, s31, 0x16800000
	s_add_u32 s4, s62, s31
	s_addc_u32 s5, s63, 0
	s_lshl_b32 s31, s25, 11
	s_lshl_b32 s29, s24, 5
	s_add_u32 s31, s31, s29
	s_add_u32 s31, s31, 0x14800000
	s_add_u32 s6, s62, s31
	s_addc_u32 s7, s63, 0
	s_add_u32 s34, s4, 7168
	s_addc_u32 s35, s5, 0
	global_load_dwordx4 v[80:83], v150, s[34:35]
	s_mov_b64 s[10:11], s[34:35]
	s_sub_u32 s10, s10, 1024
	s_subb_u32 s11, s11, 0
	global_load_dwordx4 v[144:147], v150, s[10:11]
	s_mov_b64 s[34:35], s[10:11]
	s_sub_u32 s10, s10, 1024
	s_subb_u32 s11, s11, 0
	s_add_u32 s12, s6, 458752
	s_addc_u32 s13, s7, 0
	s_mov_b32 s36, 7168
	s_mov_b32 s14, 0
	s_mov_b32 s40, 0xffff0000
	s_waitcnt vmcnt(0)
	v_and_b32_e32 v182, 0xffff, v2
	v_lshrrev_b32_e32 v183, 16, v2
	v_and_b32_e32 v184, 0xffff, v3
	v_lshrrev_b32_e32 v185, 16, v3
	v_lshl_or_b32 v100, v4, 16, v182
	v_and_or_b32 v101, v4, s40, v183
	v_lshl_or_b32 v102, v5, 16, v184
	v_and_or_b32 v103, v5, s40, v185
	v_and_b32_e32 v182, 0xffff, v6
	v_lshrrev_b32_e32 v183, 16, v6
	v_and_b32_e32 v184, 0xffff, v7
	v_lshrrev_b32_e32 v185, 16, v7
	v_lshl_or_b32 v104, v8, 16, v182
	v_and_or_b32 v105, v8, s40, v183
	v_lshl_or_b32 v106, v9, 16, v184
	v_and_or_b32 v107, v9, s40, v185
	v_and_b32_e32 v182, 0xffff, v10
	v_lshrrev_b32_e32 v183, 16, v10
	v_and_b32_e32 v184, 0xffff, v11
	v_lshrrev_b32_e32 v185, 16, v11
	v_lshl_or_b32 v108, v12, 16, v182
	v_and_or_b32 v109, v12, s40, v183
	v_lshl_or_b32 v110, v13, 16, v184
	v_and_or_b32 v111, v13, s40, v185
	v_and_b32_e32 v182, 0xffff, v14
	v_lshrrev_b32_e32 v183, 16, v14
	v_and_b32_e32 v184, 0xffff, v15
	v_lshrrev_b32_e32 v185, 16, v15
	v_lshl_or_b32 v112, v16, 16, v182
	v_and_or_b32 v113, v16, s40, v183
	v_lshl_or_b32 v114, v17, 16, v184
	v_and_or_b32 v115, v17, s40, v185
	v_cmp_eq_u32_e32 vcc, 1, v174
	v_xor_b32_e32 v182, 0x80000000, v117
	v_xor_b32_e32 v183, 0x80000000, v119
	s_nop 1
	v_cndmask_b32_e32 v122, v182, v117, vcc
	v_cndmask_b32_e32 v123, v183, v119, vcc
.Lssm_tile_d1m2:
	s_waitcnt vmcnt(5)
	v_mfma_f32_32x32x16_bf16 v[16:31], v[80:83], v[84:87], 0
	v_mfma_f32_32x32x16_bf16 v[32:47], v[80:83], v[88:91], 0
	v_mfma_f32_32x32x16_bf16 v[48:63], v[80:83], v[92:95], 0
	v_mfma_f32_32x32x16_bf16 v[64:79], v[80:83], v[96:99], 0
	v_add_u32_e32 v171, s36, v155
	ds_write_b128 v162, v[80:83]
	s_nop 11
	global_load_dwordx4 v[80:83], v150, s[10:11]
	s_sub_u32 s34, s34, 1024
	s_subb_u32 s35, s35, 0
	s_sub_u32 s10, s10, 1024
	s_subb_u32 s11, s11, 0
	v_permlane32_swap_b32_e32 v16, v48
	v_permlane32_swap_b32_e32 v17, v49
	v_permlane32_swap_b32_e32 v18, v50
	v_permlane32_swap_b32_e32 v19, v51
	v_permlane32_swap_b32_e32 v20, v52
	v_permlane32_swap_b32_e32 v21, v53
	v_permlane32_swap_b32_e32 v22, v54
	v_permlane32_swap_b32_e32 v23, v55
	v_permlane32_swap_b32_e32 v24, v56
	v_permlane32_swap_b32_e32 v25, v57
	v_permlane32_swap_b32_e32 v26, v58
	v_permlane32_swap_b32_e32 v27, v59
	v_permlane32_swap_b32_e32 v28, v60
	v_permlane32_swap_b32_e32 v29, v61
	v_permlane32_swap_b32_e32 v30, v62
	v_permlane32_swap_b32_e32 v31, v63
	v_permlane32_swap_b32_e32 v32, v64
	v_permlane32_swap_b32_e32 v33, v65
	v_permlane32_swap_b32_e32 v34, v66
	v_permlane32_swap_b32_e32 v35, v67
	v_permlane32_swap_b32_e32 v36, v68
	v_permlane32_swap_b32_e32 v37, v69
	v_permlane32_swap_b32_e32 v38, v70
	v_permlane32_swap_b32_e32 v39, v71
	v_permlane32_swap_b32_e32 v40, v72
	v_permlane32_swap_b32_e32 v41, v73
	v_permlane32_swap_b32_e32 v42, v74
	v_permlane32_swap_b32_e32 v43, v75
	v_permlane32_swap_b32_e32 v44, v76
	v_permlane32_swap_b32_e32 v45, v77
	v_permlane32_swap_b32_e32 v46, v78
	v_permlane32_swap_b32_e32 v47, v79
	v_fmac_f32_e32 v63, v116, v120
	v_fmac_f32_e32 v79, v118, v121
	v_fmac_f32_dpp v63, v120, v122 quad_perm:[1,0,3,2] row_mask:0xf bank_mask:0xf
	v_fmac_f32_dpp v79, v121, v123 quad_perm:[1,0,3,2] row_mask:0xf bank_mask:0xf
	v_cvt_pk_bf16_f32 v148, v63, v79
	ds_write_b32 v151, v148 offset:8432
	v_fmac_f32_e32 v62, v116, v63
	v_fmac_f32_e32 v78, v118, v79
	v_fmac_f32_dpp v62, v63, v122 quad_perm:[1,0,3,2] row_mask:0xf bank_mask:0xf
	v_fmac_f32_dpp v78, v79, v123 quad_perm:[1,0,3,2] row_mask:0xf bank_mask:0xf
	v_cvt_pk_bf16_f32 v149, v62, v78
	ds_write_b32 v151, v149 offset:8160
	v_fmac_f32_e32 v61, v116, v62
	v_fmac_f32_e32 v77, v118, v78
	v_fmac_f32_dpp v61, v62, v122 quad_perm:[1,0,3,2] row_mask:0xf bank_mask:0xf
	v_fmac_f32_dpp v77, v78, v123 quad_perm:[1,0,3,2] row_mask:0xf bank_mask:0xf
	v_cvt_pk_bf16_f32 v148, v61, v77
	ds_write_b32 v151, v148 offset:7888
	v_fmac_f32_e32 v60, v116, v61
	v_fmac_f32_e32 v76, v118, v77
	v_fmac_f32_dpp v60, v61, v122 quad_perm:[1,0,3,2] row_mask:0xf bank_mask:0xf
	v_fmac_f32_dpp v76, v77, v123 quad_perm:[1,0,3,2] row_mask:0xf bank_mask:0xf
	v_cvt_pk_bf16_f32 v149, v60, v76
	ds_write_b32 v151, v149 offset:7616
	v_fmac_f32_e32 v31, v116, v60
	v_fmac_f32_e32 v47, v118, v76
	v_fmac_f32_dpp v31, v60, v122 quad_perm:[1,0,3,2] row_mask:0xf bank_mask:0xf
	v_fmac_f32_dpp v47, v76, v123 quad_perm:[1,0,3,2] row_mask:0xf bank_mask:0xf
	v_cvt_pk_bf16_f32 v148, v31, v47
	ds_write_b32 v151, v148 offset:7344
	v_fmac_f32_e32 v30, v116, v31
	v_fmac_f32_e32 v46, v118, v47
	v_fmac_f32_dpp v30, v31, v122 quad_perm:[1,0,3,2] row_mask:0xf bank_mask:0xf
	v_fmac_f32_dpp v46, v47, v123 quad_perm:[1,0,3,2] row_mask:0xf bank_mask:0xf
	v_cvt_pk_bf16_f32 v149, v30, v46
	ds_write_b32 v151, v149 offset:7072
	v_fmac_f32_e32 v29, v116, v30
	v_fmac_f32_e32 v45, v118, v46
	v_fmac_f32_dpp v29, v30, v122 quad_perm:[1,0,3,2] row_mask:0xf bank_mask:0xf
	v_fmac_f32_dpp v45, v46, v123 quad_perm:[1,0,3,2] row_mask:0xf bank_mask:0xf
	v_cvt_pk_bf16_f32 v148, v29, v45
	ds_write_b32 v151, v148 offset:6800
	v_fmac_f32_e32 v28, v116, v29
	v_fmac_f32_e32 v44, v118, v45
	v_fmac_f32_dpp v28, v29, v122 quad_perm:[1,0,3,2] row_mask:0xf bank_mask:0xf
	v_fmac_f32_dpp v44, v45, v123 quad_perm:[1,0,3,2] row_mask:0xf bank_mask:0xf
	v_cvt_pk_bf16_f32 v149, v28, v44
	ds_write_b32 v151, v149 offset:6528
	v_fmac_f32_e32 v59, v116, v28
	v_fmac_f32_e32 v75, v118, v44
	v_fmac_f32_dpp v59, v28, v122 quad_perm:[1,0,3,2] row_mask:0xf bank_mask:0xf
	v_fmac_f32_dpp v75, v44, v123 quad_perm:[1,0,3,2] row_mask:0xf bank_mask:0xf
	v_cvt_pk_bf16_f32 v148, v59, v75
	ds_write_b32 v151, v148 offset:6256
	v_fmac_f32_e32 v58, v116, v59
	v_fmac_f32_e32 v74, v118, v75
	v_fmac_f32_dpp v58, v59, v122 quad_perm:[1,0,3,2] row_mask:0xf bank_mask:0xf
	v_fmac_f32_dpp v74, v75, v123 quad_perm:[1,0,3,2] row_mask:0xf bank_mask:0xf
	v_cvt_pk_bf16_f32 v149, v58, v74
	ds_write_b32 v151, v149 offset:5984
	v_fmac_f32_e32 v57, v116, v58
	v_fmac_f32_e32 v73, v118, v74
	v_fmac_f32_dpp v57, v58, v122 quad_perm:[1,0,3,2] row_mask:0xf bank_mask:0xf
	v_fmac_f32_dpp v73, v74, v123 quad_perm:[1,0,3,2] row_mask:0xf bank_mask:0xf
	v_cvt_pk_bf16_f32 v148, v57, v73
	ds_write_b32 v151, v148 offset:5712
	v_fmac_f32_e32 v56, v116, v57
	v_fmac_f32_e32 v72, v118, v73
	v_fmac_f32_dpp v56, v57, v122 quad_perm:[1,0,3,2] row_mask:0xf bank_mask:0xf
	v_fmac_f32_dpp v72, v73, v123 quad_perm:[1,0,3,2] row_mask:0xf bank_mask:0xf
	v_cvt_pk_bf16_f32 v149, v56, v72
	ds_write_b32 v151, v149 offset:5440
	v_fmac_f32_e32 v27, v116, v56
	v_fmac_f32_e32 v43, v118, v72
	v_fmac_f32_dpp v27, v56, v122 quad_perm:[1,0,3,2] row_mask:0xf bank_mask:0xf
	v_fmac_f32_dpp v43, v72, v123 quad_perm:[1,0,3,2] row_mask:0xf bank_mask:0xf
	v_cvt_pk_bf16_f32 v148, v27, v43
	ds_write_b32 v151, v148 offset:5168
	v_fmac_f32_e32 v26, v116, v27
	v_fmac_f32_e32 v42, v118, v43
	v_fmac_f32_dpp v26, v27, v122 quad_perm:[1,0,3,2] row_mask:0xf bank_mask:0xf
	v_fmac_f32_dpp v42, v43, v123 quad_perm:[1,0,3,2] row_mask:0xf bank_mask:0xf
	v_cvt_pk_bf16_f32 v149, v26, v42
	ds_write_b32 v151, v149 offset:4896
	v_fmac_f32_e32 v25, v116, v26
	v_fmac_f32_e32 v41, v118, v42
	v_fmac_f32_dpp v25, v26, v122 quad_perm:[1,0,3,2] row_mask:0xf bank_mask:0xf
	v_fmac_f32_dpp v41, v42, v123 quad_perm:[1,0,3,2] row_mask:0xf bank_mask:0xf
	v_cvt_pk_bf16_f32 v148, v25, v41
	ds_write_b32 v151, v148 offset:4624
	v_fmac_f32_e32 v24, v116, v25
	v_fmac_f32_e32 v40, v118, v41
	v_fmac_f32_dpp v24, v25, v122 quad_perm:[1,0,3,2] row_mask:0xf bank_mask:0xf
	v_fmac_f32_dpp v40, v41, v123 quad_perm:[1,0,3,2] row_mask:0xf bank_mask:0xf
	v_cvt_pk_bf16_f32 v149, v24, v40
	ds_write_b32 v151, v149 offset:4352
	v_fmac_f32_e32 v55, v116, v24
	v_fmac_f32_e32 v71, v118, v40
	v_fmac_f32_dpp v55, v24, v122 quad_perm:[1,0,3,2] row_mask:0xf bank_mask:0xf
	v_fmac_f32_dpp v71, v40, v123 quad_perm:[1,0,3,2] row_mask:0xf bank_mask:0xf
	v_cvt_pk_bf16_f32 v148, v55, v71
	ds_write_b32 v151, v148 offset:4080
	v_fmac_f32_e32 v54, v116, v55
	v_fmac_f32_e32 v70, v118, v71
	v_fmac_f32_dpp v54, v55, v122 quad_perm:[1,0,3,2] row_mask:0xf bank_mask:0xf
	v_fmac_f32_dpp v70, v71, v123 quad_perm:[1,0,3,2] row_mask:0xf bank_mask:0xf
	v_cvt_pk_bf16_f32 v149, v54, v70
	ds_write_b32 v151, v149 offset:3808
	v_fmac_f32_e32 v53, v116, v54
	v_fmac_f32_e32 v69, v118, v70
	v_fmac_f32_dpp v53, v54, v122 quad_perm:[1,0,3,2] row_mask:0xf bank_mask:0xf
	v_fmac_f32_dpp v69, v70, v123 quad_perm:[1,0,3,2] row_mask:0xf bank_mask:0xf
	v_cvt_pk_bf16_f32 v148, v53, v69
	ds_write_b32 v151, v148 offset:3536
	v_fmac_f32_e32 v52, v116, v53
	v_fmac_f32_e32 v68, v118, v69
	v_fmac_f32_dpp v52, v53, v122 quad_perm:[1,0,3,2] row_mask:0xf bank_mask:0xf
	v_fmac_f32_dpp v68, v69, v123 quad_perm:[1,0,3,2] row_mask:0xf bank_mask:0xf
	v_cvt_pk_bf16_f32 v149, v52, v68
	ds_write_b32 v151, v149 offset:3264
	v_fmac_f32_e32 v23, v116, v52
	v_fmac_f32_e32 v39, v118, v68
	v_fmac_f32_dpp v23, v52, v122 quad_perm:[1,0,3,2] row_mask:0xf bank_mask:0xf
	v_fmac_f32_dpp v39, v68, v123 quad_perm:[1,0,3,2] row_mask:0xf bank_mask:0xf
	v_cvt_pk_bf16_f32 v148, v23, v39
	ds_write_b32 v151, v148 offset:2992
	v_fmac_f32_e32 v22, v116, v23
	v_fmac_f32_e32 v38, v118, v39
	v_fmac_f32_dpp v22, v23, v122 quad_perm:[1,0,3,2] row_mask:0xf bank_mask:0xf
	v_fmac_f32_dpp v38, v39, v123 quad_perm:[1,0,3,2] row_mask:0xf bank_mask:0xf
	v_cvt_pk_bf16_f32 v149, v22, v38
	ds_write_b32 v151, v149 offset:2720
	v_fmac_f32_e32 v21, v116, v22
	v_fmac_f32_e32 v37, v118, v38
	v_fmac_f32_dpp v21, v22, v122 quad_perm:[1,0,3,2] row_mask:0xf bank_mask:0xf
	v_fmac_f32_dpp v37, v38, v123 quad_perm:[1,0,3,2] row_mask:0xf bank_mask:0xf
	v_cvt_pk_bf16_f32 v148, v21, v37
	ds_write_b32 v151, v148 offset:2448
	v_fmac_f32_e32 v20, v116, v21
	v_fmac_f32_e32 v36, v118, v37
	v_fmac_f32_dpp v20, v21, v122 quad_perm:[1,0,3,2] row_mask:0xf bank_mask:0xf
	v_fmac_f32_dpp v36, v37, v123 quad_perm:[1,0,3,2] row_mask:0xf bank_mask:0xf
	v_cvt_pk_bf16_f32 v149, v20, v36
	ds_write_b32 v151, v149 offset:2176
	v_fmac_f32_e32 v51, v116, v20
	v_fmac_f32_e32 v67, v118, v36
	v_fmac_f32_dpp v51, v20, v122 quad_perm:[1,0,3,2] row_mask:0xf bank_mask:0xf
	v_fmac_f32_dpp v67, v36, v123 quad_perm:[1,0,3,2] row_mask:0xf bank_mask:0xf
	v_cvt_pk_bf16_f32 v148, v51, v67
	ds_write_b32 v151, v148 offset:1904
	v_fmac_f32_e32 v50, v116, v51
	v_fmac_f32_e32 v66, v118, v67
	v_fmac_f32_dpp v50, v51, v122 quad_perm:[1,0,3,2] row_mask:0xf bank_mask:0xf
	v_fmac_f32_dpp v66, v67, v123 quad_perm:[1,0,3,2] row_mask:0xf bank_mask:0xf
	v_cvt_pk_bf16_f32 v149, v50, v66
	ds_write_b32 v151, v149 offset:1632
	v_fmac_f32_e32 v49, v116, v50
	v_fmac_f32_e32 v65, v118, v66
	v_fmac_f32_dpp v49, v50, v122 quad_perm:[1,0,3,2] row_mask:0xf bank_mask:0xf
	v_fmac_f32_dpp v65, v66, v123 quad_perm:[1,0,3,2] row_mask:0xf bank_mask:0xf
	v_cvt_pk_bf16_f32 v148, v49, v65
	ds_write_b32 v151, v148 offset:1360
	v_fmac_f32_e32 v48, v116, v49
	v_fmac_f32_e32 v64, v118, v65
	v_fmac_f32_dpp v48, v49, v122 quad_perm:[1,0,3,2] row_mask:0xf bank_mask:0xf
	v_fmac_f32_dpp v64, v65, v123 quad_perm:[1,0,3,2] row_mask:0xf bank_mask:0xf
	v_cvt_pk_bf16_f32 v149, v48, v64
	ds_write_b32 v151, v149 offset:1088
	v_fmac_f32_e32 v19, v116, v48
	v_fmac_f32_e32 v35, v118, v64
	v_fmac_f32_dpp v19, v48, v122 quad_perm:[1,0,3,2] row_mask:0xf bank_mask:0xf
	v_fmac_f32_dpp v35, v64, v123 quad_perm:[1,0,3,2] row_mask:0xf bank_mask:0xf
	v_cvt_pk_bf16_f32 v148, v19, v35
	ds_write_b32 v151, v148 offset:816
	v_fmac_f32_e32 v18, v116, v19
	v_fmac_f32_e32 v34, v118, v35
	v_fmac_f32_dpp v18, v19, v122 quad_perm:[1,0,3,2] row_mask:0xf bank_mask:0xf
	v_fmac_f32_dpp v34, v35, v123 quad_perm:[1,0,3,2] row_mask:0xf bank_mask:0xf
	v_cvt_pk_bf16_f32 v149, v18, v34
	ds_write_b32 v151, v149 offset:544
	v_fmac_f32_e32 v17, v116, v18
	v_fmac_f32_e32 v33, v118, v34
	v_fmac_f32_dpp v17, v18, v122 quad_perm:[1,0,3,2] row_mask:0xf bank_mask:0xf
	v_fmac_f32_dpp v33, v34, v123 quad_perm:[1,0,3,2] row_mask:0xf bank_mask:0xf
	v_cvt_pk_bf16_f32 v148, v17, v33
	ds_write_b32 v151, v148 offset:272
	v_fmac_f32_e32 v16, v116, v17
	v_fmac_f32_e32 v32, v118, v33
	v_fmac_f32_dpp v16, v17, v122 quad_perm:[1,0,3,2] row_mask:0xf bank_mask:0xf
	v_fmac_f32_dpp v32, v33, v123 quad_perm:[1,0,3,2] row_mask:0xf bank_mask:0xf
	v_cvt_pk_bf16_f32 v149, v16, v32
	ds_write_b32 v151, v149
	v_mov_b32_e32 v120, v16
	v_mov_b32_e32 v121, v32
	ds_read_b128 v[124:127], v152
	ds_read_b128 v[128:131], v152 offset:64
	ds_read_b128 v[132:135], v152 offset:128
	ds_read_b128 v[136:139], v152 offset:192
	ds_read_b64 v[168:169], v171
	ds_read_b64 v[160:161], v163
	s_waitcnt lgkmcnt(5)
	v_mfma_f32_16x16x32_bf16 v[140:143], v[100:103], v[124:127], 0
	s_waitcnt lgkmcnt(4)
	v_mfma_f32_16x16x32_bf16 v[140:143], v[104:107], v[128:131], v[140:143]
	s_waitcnt lgkmcnt(3)
	v_mfma_f32_16x16x32_bf16 v[140:143], v[108:111], v[132:135], v[140:143]
	s_waitcnt lgkmcnt(2)
	v_mfma_f32_16x16x32_bf16 v[140:143], v[112:115], v[136:139], v[140:143]
	s_nop 9
	s_waitcnt lgkmcnt(0)
	v_lshlrev_b32_e32 v182, 16, v168
	v_and_b32_e32 v183, 0xffff0000, v168
	v_lshlrev_b32_e32 v184, 16, v169
	v_and_b32_e32 v185, 0xffff0000, v169
	v_add_f32_e32 v182, v182, v140
	v_add_f32_e32 v183, v183, v141
	v_add_f32_e32 v184, v184, v142
	v_add_f32_e32 v185, v185, v143
	v_lshlrev_b32_e32 v186, 16, v160
	v_and_b32_e32 v187, 0xffff0000, v160
	v_lshlrev_b32_e32 v188, 16, v161
	v_and_b32_e32 v189, 0xffff0000, v161
	v_fmac_f32_e32 v182, v164, v186
	v_fmac_f32_e32 v183, v165, v187
	v_fmac_f32_e32 v184, v166, v188
	v_fmac_f32_e32 v185, v167, v189
	v_mul_f32_e32 v186, 0x3d372713, v182
	v_mul_f32_e32 v187, 0x3d372713, v183
	v_mul_f32_e32 v188, 0x3d372713, v184
	v_mul_f32_e32 v189, 0x3d372713, v185
	v_mul_f32_e32 v186, v182, v186
	v_mul_f32_e32 v187, v183, v187
	v_mul_f32_e32 v188, v184, v188
	v_mul_f32_e32 v189, v185, v189
	v_fma_f32 v186, v182, v186, v182
	v_fma_f32 v187, v183, v187, v183
	v_fma_f32 v188, v184, v188, v184
	v_fma_f32 v189, v185, v189, v185
	v_mul_f32_e32 v186, 0xbfcc422a, v186
	v_mul_f32_e32 v187, 0xbfcc422a, v187
	v_mul_f32_e32 v188, 0xbfcc422a, v188
	v_mul_f32_e32 v189, 0xbfcc422a, v189
	v_mul_f32_e32 v186, 0x3fb8aa3b, v186
	v_mul_f32_e32 v187, 0x3fb8aa3b, v187
	v_mul_f32_e32 v188, 0x3fb8aa3b, v188
	v_mul_f32_e32 v189, 0x3fb8aa3b, v189
	v_exp_f32_e32 v186, v186
	v_exp_f32_e32 v187, v187
	v_exp_f32_e32 v188, v188
	v_exp_f32_e32 v189, v189
	v_add_f32_e32 v186, 1.0, v186
	v_add_f32_e32 v187, 1.0, v187
	v_add_f32_e32 v188, 1.0, v188
	v_add_f32_e32 v189, 1.0, v189
	v_rcp_f32_e32 v186, v186
	v_rcp_f32_e32 v187, v187
	v_rcp_f32_e32 v188, v188
	v_rcp_f32_e32 v189, v189
	v_mul_f32_e32 v182, v182, v186
	v_mul_f32_e32 v183, v183, v187
	v_mul_f32_e32 v184, v184, v188
	v_mul_f32_e32 v185, v185, v189
	v_cvt_pk_bf16_f32 v148, v182, v183
	v_cvt_pk_bf16_f32 v149, v184, v185
	global_store_dwordx2 v156, v[148:149], s[12:13]
	ds_read_b128 v[124:127], v152 offset:4352
	ds_read_b128 v[128:131], v152 offset:4416
	ds_read_b128 v[132:135], v152 offset:4480
	ds_read_b128 v[136:139], v152 offset:4544
	ds_read_b64 v[168:169], v171 offset:512
	ds_read_b64 v[160:161], v163 offset:512
	s_waitcnt lgkmcnt(5)
	v_mfma_f32_16x16x32_bf16 v[140:143], v[100:103], v[124:127], 0
	s_waitcnt lgkmcnt(4)
	v_mfma_f32_16x16x32_bf16 v[140:143], v[104:107], v[128:131], v[140:143]
	s_waitcnt lgkmcnt(3)
	v_mfma_f32_16x16x32_bf16 v[140:143], v[108:111], v[132:135], v[140:143]
	s_waitcnt lgkmcnt(2)
	v_mfma_f32_16x16x32_bf16 v[140:143], v[112:115], v[136:139], v[140:143]
	s_nop 9
	s_waitcnt lgkmcnt(0)
	v_lshlrev_b32_e32 v182, 16, v168
	v_and_b32_e32 v183, 0xffff0000, v168
	v_lshlrev_b32_e32 v184, 16, v169
	v_and_b32_e32 v185, 0xffff0000, v169
	v_add_f32_e32 v182, v182, v140
	v_add_f32_e32 v183, v183, v141
	v_add_f32_e32 v184, v184, v142
	v_add_f32_e32 v185, v185, v143
	v_lshlrev_b32_e32 v186, 16, v160
	v_and_b32_e32 v187, 0xffff0000, v160
	v_lshlrev_b32_e32 v188, 16, v161
	v_and_b32_e32 v189, 0xffff0000, v161
	v_fmac_f32_e32 v182, v164, v186
	v_fmac_f32_e32 v183, v165, v187
	v_fmac_f32_e32 v184, v166, v188
	v_fmac_f32_e32 v185, v167, v189
	v_mul_f32_e32 v186, 0x3d372713, v182
	v_mul_f32_e32 v187, 0x3d372713, v183
	v_mul_f32_e32 v188, 0x3d372713, v184
	v_mul_f32_e32 v189, 0x3d372713, v185
	v_mul_f32_e32 v186, v182, v186
	v_mul_f32_e32 v187, v183, v187
	v_mul_f32_e32 v188, v184, v188
	v_mul_f32_e32 v189, v185, v189
	v_fma_f32 v186, v182, v186, v182
	v_fma_f32 v187, v183, v187, v183
	v_fma_f32 v188, v184, v188, v184
	v_fma_f32 v189, v185, v189, v185
	v_mul_f32_e32 v186, 0xbfcc422a, v186
	v_mul_f32_e32 v187, 0xbfcc422a, v187
	v_mul_f32_e32 v188, 0xbfcc422a, v188
	v_mul_f32_e32 v189, 0xbfcc422a, v189
	v_mul_f32_e32 v186, 0x3fb8aa3b, v186
	v_mul_f32_e32 v187, 0x3fb8aa3b, v187
	v_mul_f32_e32 v188, 0x3fb8aa3b, v188
	v_mul_f32_e32 v189, 0x3fb8aa3b, v189
	v_exp_f32_e32 v186, v186
	v_exp_f32_e32 v187, v187
	v_exp_f32_e32 v188, v188
	v_exp_f32_e32 v189, v189
	v_add_f32_e32 v186, 1.0, v186
	v_add_f32_e32 v187, 1.0, v187
	v_add_f32_e32 v188, 1.0, v188
	v_add_f32_e32 v189, 1.0, v189
	v_rcp_f32_e32 v186, v186
	v_rcp_f32_e32 v187, v187
	v_rcp_f32_e32 v188, v188
	v_rcp_f32_e32 v189, v189
	v_mul_f32_e32 v182, v182, v186
	v_mul_f32_e32 v183, v183, v187
	v_mul_f32_e32 v184, v184, v188
	v_mul_f32_e32 v185, v185, v189
	v_cvt_pk_bf16_f32 v148, v182, v183
	v_cvt_pk_bf16_f32 v149, v184, v185
	global_store_dwordx2 v159, v[148:149], s[12:13]
	s_sub_u32 s12, s12, 65536
	s_subb_u32 s13, s13, 0
	s_sub_u32 s36, s36, 1024
	s_waitcnt vmcnt(5)
	v_mfma_f32_32x32x16_bf16 v[16:31], v[144:147], v[84:87], 0
	v_mfma_f32_32x32x16_bf16 v[32:47], v[144:147], v[88:91], 0
	v_mfma_f32_32x32x16_bf16 v[48:63], v[144:147], v[92:95], 0
	v_mfma_f32_32x32x16_bf16 v[64:79], v[144:147], v[96:99], 0
	v_add_u32_e32 v171, s36, v155
	ds_write_b128 v162, v[144:147]
	s_nop 11
	global_load_dwordx4 v[144:147], v150, s[10:11]
	s_sub_u32 s34, s34, 1024
	s_subb_u32 s35, s35, 0
	s_sub_u32 s10, s10, 1024
	s_subb_u32 s11, s11, 0
	v_permlane32_swap_b32_e32 v16, v48
	v_permlane32_swap_b32_e32 v17, v49
	v_permlane32_swap_b32_e32 v18, v50
	v_permlane32_swap_b32_e32 v19, v51
	v_permlane32_swap_b32_e32 v20, v52
	v_permlane32_swap_b32_e32 v21, v53
	v_permlane32_swap_b32_e32 v22, v54
	v_permlane32_swap_b32_e32 v23, v55
	v_permlane32_swap_b32_e32 v24, v56
	v_permlane32_swap_b32_e32 v25, v57
	v_permlane32_swap_b32_e32 v26, v58
	v_permlane32_swap_b32_e32 v27, v59
	v_permlane32_swap_b32_e32 v28, v60
	v_permlane32_swap_b32_e32 v29, v61
	v_permlane32_swap_b32_e32 v30, v62
	v_permlane32_swap_b32_e32 v31, v63
	v_permlane32_swap_b32_e32 v32, v64
	v_permlane32_swap_b32_e32 v33, v65
	v_permlane32_swap_b32_e32 v34, v66
	v_permlane32_swap_b32_e32 v35, v67
	v_permlane32_swap_b32_e32 v36, v68
	v_permlane32_swap_b32_e32 v37, v69
	v_permlane32_swap_b32_e32 v38, v70
	v_permlane32_swap_b32_e32 v39, v71
	v_permlane32_swap_b32_e32 v40, v72
	v_permlane32_swap_b32_e32 v41, v73
	v_permlane32_swap_b32_e32 v42, v74
	v_permlane32_swap_b32_e32 v43, v75
	v_permlane32_swap_b32_e32 v44, v76
	v_permlane32_swap_b32_e32 v45, v77
	v_permlane32_swap_b32_e32 v46, v78
	v_permlane32_swap_b32_e32 v47, v79
	v_fmac_f32_e32 v63, v116, v120
	v_fmac_f32_e32 v79, v118, v121
	v_fmac_f32_dpp v63, v120, v122 quad_perm:[1,0,3,2] row_mask:0xf bank_mask:0xf
	v_fmac_f32_dpp v79, v121, v123 quad_perm:[1,0,3,2] row_mask:0xf bank_mask:0xf
	v_cvt_pk_bf16_f32 v148, v63, v79
	ds_write_b32 v151, v148 offset:8432
	v_fmac_f32_e32 v62, v116, v63
	v_fmac_f32_e32 v78, v118, v79
	v_fmac_f32_dpp v62, v63, v122 quad_perm:[1,0,3,2] row_mask:0xf bank_mask:0xf
	v_fmac_f32_dpp v78, v79, v123 quad_perm:[1,0,3,2] row_mask:0xf bank_mask:0xf
	v_cvt_pk_bf16_f32 v149, v62, v78
	ds_write_b32 v151, v149 offset:8160
	v_fmac_f32_e32 v61, v116, v62
	v_fmac_f32_e32 v77, v118, v78
	v_fmac_f32_dpp v61, v62, v122 quad_perm:[1,0,3,2] row_mask:0xf bank_mask:0xf
	v_fmac_f32_dpp v77, v78, v123 quad_perm:[1,0,3,2] row_mask:0xf bank_mask:0xf
	v_cvt_pk_bf16_f32 v148, v61, v77
	ds_write_b32 v151, v148 offset:7888
	v_fmac_f32_e32 v60, v116, v61
	v_fmac_f32_e32 v76, v118, v77
	v_fmac_f32_dpp v60, v61, v122 quad_perm:[1,0,3,2] row_mask:0xf bank_mask:0xf
	v_fmac_f32_dpp v76, v77, v123 quad_perm:[1,0,3,2] row_mask:0xf bank_mask:0xf
	v_cvt_pk_bf16_f32 v149, v60, v76
	ds_write_b32 v151, v149 offset:7616
	v_fmac_f32_e32 v31, v116, v60
	v_fmac_f32_e32 v47, v118, v76
	v_fmac_f32_dpp v31, v60, v122 quad_perm:[1,0,3,2] row_mask:0xf bank_mask:0xf
	v_fmac_f32_dpp v47, v76, v123 quad_perm:[1,0,3,2] row_mask:0xf bank_mask:0xf
	v_cvt_pk_bf16_f32 v148, v31, v47
	ds_write_b32 v151, v148 offset:7344
	v_fmac_f32_e32 v30, v116, v31
	v_fmac_f32_e32 v46, v118, v47
	v_fmac_f32_dpp v30, v31, v122 quad_perm:[1,0,3,2] row_mask:0xf bank_mask:0xf
	v_fmac_f32_dpp v46, v47, v123 quad_perm:[1,0,3,2] row_mask:0xf bank_mask:0xf
	v_cvt_pk_bf16_f32 v149, v30, v46
	ds_write_b32 v151, v149 offset:7072
	v_fmac_f32_e32 v29, v116, v30
	v_fmac_f32_e32 v45, v118, v46
	v_fmac_f32_dpp v29, v30, v122 quad_perm:[1,0,3,2] row_mask:0xf bank_mask:0xf
	v_fmac_f32_dpp v45, v46, v123 quad_perm:[1,0,3,2] row_mask:0xf bank_mask:0xf
	v_cvt_pk_bf16_f32 v148, v29, v45
	ds_write_b32 v151, v148 offset:6800
	v_fmac_f32_e32 v28, v116, v29
	v_fmac_f32_e32 v44, v118, v45
	v_fmac_f32_dpp v28, v29, v122 quad_perm:[1,0,3,2] row_mask:0xf bank_mask:0xf
	v_fmac_f32_dpp v44, v45, v123 quad_perm:[1,0,3,2] row_mask:0xf bank_mask:0xf
	v_cvt_pk_bf16_f32 v149, v28, v44
	ds_write_b32 v151, v149 offset:6528
	v_fmac_f32_e32 v59, v116, v28
	v_fmac_f32_e32 v75, v118, v44
	v_fmac_f32_dpp v59, v28, v122 quad_perm:[1,0,3,2] row_mask:0xf bank_mask:0xf
	v_fmac_f32_dpp v75, v44, v123 quad_perm:[1,0,3,2] row_mask:0xf bank_mask:0xf
	v_cvt_pk_bf16_f32 v148, v59, v75
	ds_write_b32 v151, v148 offset:6256
	v_fmac_f32_e32 v58, v116, v59
	v_fmac_f32_e32 v74, v118, v75
	v_fmac_f32_dpp v58, v59, v122 quad_perm:[1,0,3,2] row_mask:0xf bank_mask:0xf
	v_fmac_f32_dpp v74, v75, v123 quad_perm:[1,0,3,2] row_mask:0xf bank_mask:0xf
	v_cvt_pk_bf16_f32 v149, v58, v74
	ds_write_b32 v151, v149 offset:5984
	v_fmac_f32_e32 v57, v116, v58
	v_fmac_f32_e32 v73, v118, v74
	v_fmac_f32_dpp v57, v58, v122 quad_perm:[1,0,3,2] row_mask:0xf bank_mask:0xf
	v_fmac_f32_dpp v73, v74, v123 quad_perm:[1,0,3,2] row_mask:0xf bank_mask:0xf
	v_cvt_pk_bf16_f32 v148, v57, v73
	ds_write_b32 v151, v148 offset:5712
	v_fmac_f32_e32 v56, v116, v57
	v_fmac_f32_e32 v72, v118, v73
	v_fmac_f32_dpp v56, v57, v122 quad_perm:[1,0,3,2] row_mask:0xf bank_mask:0xf
	v_fmac_f32_dpp v72, v73, v123 quad_perm:[1,0,3,2] row_mask:0xf bank_mask:0xf
	v_cvt_pk_bf16_f32 v149, v56, v72
	ds_write_b32 v151, v149 offset:5440
	v_fmac_f32_e32 v27, v116, v56
	v_fmac_f32_e32 v43, v118, v72
	v_fmac_f32_dpp v27, v56, v122 quad_perm:[1,0,3,2] row_mask:0xf bank_mask:0xf
	v_fmac_f32_dpp v43, v72, v123 quad_perm:[1,0,3,2] row_mask:0xf bank_mask:0xf
	v_cvt_pk_bf16_f32 v148, v27, v43
	ds_write_b32 v151, v148 offset:5168
	v_fmac_f32_e32 v26, v116, v27
	v_fmac_f32_e32 v42, v118, v43
	v_fmac_f32_dpp v26, v27, v122 quad_perm:[1,0,3,2] row_mask:0xf bank_mask:0xf
	v_fmac_f32_dpp v42, v43, v123 quad_perm:[1,0,3,2] row_mask:0xf bank_mask:0xf
	v_cvt_pk_bf16_f32 v149, v26, v42
	ds_write_b32 v151, v149 offset:4896
	v_fmac_f32_e32 v25, v116, v26
	v_fmac_f32_e32 v41, v118, v42
	v_fmac_f32_dpp v25, v26, v122 quad_perm:[1,0,3,2] row_mask:0xf bank_mask:0xf
	v_fmac_f32_dpp v41, v42, v123 quad_perm:[1,0,3,2] row_mask:0xf bank_mask:0xf
	v_cvt_pk_bf16_f32 v148, v25, v41
	ds_write_b32 v151, v148 offset:4624
	v_fmac_f32_e32 v24, v116, v25
	v_fmac_f32_e32 v40, v118, v41
	v_fmac_f32_dpp v24, v25, v122 quad_perm:[1,0,3,2] row_mask:0xf bank_mask:0xf
	v_fmac_f32_dpp v40, v41, v123 quad_perm:[1,0,3,2] row_mask:0xf bank_mask:0xf
	v_cvt_pk_bf16_f32 v149, v24, v40
	ds_write_b32 v151, v149 offset:4352
	v_fmac_f32_e32 v55, v116, v24
	v_fmac_f32_e32 v71, v118, v40
	v_fmac_f32_dpp v55, v24, v122 quad_perm:[1,0,3,2] row_mask:0xf bank_mask:0xf
	v_fmac_f32_dpp v71, v40, v123 quad_perm:[1,0,3,2] row_mask:0xf bank_mask:0xf
	v_cvt_pk_bf16_f32 v148, v55, v71
	ds_write_b32 v151, v148 offset:4080
	v_fmac_f32_e32 v54, v116, v55
	v_fmac_f32_e32 v70, v118, v71
	v_fmac_f32_dpp v54, v55, v122 quad_perm:[1,0,3,2] row_mask:0xf bank_mask:0xf
	v_fmac_f32_dpp v70, v71, v123 quad_perm:[1,0,3,2] row_mask:0xf bank_mask:0xf
	v_cvt_pk_bf16_f32 v149, v54, v70
	ds_write_b32 v151, v149 offset:3808
	v_fmac_f32_e32 v53, v116, v54
	v_fmac_f32_e32 v69, v118, v70
	v_fmac_f32_dpp v53, v54, v122 quad_perm:[1,0,3,2] row_mask:0xf bank_mask:0xf
	v_fmac_f32_dpp v69, v70, v123 quad_perm:[1,0,3,2] row_mask:0xf bank_mask:0xf
	v_cvt_pk_bf16_f32 v148, v53, v69
	ds_write_b32 v151, v148 offset:3536
	v_fmac_f32_e32 v52, v116, v53
	v_fmac_f32_e32 v68, v118, v69
	v_fmac_f32_dpp v52, v53, v122 quad_perm:[1,0,3,2] row_mask:0xf bank_mask:0xf
	v_fmac_f32_dpp v68, v69, v123 quad_perm:[1,0,3,2] row_mask:0xf bank_mask:0xf
	v_cvt_pk_bf16_f32 v149, v52, v68
	ds_write_b32 v151, v149 offset:3264
	v_fmac_f32_e32 v23, v116, v52
	v_fmac_f32_e32 v39, v118, v68
	v_fmac_f32_dpp v23, v52, v122 quad_perm:[1,0,3,2] row_mask:0xf bank_mask:0xf
	v_fmac_f32_dpp v39, v68, v123 quad_perm:[1,0,3,2] row_mask:0xf bank_mask:0xf
	v_cvt_pk_bf16_f32 v148, v23, v39
	ds_write_b32 v151, v148 offset:2992
	v_fmac_f32_e32 v22, v116, v23
	v_fmac_f32_e32 v38, v118, v39
	v_fmac_f32_dpp v22, v23, v122 quad_perm:[1,0,3,2] row_mask:0xf bank_mask:0xf
	v_fmac_f32_dpp v38, v39, v123 quad_perm:[1,0,3,2] row_mask:0xf bank_mask:0xf
	v_cvt_pk_bf16_f32 v149, v22, v38
	ds_write_b32 v151, v149 offset:2720
	v_fmac_f32_e32 v21, v116, v22
	v_fmac_f32_e32 v37, v118, v38
	v_fmac_f32_dpp v21, v22, v122 quad_perm:[1,0,3,2] row_mask:0xf bank_mask:0xf
	v_fmac_f32_dpp v37, v38, v123 quad_perm:[1,0,3,2] row_mask:0xf bank_mask:0xf
	v_cvt_pk_bf16_f32 v148, v21, v37
	ds_write_b32 v151, v148 offset:2448
	v_fmac_f32_e32 v20, v116, v21
	v_fmac_f32_e32 v36, v118, v37
	v_fmac_f32_dpp v20, v21, v122 quad_perm:[1,0,3,2] row_mask:0xf bank_mask:0xf
	v_fmac_f32_dpp v36, v37, v123 quad_perm:[1,0,3,2] row_mask:0xf bank_mask:0xf
	v_cvt_pk_bf16_f32 v149, v20, v36
	ds_write_b32 v151, v149 offset:2176
	v_fmac_f32_e32 v51, v116, v20
	v_fmac_f32_e32 v67, v118, v36
	v_fmac_f32_dpp v51, v20, v122 quad_perm:[1,0,3,2] row_mask:0xf bank_mask:0xf
	v_fmac_f32_dpp v67, v36, v123 quad_perm:[1,0,3,2] row_mask:0xf bank_mask:0xf
	v_cvt_pk_bf16_f32 v148, v51, v67
	ds_write_b32 v151, v148 offset:1904
	v_fmac_f32_e32 v50, v116, v51
	v_fmac_f32_e32 v66, v118, v67
	v_fmac_f32_dpp v50, v51, v122 quad_perm:[1,0,3,2] row_mask:0xf bank_mask:0xf
	v_fmac_f32_dpp v66, v67, v123 quad_perm:[1,0,3,2] row_mask:0xf bank_mask:0xf
	v_cvt_pk_bf16_f32 v149, v50, v66
	ds_write_b32 v151, v149 offset:1632
	v_fmac_f32_e32 v49, v116, v50
	v_fmac_f32_e32 v65, v118, v66
	v_fmac_f32_dpp v49, v50, v122 quad_perm:[1,0,3,2] row_mask:0xf bank_mask:0xf
	v_fmac_f32_dpp v65, v66, v123 quad_perm:[1,0,3,2] row_mask:0xf bank_mask:0xf
	v_cvt_pk_bf16_f32 v148, v49, v65
	ds_write_b32 v151, v148 offset:1360
	v_fmac_f32_e32 v48, v116, v49
	v_fmac_f32_e32 v64, v118, v65
	v_fmac_f32_dpp v48, v49, v122 quad_perm:[1,0,3,2] row_mask:0xf bank_mask:0xf
	v_fmac_f32_dpp v64, v65, v123 quad_perm:[1,0,3,2] row_mask:0xf bank_mask:0xf
	v_cvt_pk_bf16_f32 v149, v48, v64
	ds_write_b32 v151, v149 offset:1088
	v_fmac_f32_e32 v19, v116, v48
	v_fmac_f32_e32 v35, v118, v64
	v_fmac_f32_dpp v19, v48, v122 quad_perm:[1,0,3,2] row_mask:0xf bank_mask:0xf
	v_fmac_f32_dpp v35, v64, v123 quad_perm:[1,0,3,2] row_mask:0xf bank_mask:0xf
	v_cvt_pk_bf16_f32 v148, v19, v35
	ds_write_b32 v151, v148 offset:816
	v_fmac_f32_e32 v18, v116, v19
	v_fmac_f32_e32 v34, v118, v35
	v_fmac_f32_dpp v18, v19, v122 quad_perm:[1,0,3,2] row_mask:0xf bank_mask:0xf
	v_fmac_f32_dpp v34, v35, v123 quad_perm:[1,0,3,2] row_mask:0xf bank_mask:0xf
	v_cvt_pk_bf16_f32 v149, v18, v34
	ds_write_b32 v151, v149 offset:544
	v_fmac_f32_e32 v17, v116, v18
	v_fmac_f32_e32 v33, v118, v34
	v_fmac_f32_dpp v17, v18, v122 quad_perm:[1,0,3,2] row_mask:0xf bank_mask:0xf
	v_fmac_f32_dpp v33, v34, v123 quad_perm:[1,0,3,2] row_mask:0xf bank_mask:0xf
	v_cvt_pk_bf16_f32 v148, v17, v33
	ds_write_b32 v151, v148 offset:272
	v_fmac_f32_e32 v16, v116, v17
	v_fmac_f32_e32 v32, v118, v33
	v_fmac_f32_dpp v16, v17, v122 quad_perm:[1,0,3,2] row_mask:0xf bank_mask:0xf
	v_fmac_f32_dpp v32, v33, v123 quad_perm:[1,0,3,2] row_mask:0xf bank_mask:0xf
	v_cvt_pk_bf16_f32 v149, v16, v32
	ds_write_b32 v151, v149
	v_mov_b32_e32 v120, v16
	v_mov_b32_e32 v121, v32
	ds_read_b128 v[124:127], v152
	ds_read_b128 v[128:131], v152 offset:64
	ds_read_b128 v[132:135], v152 offset:128
	ds_read_b128 v[136:139], v152 offset:192
	ds_read_b64 v[168:169], v171
	ds_read_b64 v[160:161], v163
	s_waitcnt lgkmcnt(5)
	v_mfma_f32_16x16x32_bf16 v[140:143], v[100:103], v[124:127], 0
	s_waitcnt lgkmcnt(4)
	v_mfma_f32_16x16x32_bf16 v[140:143], v[104:107], v[128:131], v[140:143]
	s_waitcnt lgkmcnt(3)
	v_mfma_f32_16x16x32_bf16 v[140:143], v[108:111], v[132:135], v[140:143]
	s_waitcnt lgkmcnt(2)
	v_mfma_f32_16x16x32_bf16 v[140:143], v[112:115], v[136:139], v[140:143]
	s_nop 9
	s_waitcnt lgkmcnt(0)
	v_lshlrev_b32_e32 v182, 16, v168
	v_and_b32_e32 v183, 0xffff0000, v168
	v_lshlrev_b32_e32 v184, 16, v169
	v_and_b32_e32 v185, 0xffff0000, v169
	v_add_f32_e32 v182, v182, v140
	v_add_f32_e32 v183, v183, v141
	v_add_f32_e32 v184, v184, v142
	v_add_f32_e32 v185, v185, v143
	v_lshlrev_b32_e32 v186, 16, v160
	v_and_b32_e32 v187, 0xffff0000, v160
	v_lshlrev_b32_e32 v188, 16, v161
	v_and_b32_e32 v189, 0xffff0000, v161
	v_fmac_f32_e32 v182, v164, v186
	v_fmac_f32_e32 v183, v165, v187
	v_fmac_f32_e32 v184, v166, v188
	v_fmac_f32_e32 v185, v167, v189
	v_mul_f32_e32 v186, 0x3d372713, v182
	v_mul_f32_e32 v187, 0x3d372713, v183
	v_mul_f32_e32 v188, 0x3d372713, v184
	v_mul_f32_e32 v189, 0x3d372713, v185
	v_mul_f32_e32 v186, v182, v186
	v_mul_f32_e32 v187, v183, v187
	v_mul_f32_e32 v188, v184, v188
	v_mul_f32_e32 v189, v185, v189
	v_fma_f32 v186, v182, v186, v182
	v_fma_f32 v187, v183, v187, v183
	v_fma_f32 v188, v184, v188, v184
	v_fma_f32 v189, v185, v189, v185
	v_mul_f32_e32 v186, 0xbfcc422a, v186
	v_mul_f32_e32 v187, 0xbfcc422a, v187
	v_mul_f32_e32 v188, 0xbfcc422a, v188
	v_mul_f32_e32 v189, 0xbfcc422a, v189
	v_mul_f32_e32 v186, 0x3fb8aa3b, v186
	v_mul_f32_e32 v187, 0x3fb8aa3b, v187
	v_mul_f32_e32 v188, 0x3fb8aa3b, v188
	v_mul_f32_e32 v189, 0x3fb8aa3b, v189
	v_exp_f32_e32 v186, v186
	v_exp_f32_e32 v187, v187
	v_exp_f32_e32 v188, v188
	v_exp_f32_e32 v189, v189
	v_add_f32_e32 v186, 1.0, v186
	v_add_f32_e32 v187, 1.0, v187
	v_add_f32_e32 v188, 1.0, v188
	v_add_f32_e32 v189, 1.0, v189
	v_rcp_f32_e32 v186, v186
	v_rcp_f32_e32 v187, v187
	v_rcp_f32_e32 v188, v188
	v_rcp_f32_e32 v189, v189
	v_mul_f32_e32 v182, v182, v186
	v_mul_f32_e32 v183, v183, v187
	v_mul_f32_e32 v184, v184, v188
	v_mul_f32_e32 v185, v185, v189
	v_cvt_pk_bf16_f32 v148, v182, v183
	v_cvt_pk_bf16_f32 v149, v184, v185
	global_store_dwordx2 v156, v[148:149], s[12:13]
	ds_read_b128 v[124:127], v152 offset:4352
	ds_read_b128 v[128:131], v152 offset:4416
	ds_read_b128 v[132:135], v152 offset:4480
	ds_read_b128 v[136:139], v152 offset:4544
	ds_read_b64 v[168:169], v171 offset:512
	ds_read_b64 v[160:161], v163 offset:512
	s_waitcnt lgkmcnt(5)
	v_mfma_f32_16x16x32_bf16 v[140:143], v[100:103], v[124:127], 0
	s_waitcnt lgkmcnt(4)
	v_mfma_f32_16x16x32_bf16 v[140:143], v[104:107], v[128:131], v[140:143]
	s_waitcnt lgkmcnt(3)
	v_mfma_f32_16x16x32_bf16 v[140:143], v[108:111], v[132:135], v[140:143]
	s_waitcnt lgkmcnt(2)
	v_mfma_f32_16x16x32_bf16 v[140:143], v[112:115], v[136:139], v[140:143]
	s_nop 9
	s_waitcnt lgkmcnt(0)
	v_lshlrev_b32_e32 v182, 16, v168
	v_and_b32_e32 v183, 0xffff0000, v168
	v_lshlrev_b32_e32 v184, 16, v169
	v_and_b32_e32 v185, 0xffff0000, v169
	v_add_f32_e32 v182, v182, v140
	v_add_f32_e32 v183, v183, v141
	v_add_f32_e32 v184, v184, v142
	v_add_f32_e32 v185, v185, v143
	v_lshlrev_b32_e32 v186, 16, v160
	v_and_b32_e32 v187, 0xffff0000, v160
	v_lshlrev_b32_e32 v188, 16, v161
	v_and_b32_e32 v189, 0xffff0000, v161
	v_fmac_f32_e32 v182, v164, v186
	v_fmac_f32_e32 v183, v165, v187
	v_fmac_f32_e32 v184, v166, v188
	v_fmac_f32_e32 v185, v167, v189
	v_mul_f32_e32 v186, 0x3d372713, v182
	v_mul_f32_e32 v187, 0x3d372713, v183
	v_mul_f32_e32 v188, 0x3d372713, v184
	v_mul_f32_e32 v189, 0x3d372713, v185
	v_mul_f32_e32 v186, v182, v186
	v_mul_f32_e32 v187, v183, v187
	v_mul_f32_e32 v188, v184, v188
	v_mul_f32_e32 v189, v185, v189
	v_fma_f32 v186, v182, v186, v182
	v_fma_f32 v187, v183, v187, v183
	v_fma_f32 v188, v184, v188, v184
	v_fma_f32 v189, v185, v189, v185
	v_mul_f32_e32 v186, 0xbfcc422a, v186
	v_mul_f32_e32 v187, 0xbfcc422a, v187
	v_mul_f32_e32 v188, 0xbfcc422a, v188
	v_mul_f32_e32 v189, 0xbfcc422a, v189
	v_mul_f32_e32 v186, 0x3fb8aa3b, v186
	v_mul_f32_e32 v187, 0x3fb8aa3b, v187
	v_mul_f32_e32 v188, 0x3fb8aa3b, v188
	v_mul_f32_e32 v189, 0x3fb8aa3b, v189
	v_exp_f32_e32 v186, v186
	v_exp_f32_e32 v187, v187
	v_exp_f32_e32 v188, v188
	v_exp_f32_e32 v189, v189
	v_add_f32_e32 v186, 1.0, v186
	v_add_f32_e32 v187, 1.0, v187
	v_add_f32_e32 v188, 1.0, v188
	v_add_f32_e32 v189, 1.0, v189
	v_rcp_f32_e32 v186, v186
	v_rcp_f32_e32 v187, v187
	v_rcp_f32_e32 v188, v188
	v_rcp_f32_e32 v189, v189
	v_mul_f32_e32 v182, v182, v186
	v_mul_f32_e32 v183, v183, v187
	v_mul_f32_e32 v184, v184, v188
	v_mul_f32_e32 v185, v185, v189
	v_cvt_pk_bf16_f32 v148, v182, v183
	v_cvt_pk_bf16_f32 v149, v184, v185
	global_store_dwordx2 v159, v[148:149], s[12:13]
	s_sub_u32 s12, s12, 65536
	s_subb_u32 s13, s13, 0
	s_sub_u32 s36, s36, 1024
	s_add_u32 s14, s14, 2
	s_cmp_lt_u32 s14, 8
	s_cbranch_scc1 .Lssm_tile_d1m2
	s_add_u32 s30, s30, 0x8000000
	s_add_u32 s16, s60, s30
	s_addc_u32 s17, s61, 0
	global_store_dword v180, v120, s[16:17]
	global_store_dword v180, v121, s[16:17] offset:64
	s_waitcnt vmcnt(0) lgkmcnt(0)
	s_add_u32 s27, s27, 1
	s_cmp_lt_u32 s27, 2
	s_cbranch_scc1 .Lssm_ctx_loop
